# v33 + MLP-up epilogue: rstd partial-sum loads hoisted/double-buffered with counted vmcnt (stores no longer waited), canonicalizing self-max removed
# baseline (speedup 1.0000x reference)
; DI u32x4 pack_v8(f32x4 v0, f32x4 v1) { u32x4 w; w.x = pk2(v0[0], v0[1]); w.y = pk2(v0[2], v0[3]); w.z = pk2(v1[0], v1[1]); w.w = pk2(v1[2], v1[3]); return w; }
; DI float rstd16(const float* ssq, int row) { const f32x4* p = (const f32x4*)(ssq + (size_t)row * 16); const f32x4 a = p[0], b = p[1], c = p[2], d = p[3];
;   return __builtin_amdgcn_rsqf((((a[0] + a[1]) + (a[2] + a[3])) + ((b[0] + b[1]) + (b[2] + b[3])) + ((c[0] + c[1]) + (c[2] + c[3])) + ((d[0] + d[1]) + (d[2] + d[3]))) * (1.0f / 1024.0f) + EPS); }
;   DI void operator()(AccRef acc, const Unit& u, int wr, int wc, int fr, int fq) const {
;     const int rowb = u.pm * 256 + wr * 64 + fr; const int cb = u.pn * 256 + wc * 32 + 8 * fq;
; #pragma unroll
;     for (int ai = 0; ai < 2; ++ai)
; #pragma unroll
;       for (int m = 0; m < 4; ++m) { const int row = rowb + ai * 128 + m * 16; const float rs = rstd16(SSQH, row);
; #pragma unroll
;         for (int bj = 0; bj < 2; ++bj) { f32x4 v0 = acc[ai][bj][m][0], v1 = acc[ai][bj][m][1];
; #pragma unroll
;           for (int j = 0; j < 4; ++j) { const float a = fmaxf(v0[j], 0.f) * rs, b = fmaxf(v1[j], 0.f) * rs; v0[j] = a * a; v1[j] = b * b; }
;           *(u32x4*)(A2 + (size_t)row * DFF + cb + bj * 128) = pack_v8(v0, v1); } }
;   }
.LBB0_899:
	s_lshl_b32 s15, s24, 8
	v_mov_b32_e32 v151, v224
	s_add_i32 s15, s15, s42
	v_and_or_b32 v144, v151, 15, s15
	v_ashrrev_i32_e32 v145, 31, v144
	v_lshlrev_b64 v[152:153], 6, v[144:145]
	v_lshl_add_u64 v[164:165], s[60:61], 0, v[152:153]
	v_mov_b32_e32 v208, v164
	v_mov_b32_e32 v209, v165
	s_mov_b64 s[98:99], 0x2000
	v_lshl_add_u64 v[210:211], s[98:99], 0, v[164:165]
	global_load_dwordx4 v[152:155], v[164:165], off
	global_load_dwordx4 v[156:159], v[164:165], off offset:16
	global_load_dwordx4 v[160:163], v[164:165], off offset:32
	s_nop 0
	global_load_dwordx4 v[164:167], v[164:165], off offset:48
	global_load_dwordx4 v[192:195], v[208:209], off offset:1024
	global_load_dwordx4 v[196:199], v[208:209], off offset:1040
	global_load_dwordx4 v[200:203], v[208:209], off offset:1056
	global_load_dwordx4 v[204:207], v[208:209], off offset:1072
	v_max_f32_e32 v169, v117, v117
	v_max_f32_e32 v172, v119, v119
	v_max_f32_e32 v117, 0, v121
	v_max_f32_e32 v119, 0, v127
	v_max_f32_e32 v121, 0, v123
	v_max_f32_e32 v123, 0, v169
	v_max_f32_e32 v127, 0, v172
	v_max_f32_e32 v169, 0, v115
	v_lshlrev_b64 v[172:173], 13, v[144:145]
	s_lshl_b32 s15, s64, 8
	v_max_f32_e32 v171, v114, v114
	v_max_f32_e32 v114, 0, v124
	v_max_f32_e32 v124, 0, v112
	v_lshrrev_b32_e32 v112, 1, v151
	v_and_or_b32 v112, v112, 24, s15
	v_max_f32_e32 v168, v116, v116
	v_max_f32_e32 v170, v118, v118
	v_max_f32_e32 v116, 0, v120
	v_max_f32_e32 v115, 0, v125
	v_max_f32_e32 v118, 0, v126
	v_max_f32_e32 v120, 0, v122
	v_or_b32_e32 v112, s43, v112
	v_max_f32_e32 v122, 0, v168
	v_max_f32_e32 v125, 0, v113
	v_max_f32_e32 v126, 0, v170
	v_max_f32_e32 v168, 0, v171
	v_ashrrev_i32_e32 v113, 31, v112
	v_or_b32_e32 v170, 16, v144
	v_lshlrev_b64 v[112:113], 1, v[112:113]
	v_ashrrev_i32_e32 v171, 31, v170
	v_max_f32_e32 v151, v97, v97
	v_max_f32_e32 v97, 0, v109
	s_waitcnt vmcnt(4) lgkmcnt(0)
	global_load_dwordx4 v[176:179], v[208:209], off offset:2048
	global_load_dwordx4 v[180:183], v[208:209], off offset:2064
	global_load_dwordx4 v[184:187], v[208:209], off offset:2080
	global_load_dwordx4 v[188:191], v[208:209], off offset:2096
	v_mov_b32_e32 v174, v153
	v_mov_b32_e32 v175, v154
	v_mov_b32_e32 v153, v155
	v_mov_b32_e32 v154, v157
	v_mov_b32_e32 v155, v158
	v_mov_b32_e32 v157, v159
	v_pk_add_f32 v[152:153], v[174:175], v[152:153]
	v_pk_add_f32 v[154:155], v[154:155], v[156:157]
	v_pk_add_f32 v[152:153], v[152:153], v[152:153] op_sel:[0,1] op_sel_hi:[1,0]
	v_pk_add_f32 v[154:155], v[154:155], v[154:155] op_sel:[0,1] op_sel_hi:[1,0]
	v_add_f32_e32 v158, v160, v161
	v_add_f32_e32 v160, v162, v163
	v_mov_b32_e32 v159, v166
	v_mov_b32_e32 v161, v167
	v_mov_b32_e32 v153, v164
	v_mov_b32_e32 v155, v165
	v_pk_add_f32 v[156:157], v[158:159], v[160:161]
	v_pk_add_f32 v[152:153], v[152:153], v[154:155]
	v_lshl_add_u64 v[154:155], s[52:53], 0, v[172:173]
	v_pk_add_f32 v[152:153], v[152:153], v[156:157]
	v_lshl_add_u64 v[154:155], v[154:155], 0, v[112:113]
	v_add_f32_e32 v145, v152, v153
	v_fmamk_f32 v145, v145, 0x3a800000, v150
	v_rsq_f32_e32 v152, v145
	v_max_f32_e32 v145, v101, v101
	v_max_f32_e32 v156, v102, v102
	v_max_f32_e32 v157, v98, v98
	v_pk_mul_f32 v[114:115], v[114:115], v[152:153] op_sel_hi:[1,0]
	v_pk_mul_f32 v[116:117], v[116:117], v[152:153] op_sel_hi:[1,0]
	v_pk_mul_f32 v[118:119], v[118:119], v[152:153] op_sel_hi:[1,0]
	v_pk_mul_f32 v[120:121], v[120:121], v[152:153] op_sel_hi:[1,0]
	v_pk_mul_f32 v[122:123], v[122:123], v[152:153] op_sel_hi:[1,0]
	v_pk_mul_f32 v[124:125], v[124:125], v[152:153] op_sel_hi:[1,0]
	v_pk_mul_f32 v[126:127], v[126:127], v[152:153] op_sel_hi:[1,0]
	v_pk_mul_f32 v[152:153], v[168:169], v[152:153] op_sel_hi:[1,0]
	v_pk_mul_f32 v[114:115], v[114:115], v[114:115]
	v_pk_mul_f32 v[116:117], v[116:117], v[116:117]
	v_pk_mul_f32 v[118:119], v[118:119], v[118:119]
	v_pk_mul_f32 v[120:121], v[120:121], v[120:121]
	v_pk_mul_f32 v[122:123], v[122:123], v[122:123]
	v_pk_mul_f32 v[124:125], v[124:125], v[124:125]
	v_pk_mul_f32 v[126:127], v[126:127], v[126:127]
	v_pk_mul_f32 v[152:153], v[152:153], v[152:153]
	v_cvt_pk_bf16_f32 v114, v114, v115
	v_cvt_pk_bf16_f32 v115, v118, v119
	v_cvt_pk_bf16_f32 v116, v116, v117
	v_cvt_pk_bf16_f32 v117, v120, v121
	v_cvt_pk_bf16_f32 v118, v122, v123
	v_cvt_pk_bf16_f32 v119, v126, v127
	v_cvt_pk_bf16_f32 v120, v124, v125
	v_cvt_pk_bf16_f32 v121, v152, v153
	global_store_dwordx4 v[154:155], v[114:117], off
	global_store_dwordx4 v[154:155], v[118:121], off offset:256
	v_max_f32_e32 v158, v103, v103
	v_lshlrev_b64 v[114:115], 6, v[170:171]
	v_lshl_add_u64 v[126:127], s[60:61], 0, v[114:115]
	v_max_f32_e32 v126, v100, v100
	v_max_f32_e32 v127, v96, v96
	v_max_f32_e32 v159, v99, v99
	v_max_f32_e32 v96, 0, v108
	v_max_f32_e32 v98, 0, v104
	v_max_f32_e32 v99, 0, v105
	v_max_f32_e32 v100, 0, v110
	v_max_f32_e32 v102, 0, v106
	v_max_f32_e32 v101, 0, v111
	v_max_f32_e32 v103, 0, v107
	v_max_f32_e32 v104, 0, v126
	v_max_f32_e32 v106, 0, v127
	v_max_f32_e32 v105, 0, v145
	v_max_f32_e32 v107, 0, v151
	v_max_f32_e32 v108, 0, v156
	v_max_f32_e32 v110, 0, v157
	v_max_f32_e32 v109, 0, v158
	v_max_f32_e32 v111, 0, v159
	v_or_b32_e32 v126, 32, v144
	v_lshlrev_b64 v[156:157], 13, v[170:171]
	v_ashrrev_i32_e32 v127, 31, v126
	v_lshlrev_b64 v[158:159], 6, v[126:127]
	s_andn2_b64 vcc, exec, s[4:5]
	s_mov_b64 s[4:5], -1
	s_waitcnt vmcnt(6) lgkmcnt(0)
; DI u32x4 pack_v8(f32x4 v0, f32x4 v1) { u32x4 w; w.x = pk2(v0[0], v0[1]); w.y = pk2(v0[2], v0[3]); w.z = pk2(v1[0], v1[1]); w.w = pk2(v1[2], v1[3]); return w; }
; DI float rstd16(const float* ssq, int row) { const f32x4* p = (const f32x4*)(ssq + (size_t)row * 16); const f32x4 a = p[0], b = p[1], c = p[2], d = p[3];
;   return __builtin_amdgcn_rsqf((((a[0] + a[1]) + (a[2] + a[3])) + ((b[0] + b[1]) + (b[2] + b[3])) + ((c[0] + c[1]) + (c[2] + c[3])) + ((d[0] + d[1]) + (d[2] + d[3]))) * (1.0f / 1024.0f) + EPS); }
;   DI void operator()(AccRef acc, const Unit& u, int wr, int wc, int fr, int fq) const {
;     const int rowb = u.pm * 256 + wr * 64 + fr; const int cb = u.pn * 256 + wc * 32 + 8 * fq;
; #pragma unroll
;     for (int ai = 0; ai < 2; ++ai)
; #pragma unroll
;       for (int m = 0; m < 4; ++m) { const int row = rowb + ai * 128 + m * 16; const float rs = rstd16(SSQH, row);
; #pragma unroll
;         for (int bj = 0; bj < 2; ++bj) { f32x4 v0 = acc[ai][bj][m][0], v1 = acc[ai][bj][m][1];
; #pragma unroll
;           for (int j = 0; j < 4; ++j) { const float a = fmaxf(v0[j], 0.f) * rs, b = fmaxf(v1[j], 0.f) * rs; v0[j] = a * a; v1[j] = b * b; }
;           *(u32x4*)(A2 + (size_t)row * DFF + cb + bj * 128) = pack_v8(v0, v1); } }
;   }
	v_mov_b32_e32 v114, v192
	v_mov_b32_e32 v115, v193
	v_mov_b32_e32 v116, v194
	v_mov_b32_e32 v117, v195
	v_mov_b32_e32 v118, v196
	v_mov_b32_e32 v119, v197
	v_mov_b32_e32 v120, v198
	v_mov_b32_e32 v121, v199
	v_mov_b32_e32 v122, v200
	v_mov_b32_e32 v123, v201
	v_mov_b32_e32 v124, v202
	v_mov_b32_e32 v125, v203
	v_mov_b32_e32 v152, v204
	v_mov_b32_e32 v153, v205
	v_mov_b32_e32 v154, v206
	v_mov_b32_e32 v155, v207
	global_load_dwordx4 v[192:195], v[208:209], off offset:3072
	global_load_dwordx4 v[196:199], v[208:209], off offset:3088
	global_load_dwordx4 v[200:203], v[208:209], off offset:3104
	global_load_dwordx4 v[204:207], v[208:209], off offset:3120
	v_mov_b32_e32 v160, v115
	v_mov_b32_e32 v161, v116
	v_mov_b32_e32 v115, v117
	v_mov_b32_e32 v116, v119
	v_mov_b32_e32 v117, v120
	v_mov_b32_e32 v119, v121
	v_pk_add_f32 v[114:115], v[160:161], v[114:115]
	v_pk_add_f32 v[116:117], v[116:117], v[118:119]
	v_pk_add_f32 v[114:115], v[114:115], v[114:115] op_sel:[0,1] op_sel_hi:[1,0]
	v_pk_add_f32 v[116:117], v[116:117], v[116:117] op_sel:[0,1] op_sel_hi:[1,0]
	v_add_f32_e32 v120, v122, v123
	v_add_f32_e32 v122, v124, v125
	v_mov_b32_e32 v121, v154
	v_mov_b32_e32 v123, v155
	v_mov_b32_e32 v115, v152
	v_mov_b32_e32 v117, v153
	v_pk_add_f32 v[118:119], v[120:121], v[122:123]
	v_pk_add_f32 v[114:115], v[114:115], v[116:117]
	v_lshl_add_u64 v[116:117], s[52:53], 0, v[156:157]
	v_pk_add_f32 v[114:115], v[114:115], v[118:119]
	v_lshl_add_u64 v[116:117], v[116:117], 0, v[112:113]
	v_add_f32_e32 v114, v114, v115
	v_fmamk_f32 v114, v114, 0x3a800000, v150
	v_rsq_f32_e32 v114, v114
	v_lshl_add_u64 v[118:119], s[60:61], 0, v[158:159]
	v_pk_mul_f32 v[96:97], v[96:97], v[114:115] op_sel_hi:[1,0]
	v_pk_mul_f32 v[98:99], v[98:99], v[114:115] op_sel_hi:[1,0]
	v_pk_mul_f32 v[100:101], v[100:101], v[114:115] op_sel_hi:[1,0]
	v_pk_mul_f32 v[102:103], v[102:103], v[114:115] op_sel_hi:[1,0]
	v_pk_mul_f32 v[104:105], v[104:105], v[114:115] op_sel_hi:[1,0]
	v_pk_mul_f32 v[106:107], v[106:107], v[114:115] op_sel_hi:[1,0]
	v_pk_mul_f32 v[108:109], v[108:109], v[114:115] op_sel_hi:[1,0]
	v_pk_mul_f32 v[110:111], v[110:111], v[114:115] op_sel_hi:[1,0]
	v_pk_mul_f32 v[96:97], v[96:97], v[96:97]
	v_pk_mul_f32 v[98:99], v[98:99], v[98:99]
	v_pk_mul_f32 v[100:101], v[100:101], v[100:101]
	v_pk_mul_f32 v[102:103], v[102:103], v[102:103]
	v_pk_mul_f32 v[104:105], v[104:105], v[104:105]
	v_pk_mul_f32 v[106:107], v[106:107], v[106:107]
	v_pk_mul_f32 v[108:109], v[108:109], v[108:109]
	v_pk_mul_f32 v[110:111], v[110:111], v[110:111]
	v_cvt_pk_bf16_f32 v96, v96, v97
	v_cvt_pk_bf16_f32 v97, v100, v101
	v_cvt_pk_bf16_f32 v98, v98, v99
	v_cvt_pk_bf16_f32 v99, v102, v103
	v_cvt_pk_bf16_f32 v100, v104, v105
	v_cvt_pk_bf16_f32 v101, v108, v109
	v_cvt_pk_bf16_f32 v102, v106, v107
	v_cvt_pk_bf16_f32 v103, v110, v111
	global_store_dwordx4 v[116:117], v[96:99], off
	global_store_dwordx4 v[116:117], v[100:103], off offset:256
	s_nop 0
	v_max_f32_e32 v116, v85, v85
	v_max_f32_e32 v117, v81, v81
	v_max_f32_e32 v81, 0, v93
	v_max_f32_e32 v85, 0, v95
	v_max_f32_e32 v93, 0, v87
	v_max_f32_e32 v95, 0, v83
	v_max_f32_e32 v114, v84, v84
	v_max_f32_e32 v115, v80, v80
	v_max_f32_e32 v118, v86, v86
	v_max_f32_e32 v119, v82, v82
	v_max_f32_e32 v80, 0, v92
	v_max_f32_e32 v82, 0, v88
	v_max_f32_e32 v83, 0, v89
	v_max_f32_e32 v84, 0, v94
	v_max_f32_e32 v86, 0, v90
	v_max_f32_e32 v87, 0, v91
	v_max_f32_e32 v88, 0, v114
	v_max_f32_e32 v90, 0, v115
	v_max_f32_e32 v89, 0, v116
	v_max_f32_e32 v91, 0, v117
	v_max_f32_e32 v92, 0, v118
	v_max_f32_e32 v94, 0, v119
	v_or_b32_e32 v114, 48, v144
	v_lshlrev_b64 v[116:117], 13, v[126:127]
	v_ashrrev_i32_e32 v115, 31, v114
	v_lshlrev_b64 v[118:119], 6, v[114:115]
	s_waitcnt vmcnt(8) lgkmcnt(0)
	v_mov_b32_e32 v96, v176
	v_mov_b32_e32 v97, v177
	v_mov_b32_e32 v98, v178
	v_mov_b32_e32 v99, v179
	v_mov_b32_e32 v100, v180
	v_mov_b32_e32 v101, v181
	v_mov_b32_e32 v102, v182
	v_mov_b32_e32 v103, v183
	v_mov_b32_e32 v104, v184
	v_mov_b32_e32 v105, v185
	v_mov_b32_e32 v106, v186
	v_mov_b32_e32 v107, v187
	v_mov_b32_e32 v108, v188
	v_mov_b32_e32 v109, v189
	v_mov_b32_e32 v110, v190
	v_mov_b32_e32 v111, v191
	global_load_dwordx4 v[176:179], v[210:211], off offset:0
	global_load_dwordx4 v[180:183], v[210:211], off offset:16
	global_load_dwordx4 v[184:187], v[210:211], off offset:32
	global_load_dwordx4 v[188:191], v[210:211], off offset:48
	v_mov_b32_e32 v120, v97
	v_mov_b32_e32 v121, v98
	v_mov_b32_e32 v97, v99
	v_mov_b32_e32 v98, v101
	v_mov_b32_e32 v99, v102
	v_mov_b32_e32 v101, v103
	v_pk_add_f32 v[96:97], v[120:121], v[96:97]
	v_pk_add_f32 v[98:99], v[98:99], v[100:101]
	v_pk_add_f32 v[96:97], v[96:97], v[96:97] op_sel:[0,1] op_sel_hi:[1,0]
	v_pk_add_f32 v[98:99], v[98:99], v[98:99] op_sel:[0,1] op_sel_hi:[1,0]
	v_add_f32_e32 v102, v104, v105
	v_add_f32_e32 v104, v106, v107
	v_mov_b32_e32 v103, v110
	v_mov_b32_e32 v105, v111
	v_mov_b32_e32 v97, v108
	v_mov_b32_e32 v99, v109
	v_pk_add_f32 v[100:101], v[102:103], v[104:105]
	v_pk_add_f32 v[96:97], v[96:97], v[98:99]
	v_lshl_add_u64 v[98:99], s[52:53], 0, v[116:117]
	v_pk_add_f32 v[96:97], v[96:97], v[100:101]
	v_lshl_add_u64 v[98:99], v[98:99], 0, v[112:113]
	v_add_f32_e32 v96, v96, v97
	v_fmamk_f32 v96, v96, 0x3a800000, v150
	v_rsq_f32_e32 v96, v96
	v_lshl_add_u64 v[100:101], s[60:61], 0, v[118:119]
	v_pk_mul_f32 v[80:81], v[80:81], v[96:97] op_sel_hi:[1,0]
	v_pk_mul_f32 v[82:83], v[82:83], v[96:97] op_sel_hi:[1,0]
	v_pk_mul_f32 v[84:85], v[84:85], v[96:97] op_sel_hi:[1,0]
	v_pk_mul_f32 v[86:87], v[86:87], v[96:97] op_sel_hi:[1,0]
	v_pk_mul_f32 v[88:89], v[88:89], v[96:97] op_sel_hi:[1,0]
	v_pk_mul_f32 v[90:91], v[90:91], v[96:97] op_sel_hi:[1,0]
; DI u32x4 pack_v8(f32x4 v0, f32x4 v1) { u32x4 w; w.x = pk2(v0[0], v0[1]); w.y = pk2(v0[2], v0[3]); w.z = pk2(v1[0], v1[1]); w.w = pk2(v1[2], v1[3]); return w; }
; DI float rstd16(const float* ssq, int row) { const f32x4* p = (const f32x4*)(ssq + (size_t)row * 16); const f32x4 a = p[0], b = p[1], c = p[2], d = p[3];
;   return __builtin_amdgcn_rsqf((((a[0] + a[1]) + (a[2] + a[3])) + ((b[0] + b[1]) + (b[2] + b[3])) + ((c[0] + c[1]) + (c[2] + c[3])) + ((d[0] + d[1]) + (d[2] + d[3]))) * (1.0f / 1024.0f) + EPS); }
;   DI void operator()(AccRef acc, const Unit& u, int wr, int wc, int fr, int fq) const {
;     const int rowb = u.pm * 256 + wr * 64 + fr; const int cb = u.pn * 256 + wc * 32 + 8 * fq;
; #pragma unroll
;     for (int ai = 0; ai < 2; ++ai)
; #pragma unroll
;       for (int m = 0; m < 4; ++m) { const int row = rowb + ai * 128 + m * 16; const float rs = rstd16(SSQH, row);
; #pragma unroll
;         for (int bj = 0; bj < 2; ++bj) { f32x4 v0 = acc[ai][bj][m][0], v1 = acc[ai][bj][m][1];
; #pragma unroll
;           for (int j = 0; j < 4; ++j) { const float a = fmaxf(v0[j], 0.f) * rs, b = fmaxf(v1[j], 0.f) * rs; v0[j] = a * a; v1[j] = b * b; }
;           *(u32x4*)(A2 + (size_t)row * DFF + cb + bj * 128) = pack_v8(v0, v1); } }
;   }
	v_pk_mul_f32 v[92:93], v[92:93], v[96:97] op_sel_hi:[1,0]
	v_pk_mul_f32 v[94:95], v[94:95], v[96:97] op_sel_hi:[1,0]
	v_pk_mul_f32 v[80:81], v[80:81], v[80:81]
	v_pk_mul_f32 v[82:83], v[82:83], v[82:83]
	v_pk_mul_f32 v[84:85], v[84:85], v[84:85]
	v_pk_mul_f32 v[86:87], v[86:87], v[86:87]
	v_pk_mul_f32 v[88:89], v[88:89], v[88:89]
	v_pk_mul_f32 v[90:91], v[90:91], v[90:91]
	v_pk_mul_f32 v[92:93], v[92:93], v[92:93]
	v_pk_mul_f32 v[94:95], v[94:95], v[94:95]
	v_cvt_pk_bf16_f32 v80, v80, v81
	v_cvt_pk_bf16_f32 v81, v84, v85
	v_cvt_pk_bf16_f32 v82, v82, v83
	v_cvt_pk_bf16_f32 v83, v86, v87
	v_cvt_pk_bf16_f32 v84, v88, v89
	v_cvt_pk_bf16_f32 v85, v92, v93
	v_cvt_pk_bf16_f32 v86, v90, v91
	v_cvt_pk_bf16_f32 v87, v94, v95
	global_store_dwordx4 v[98:99], v[80:83], off
	global_store_dwordx4 v[98:99], v[84:87], off offset:256
	s_nop 0
	v_max_f32_e32 v98, v69, v69
	v_max_f32_e32 v99, v65, v65
	v_max_f32_e32 v65, 0, v77
	v_max_f32_e32 v69, 0, v79
	v_max_f32_e32 v77, 0, v71
	v_max_f32_e32 v79, 0, v67
	v_max_f32_e32 v96, v68, v68
	v_max_f32_e32 v97, v64, v64
	v_max_f32_e32 v100, v70, v70
	v_max_f32_e32 v101, v66, v66
	v_max_f32_e32 v64, 0, v76
	v_max_f32_e32 v66, 0, v72
	v_max_f32_e32 v67, 0, v73
	v_max_f32_e32 v68, 0, v78
	v_max_f32_e32 v70, 0, v74
	v_max_f32_e32 v71, 0, v75
	v_max_f32_e32 v72, 0, v96
	v_max_f32_e32 v74, 0, v97
	v_max_f32_e32 v73, 0, v98
	v_max_f32_e32 v75, 0, v99
	v_max_f32_e32 v76, 0, v100
	v_max_f32_e32 v78, 0, v101
	v_add_u32_e32 v96, 0x80, v144
	v_lshlrev_b64 v[98:99], 13, v[114:115]
	v_ashrrev_i32_e32 v97, 31, v96
	v_lshlrev_b64 v[100:101], 6, v[96:97]
	s_waitcnt vmcnt(8) lgkmcnt(0)
	v_mov_b32_e32 v80, v192
	v_mov_b32_e32 v81, v193
	v_mov_b32_e32 v82, v194
	v_mov_b32_e32 v83, v195
	v_mov_b32_e32 v84, v196
	v_mov_b32_e32 v85, v197
	v_mov_b32_e32 v86, v198
	v_mov_b32_e32 v87, v199
	v_mov_b32_e32 v88, v200
	v_mov_b32_e32 v89, v201
	v_mov_b32_e32 v90, v202
	v_mov_b32_e32 v91, v203
	v_mov_b32_e32 v92, v204
	v_mov_b32_e32 v93, v205
	v_mov_b32_e32 v94, v206
	v_mov_b32_e32 v95, v207
	global_load_dwordx4 v[192:195], v[210:211], off offset:1024
	global_load_dwordx4 v[196:199], v[210:211], off offset:1040
	global_load_dwordx4 v[200:203], v[210:211], off offset:1056
	global_load_dwordx4 v[204:207], v[210:211], off offset:1072
	v_mov_b32_e32 v102, v81
	v_mov_b32_e32 v103, v82
	v_mov_b32_e32 v81, v83
	v_mov_b32_e32 v82, v85
	v_mov_b32_e32 v83, v86
	v_mov_b32_e32 v85, v87
	v_pk_add_f32 v[80:81], v[102:103], v[80:81]
	v_pk_add_f32 v[82:83], v[82:83], v[84:85]
	v_pk_add_f32 v[80:81], v[80:81], v[80:81] op_sel:[0,1] op_sel_hi:[1,0]
	v_pk_add_f32 v[82:83], v[82:83], v[82:83] op_sel:[0,1] op_sel_hi:[1,0]
	v_add_f32_e32 v86, v88, v89
	v_add_f32_e32 v88, v90, v91
	v_mov_b32_e32 v87, v94
	v_mov_b32_e32 v89, v95
	v_mov_b32_e32 v81, v92
	v_mov_b32_e32 v83, v93
	v_pk_add_f32 v[84:85], v[86:87], v[88:89]
	v_pk_add_f32 v[80:81], v[80:81], v[82:83]
	v_lshl_add_u64 v[82:83], s[52:53], 0, v[98:99]
	v_pk_add_f32 v[80:81], v[80:81], v[84:85]
	v_lshl_add_u64 v[82:83], v[82:83], 0, v[112:113]
	v_add_f32_e32 v80, v80, v81
	v_fmamk_f32 v80, v80, 0x3a800000, v150
	v_rsq_f32_e32 v80, v80
	v_lshl_add_u64 v[84:85], s[60:61], 0, v[100:101]
	v_pk_mul_f32 v[64:65], v[64:65], v[80:81] op_sel_hi:[1,0]
	v_pk_mul_f32 v[66:67], v[66:67], v[80:81] op_sel_hi:[1,0]
	v_pk_mul_f32 v[68:69], v[68:69], v[80:81] op_sel_hi:[1,0]
	v_pk_mul_f32 v[70:71], v[70:71], v[80:81] op_sel_hi:[1,0]
	v_pk_mul_f32 v[72:73], v[72:73], v[80:81] op_sel_hi:[1,0]
	v_pk_mul_f32 v[74:75], v[74:75], v[80:81] op_sel_hi:[1,0]
	v_pk_mul_f32 v[76:77], v[76:77], v[80:81] op_sel_hi:[1,0]
	v_pk_mul_f32 v[78:79], v[78:79], v[80:81] op_sel_hi:[1,0]
	v_pk_mul_f32 v[64:65], v[64:65], v[64:65]
	v_pk_mul_f32 v[66:67], v[66:67], v[66:67]
	v_pk_mul_f32 v[68:69], v[68:69], v[68:69]
	v_pk_mul_f32 v[70:71], v[70:71], v[70:71]
	v_pk_mul_f32 v[72:73], v[72:73], v[72:73]
	v_pk_mul_f32 v[74:75], v[74:75], v[74:75]
	v_pk_mul_f32 v[76:77], v[76:77], v[76:77]
	v_pk_mul_f32 v[78:79], v[78:79], v[78:79]
	v_cvt_pk_bf16_f32 v64, v64, v65
	v_cvt_pk_bf16_f32 v65, v68, v69
	v_cvt_pk_bf16_f32 v66, v66, v67
	v_cvt_pk_bf16_f32 v67, v70, v71
	v_cvt_pk_bf16_f32 v68, v72, v73
	v_cvt_pk_bf16_f32 v69, v76, v77
	v_cvt_pk_bf16_f32 v70, v74, v75
	v_cvt_pk_bf16_f32 v71, v78, v79
	global_store_dwordx4 v[82:83], v[64:67], off
	global_store_dwordx4 v[82:83], v[68:71], off offset:256
	s_nop 0
	v_max_f32_e32 v82, v53, v53
	v_max_f32_e32 v83, v49, v49
	v_max_f32_e32 v49, 0, v61
	v_max_f32_e32 v53, 0, v63
	v_max_f32_e32 v61, 0, v55
	v_max_f32_e32 v63, 0, v51
	v_max_f32_e32 v80, v52, v52
	v_max_f32_e32 v81, v48, v48
	v_max_f32_e32 v84, v54, v54
	v_max_f32_e32 v85, v50, v50
	v_max_f32_e32 v48, 0, v60
	v_max_f32_e32 v50, 0, v56
	v_max_f32_e32 v51, 0, v57
	v_max_f32_e32 v52, 0, v62
	v_max_f32_e32 v54, 0, v58
	v_max_f32_e32 v55, 0, v59
	v_max_f32_e32 v56, 0, v80
	v_max_f32_e32 v58, 0, v81
	v_max_f32_e32 v57, 0, v82
	v_max_f32_e32 v59, 0, v83
	v_max_f32_e32 v60, 0, v84
	v_max_f32_e32 v62, 0, v85
	v_add_u32_e32 v80, 0x90, v144
	v_lshlrev_b64 v[82:83], 13, v[96:97]
	v_ashrrev_i32_e32 v81, 31, v80
	v_lshlrev_b64 v[84:85], 6, v[80:81]
	s_waitcnt vmcnt(8) lgkmcnt(0)
; DI u32x4 pack_v8(f32x4 v0, f32x4 v1) { u32x4 w; w.x = pk2(v0[0], v0[1]); w.y = pk2(v0[2], v0[3]); w.z = pk2(v1[0], v1[1]); w.w = pk2(v1[2], v1[3]); return w; }
; DI float rstd16(const float* ssq, int row) { const f32x4* p = (const f32x4*)(ssq + (size_t)row * 16); const f32x4 a = p[0], b = p[1], c = p[2], d = p[3];
;   return __builtin_amdgcn_rsqf((((a[0] + a[1]) + (a[2] + a[3])) + ((b[0] + b[1]) + (b[2] + b[3])) + ((c[0] + c[1]) + (c[2] + c[3])) + ((d[0] + d[1]) + (d[2] + d[3]))) * (1.0f / 1024.0f) + EPS); }
;   DI void operator()(AccRef acc, const Unit& u, int wr, int wc, int fr, int fq) const {
;     const int rowb = u.pm * 256 + wr * 64 + fr; const int cb = u.pn * 256 + wc * 32 + 8 * fq;
; #pragma unroll
;     for (int ai = 0; ai < 2; ++ai)
; #pragma unroll
;       for (int m = 0; m < 4; ++m) { const int row = rowb + ai * 128 + m * 16; const float rs = rstd16(SSQH, row);
; #pragma unroll
;         for (int bj = 0; bj < 2; ++bj) { f32x4 v0 = acc[ai][bj][m][0], v1 = acc[ai][bj][m][1];
; #pragma unroll
;           for (int j = 0; j < 4; ++j) { const float a = fmaxf(v0[j], 0.f) * rs, b = fmaxf(v1[j], 0.f) * rs; v0[j] = a * a; v1[j] = b * b; }
;           *(u32x4*)(A2 + (size_t)row * DFF + cb + bj * 128) = pack_v8(v0, v1); } }
;   }
	v_mov_b32_e32 v64, v176
	v_mov_b32_e32 v65, v177
	v_mov_b32_e32 v66, v178
	v_mov_b32_e32 v67, v179
	v_mov_b32_e32 v68, v180
	v_mov_b32_e32 v69, v181
	v_mov_b32_e32 v70, v182
	v_mov_b32_e32 v71, v183
	v_mov_b32_e32 v72, v184
	v_mov_b32_e32 v73, v185
	v_mov_b32_e32 v74, v186
	v_mov_b32_e32 v75, v187
	v_mov_b32_e32 v76, v188
	v_mov_b32_e32 v77, v189
	v_mov_b32_e32 v78, v190
	v_mov_b32_e32 v79, v191
	global_load_dwordx4 v[176:179], v[210:211], off offset:2048
	global_load_dwordx4 v[180:183], v[210:211], off offset:2064
	global_load_dwordx4 v[184:187], v[210:211], off offset:2080
	global_load_dwordx4 v[188:191], v[210:211], off offset:2096
	v_mov_b32_e32 v86, v65
	v_mov_b32_e32 v87, v66
	v_mov_b32_e32 v65, v67
	v_mov_b32_e32 v66, v69
	v_mov_b32_e32 v67, v70
	v_mov_b32_e32 v69, v71
	v_pk_add_f32 v[64:65], v[86:87], v[64:65]
	v_pk_add_f32 v[66:67], v[66:67], v[68:69]
	v_pk_add_f32 v[64:65], v[64:65], v[64:65] op_sel:[0,1] op_sel_hi:[1,0]
	v_pk_add_f32 v[66:67], v[66:67], v[66:67] op_sel:[0,1] op_sel_hi:[1,0]
	v_add_f32_e32 v70, v72, v73
	v_add_f32_e32 v72, v74, v75
	v_mov_b32_e32 v71, v78
	v_mov_b32_e32 v73, v79
	v_mov_b32_e32 v65, v76
	v_mov_b32_e32 v67, v77
	v_pk_add_f32 v[68:69], v[70:71], v[72:73]
	v_pk_add_f32 v[64:65], v[64:65], v[66:67]
	v_lshl_add_u64 v[66:67], s[52:53], 0, v[82:83]
	v_pk_add_f32 v[64:65], v[64:65], v[68:69]
	v_lshl_add_u64 v[66:67], v[66:67], 0, v[112:113]
	v_add_f32_e32 v64, v64, v65
	v_fmamk_f32 v64, v64, 0x3a800000, v150
	v_rsq_f32_e32 v64, v64
	v_lshl_add_u64 v[68:69], s[60:61], 0, v[84:85]
	v_pk_mul_f32 v[48:49], v[48:49], v[64:65] op_sel_hi:[1,0]
	v_pk_mul_f32 v[50:51], v[50:51], v[64:65] op_sel_hi:[1,0]
	v_pk_mul_f32 v[52:53], v[52:53], v[64:65] op_sel_hi:[1,0]
	v_pk_mul_f32 v[54:55], v[54:55], v[64:65] op_sel_hi:[1,0]
	v_pk_mul_f32 v[56:57], v[56:57], v[64:65] op_sel_hi:[1,0]
	v_pk_mul_f32 v[58:59], v[58:59], v[64:65] op_sel_hi:[1,0]
	v_pk_mul_f32 v[60:61], v[60:61], v[64:65] op_sel_hi:[1,0]
	v_pk_mul_f32 v[62:63], v[62:63], v[64:65] op_sel_hi:[1,0]
	v_pk_mul_f32 v[48:49], v[48:49], v[48:49]
	v_pk_mul_f32 v[50:51], v[50:51], v[50:51]
	v_pk_mul_f32 v[52:53], v[52:53], v[52:53]
	v_pk_mul_f32 v[54:55], v[54:55], v[54:55]
	v_pk_mul_f32 v[56:57], v[56:57], v[56:57]
	v_pk_mul_f32 v[58:59], v[58:59], v[58:59]
	v_pk_mul_f32 v[60:61], v[60:61], v[60:61]
	v_pk_mul_f32 v[62:63], v[62:63], v[62:63]
	v_cvt_pk_bf16_f32 v48, v48, v49
	v_cvt_pk_bf16_f32 v49, v52, v53
	v_cvt_pk_bf16_f32 v50, v50, v51
	v_cvt_pk_bf16_f32 v51, v54, v55
	v_cvt_pk_bf16_f32 v52, v56, v57
	v_cvt_pk_bf16_f32 v53, v60, v61
	v_cvt_pk_bf16_f32 v54, v58, v59
	v_cvt_pk_bf16_f32 v55, v62, v63
	global_store_dwordx4 v[66:67], v[48:51], off
	global_store_dwordx4 v[66:67], v[52:55], off offset:256
	s_nop 0
	v_max_f32_e32 v66, v37, v37
	v_max_f32_e32 v67, v33, v33
	v_max_f32_e32 v33, 0, v45
	v_max_f32_e32 v37, 0, v47
	v_max_f32_e32 v45, 0, v39
	v_max_f32_e32 v47, 0, v35
	v_max_f32_e32 v64, v36, v36
	v_max_f32_e32 v65, v32, v32
	v_max_f32_e32 v68, v38, v38
	v_max_f32_e32 v69, v34, v34
	v_max_f32_e32 v32, 0, v44
	v_max_f32_e32 v34, 0, v40
	v_max_f32_e32 v35, 0, v41
	v_max_f32_e32 v36, 0, v46
	v_max_f32_e32 v38, 0, v42
	v_max_f32_e32 v39, 0, v43
	v_max_f32_e32 v40, 0, v64
	v_max_f32_e32 v42, 0, v65
	v_max_f32_e32 v41, 0, v66
	v_max_f32_e32 v43, 0, v67
	v_max_f32_e32 v44, 0, v68
	v_max_f32_e32 v46, 0, v69
	v_add_u32_e32 v64, 0xa0, v144
	v_lshlrev_b64 v[66:67], 13, v[80:81]
	v_ashrrev_i32_e32 v65, 31, v64
	v_lshlrev_b64 v[68:69], 6, v[64:65]
	s_waitcnt vmcnt(8) lgkmcnt(0)
	v_mov_b32_e32 v48, v192
	v_mov_b32_e32 v49, v193
	v_mov_b32_e32 v50, v194
	v_mov_b32_e32 v51, v195
	v_mov_b32_e32 v52, v196
	v_mov_b32_e32 v53, v197
	v_mov_b32_e32 v54, v198
	v_mov_b32_e32 v55, v199
	v_mov_b32_e32 v56, v200
	v_mov_b32_e32 v57, v201
	v_mov_b32_e32 v58, v202
	v_mov_b32_e32 v59, v203
	v_mov_b32_e32 v60, v204
	v_mov_b32_e32 v61, v205
	v_mov_b32_e32 v62, v206
	v_mov_b32_e32 v63, v207
	global_load_dwordx4 v[192:195], v[210:211], off offset:3072
	global_load_dwordx4 v[196:199], v[210:211], off offset:3088
	global_load_dwordx4 v[200:203], v[210:211], off offset:3104
	global_load_dwordx4 v[204:207], v[210:211], off offset:3120
	v_mov_b32_e32 v70, v49
	v_mov_b32_e32 v71, v50
	v_mov_b32_e32 v49, v51
	v_mov_b32_e32 v50, v53
	v_mov_b32_e32 v51, v54
	v_mov_b32_e32 v53, v55
	v_pk_add_f32 v[48:49], v[70:71], v[48:49]
	v_pk_add_f32 v[50:51], v[50:51], v[52:53]
	v_pk_add_f32 v[48:49], v[48:49], v[48:49] op_sel:[0,1] op_sel_hi:[1,0]
	v_pk_add_f32 v[50:51], v[50:51], v[50:51] op_sel:[0,1] op_sel_hi:[1,0]
	v_add_f32_e32 v54, v56, v57
	v_add_f32_e32 v56, v58, v59
	v_mov_b32_e32 v55, v62
	v_mov_b32_e32 v57, v63
	v_mov_b32_e32 v49, v60
	v_mov_b32_e32 v51, v61
	v_pk_add_f32 v[52:53], v[54:55], v[56:57]
	v_pk_add_f32 v[48:49], v[48:49], v[50:51]
	v_lshl_add_u64 v[50:51], s[52:53], 0, v[66:67]
	v_pk_add_f32 v[48:49], v[48:49], v[52:53]
	v_lshl_add_u64 v[50:51], v[50:51], 0, v[112:113]
	v_add_f32_e32 v48, v48, v49
	v_fmamk_f32 v48, v48, 0x3a800000, v150
	v_rsq_f32_e32 v48, v48
	v_lshl_add_u64 v[52:53], s[60:61], 0, v[68:69]
	v_pk_mul_f32 v[32:33], v[32:33], v[48:49] op_sel_hi:[1,0]
	v_pk_mul_f32 v[34:35], v[34:35], v[48:49] op_sel_hi:[1,0]
	v_pk_mul_f32 v[36:37], v[36:37], v[48:49] op_sel_hi:[1,0]
	v_pk_mul_f32 v[38:39], v[38:39], v[48:49] op_sel_hi:[1,0]
	v_pk_mul_f32 v[40:41], v[40:41], v[48:49] op_sel_hi:[1,0]
	v_pk_mul_f32 v[42:43], v[42:43], v[48:49] op_sel_hi:[1,0]
	v_pk_mul_f32 v[44:45], v[44:45], v[48:49] op_sel_hi:[1,0]
	v_pk_mul_f32 v[46:47], v[46:47], v[48:49] op_sel_hi:[1,0]
	v_pk_mul_f32 v[32:33], v[32:33], v[32:33]
	v_pk_mul_f32 v[34:35], v[34:35], v[34:35]
	v_pk_mul_f32 v[36:37], v[36:37], v[36:37]
	v_pk_mul_f32 v[38:39], v[38:39], v[38:39]
	v_pk_mul_f32 v[40:41], v[40:41], v[40:41]
	v_pk_mul_f32 v[42:43], v[42:43], v[42:43]
	v_pk_mul_f32 v[44:45], v[44:45], v[44:45]
	v_pk_mul_f32 v[46:47], v[46:47], v[46:47]
	v_cvt_pk_bf16_f32 v32, v32, v33
	v_cvt_pk_bf16_f32 v33, v36, v37
	v_cvt_pk_bf16_f32 v34, v34, v35
	v_cvt_pk_bf16_f32 v35, v38, v39
	v_cvt_pk_bf16_f32 v36, v40, v41
	v_cvt_pk_bf16_f32 v37, v44, v45
	v_cvt_pk_bf16_f32 v38, v42, v43
	v_cvt_pk_bf16_f32 v39, v46, v47
	global_store_dwordx4 v[50:51], v[32:35], off
	global_store_dwordx4 v[50:51], v[36:39], off offset:256
	s_nop 0
	v_max_f32_e32 v50, v21, v21
	v_max_f32_e32 v51, v17, v17
	v_max_f32_e32 v17, 0, v29
	v_max_f32_e32 v21, 0, v31
	v_max_f32_e32 v29, 0, v23
	v_max_f32_e32 v31, 0, v19
	v_max_f32_e32 v48, v20, v20
	v_max_f32_e32 v49, v16, v16
	v_max_f32_e32 v52, v22, v22
	v_max_f32_e32 v53, v18, v18
	v_max_f32_e32 v16, 0, v28
	v_max_f32_e32 v18, 0, v24
	v_max_f32_e32 v19, 0, v25
	v_max_f32_e32 v20, 0, v30
	v_max_f32_e32 v22, 0, v26
	v_max_f32_e32 v23, 0, v27
	v_max_f32_e32 v24, 0, v48
	v_max_f32_e32 v26, 0, v49
	v_max_f32_e32 v25, 0, v50
	v_max_f32_e32 v27, 0, v51
	v_max_f32_e32 v28, 0, v52
	v_max_f32_e32 v30, 0, v53
	v_add_u32_e32 v48, 0xb0, v144
	v_lshlrev_b64 v[50:51], 13, v[64:65]
	v_ashrrev_i32_e32 v49, 31, v48
	v_lshlrev_b64 v[52:53], 6, v[48:49]
	s_waitcnt vmcnt(8) lgkmcnt(0)
; DI float ozero() { float z = 0.f; asm volatile("" : "+v"(z)); return z; }
; DI int otid() { int t = threadIdx.x; asm volatile("" : "+v"(t)); return t; }
; #define PG8_BAR __builtin_amdgcn_s_barrier()
; DI u32x4 pack_v8(f32x4 v0, f32x4 v1) { u32x4 w; w.x = pk2(v0[0], v0[1]); w.y = pk2(v0[2], v0[3]); w.z = pk2(v1[0], v1[1]); w.w = pk2(v1[2], v1[3]); return w; }
; template <class Epi, class Sched>
; DI void gemm_phase(LAS unsigned char* lds, const Gemm g, const Sched& S, const Epi& E) {
;     ...
;     if (wr == 0) PG8_BAR;
;     { const int l2 = otid() & 63; E(acc, cur, wr, wc, l2 & 15, l2 >> 4); }
;     if (!has_next) break;
;     { const float z0 = ozero();
; #pragma unroll
;     for (int a = 0; a < 2; ++a)
; #pragma unroll
;       for (int b = 0; b < 2; ++b)
; #pragma unroll
;         for (int m = 0; m < 4; ++m)
; #pragma unroll
;           for (int n = 0; n < 2; ++n) acc[a][b][m][n] = (f32x4){z0, z0, z0, z0}; }
;     cur = nxt; cA = nA; cB = nB; ++ui;
;     if (wr == 1) PG8_BAR;
; DI float rstd16(const float* ssq, int row) { const f32x4* p = (const f32x4*)(ssq + (size_t)row * 16); const f32x4 a = p[0], b = p[1], c = p[2], d = p[3];
;   return __builtin_amdgcn_rsqf((((a[0] + a[1]) + (a[2] + a[3])) + ((b[0] + b[1]) + (b[2] + b[3])) + ((c[0] + c[1]) + (c[2] + c[3])) + ((d[0] + d[1]) + (d[2] + d[3]))) * (1.0f / 1024.0f) + EPS); }
;   DI void operator()(AccRef acc, const Unit& u, int wr, int wc, int fr, int fq) const {
;     const int rowb = u.pm * 256 + wr * 64 + fr; const int cb = u.pn * 256 + wc * 32 + 8 * fq;
; #pragma unroll
;     for (int ai = 0; ai < 2; ++ai)
; #pragma unroll
;       for (int m = 0; m < 4; ++m) { const int row = rowb + ai * 128 + m * 16; const float rs = rstd16(SSQH, row);
; #pragma unroll
;         for (int bj = 0; bj < 2; ++bj) { f32x4 v0 = acc[ai][bj][m][0], v1 = acc[ai][bj][m][1];
; #pragma unroll
;           for (int j = 0; j < 4; ++j) { const float a = fmaxf(v0[j], 0.f) * rs, b = fmaxf(v1[j], 0.f) * rs; v0[j] = a * a; v1[j] = b * b; }
;           *(u32x4*)(A2 + (size_t)row * DFF + cb + bj * 128) = pack_v8(v0, v1); } }
;   }
	v_mov_b32_e32 v32, v176
	v_mov_b32_e32 v33, v177
	v_mov_b32_e32 v34, v178
	v_mov_b32_e32 v35, v179
	v_mov_b32_e32 v36, v180
	v_mov_b32_e32 v37, v181
	v_mov_b32_e32 v38, v182
	v_mov_b32_e32 v39, v183
	v_mov_b32_e32 v40, v184
	v_mov_b32_e32 v41, v185
	v_mov_b32_e32 v42, v186
	v_mov_b32_e32 v43, v187
	v_mov_b32_e32 v44, v188
	v_mov_b32_e32 v45, v189
	v_mov_b32_e32 v46, v190
	v_mov_b32_e32 v47, v191
	v_mov_b32_e32 v54, v33
	v_mov_b32_e32 v55, v34
	v_mov_b32_e32 v33, v35
	v_mov_b32_e32 v34, v37
	v_mov_b32_e32 v35, v38
	v_mov_b32_e32 v37, v39
	v_pk_add_f32 v[32:33], v[54:55], v[32:33]
	v_pk_add_f32 v[34:35], v[34:35], v[36:37]
	v_pk_add_f32 v[32:33], v[32:33], v[32:33] op_sel:[0,1] op_sel_hi:[1,0]
	v_pk_add_f32 v[34:35], v[34:35], v[34:35] op_sel:[0,1] op_sel_hi:[1,0]
	v_add_f32_e32 v38, v40, v41
	v_add_f32_e32 v40, v42, v43
	v_mov_b32_e32 v39, v46
	v_mov_b32_e32 v41, v47
	v_mov_b32_e32 v33, v44
	v_mov_b32_e32 v35, v45
	v_pk_add_f32 v[36:37], v[38:39], v[40:41]
	v_pk_add_f32 v[32:33], v[32:33], v[34:35]
	v_lshl_add_u64 v[34:35], s[52:53], 0, v[50:51]
	v_pk_add_f32 v[32:33], v[32:33], v[36:37]
	v_lshl_add_u64 v[34:35], v[34:35], 0, v[112:113]
	v_add_f32_e32 v32, v32, v33
	v_fmamk_f32 v32, v32, 0x3a800000, v150
	v_rsq_f32_e32 v32, v32
	v_lshl_add_u64 v[36:37], s[60:61], 0, v[52:53]
	v_max_f32_e32 v38, v7, v7
	v_max_f32_e32 v39, v3, v3
	v_pk_mul_f32 v[16:17], v[16:17], v[32:33] op_sel_hi:[1,0]
	v_pk_mul_f32 v[18:19], v[18:19], v[32:33] op_sel_hi:[1,0]
	v_pk_mul_f32 v[20:21], v[20:21], v[32:33] op_sel_hi:[1,0]
	v_pk_mul_f32 v[22:23], v[22:23], v[32:33] op_sel_hi:[1,0]
	v_pk_mul_f32 v[24:25], v[24:25], v[32:33] op_sel_hi:[1,0]
	v_pk_mul_f32 v[26:27], v[26:27], v[32:33] op_sel_hi:[1,0]
	v_pk_mul_f32 v[28:29], v[28:29], v[32:33] op_sel_hi:[1,0]
	v_pk_mul_f32 v[30:31], v[30:31], v[32:33] op_sel_hi:[1,0]
	v_pk_mul_f32 v[16:17], v[16:17], v[16:17]
	v_pk_mul_f32 v[18:19], v[18:19], v[18:19]
	v_pk_mul_f32 v[20:21], v[20:21], v[20:21]
	v_pk_mul_f32 v[22:23], v[22:23], v[22:23]
	v_pk_mul_f32 v[24:25], v[24:25], v[24:25]
	v_pk_mul_f32 v[26:27], v[26:27], v[26:27]
	v_pk_mul_f32 v[28:29], v[28:29], v[28:29]
	v_pk_mul_f32 v[30:31], v[30:31], v[30:31]
	v_cvt_pk_bf16_f32 v16, v16, v17
	v_cvt_pk_bf16_f32 v17, v20, v21
	v_cvt_pk_bf16_f32 v18, v18, v19
	v_cvt_pk_bf16_f32 v19, v22, v23
	v_cvt_pk_bf16_f32 v20, v24, v25
	v_cvt_pk_bf16_f32 v21, v28, v29
	v_cvt_pk_bf16_f32 v22, v26, v27
	v_cvt_pk_bf16_f32 v23, v30, v31
	global_store_dwordx4 v[34:35], v[16:19], off
	global_store_dwordx4 v[34:35], v[20:23], off offset:256
	s_nop 0
	v_max_f32_e32 v36, v6, v6
	v_max_f32_e32 v37, v2, v2
	v_max_f32_e32 v2, 0, v8
	v_max_f32_e32 v6, 0, v10
	v_max_f32_e32 v8, 0, v4
	v_max_f32_e32 v10, 0, v0
	v_max_f32_e32 v34, v5, v5
	v_max_f32_e32 v35, v1, v1
	v_max_f32_e32 v0, 0, v12
	v_max_f32_e32 v1, 0, v13
	v_max_f32_e32 v3, 0, v9
	v_max_f32_e32 v4, 0, v14
	v_max_f32_e32 v5, 0, v15
	v_max_f32_e32 v7, 0, v11
	v_max_f32_e32 v9, 0, v34
	v_max_f32_e32 v11, 0, v35
	v_max_f32_e32 v12, 0, v36
	v_max_f32_e32 v14, 0, v37
	v_max_f32_e32 v13, 0, v38
	v_max_f32_e32 v15, 0, v39
	s_waitcnt vmcnt(4) lgkmcnt(0)
	v_mov_b32_e32 v16, v192
	v_mov_b32_e32 v17, v193
	v_mov_b32_e32 v18, v194
	v_mov_b32_e32 v19, v195
	v_mov_b32_e32 v20, v196
	v_mov_b32_e32 v21, v197
	v_mov_b32_e32 v22, v198
	v_mov_b32_e32 v23, v199
	v_mov_b32_e32 v24, v200
	v_mov_b32_e32 v25, v201
	v_mov_b32_e32 v26, v202
	v_mov_b32_e32 v27, v203
	v_mov_b32_e32 v28, v204
	v_mov_b32_e32 v29, v205
	v_mov_b32_e32 v30, v206
	v_mov_b32_e32 v31, v207
	v_mov_b32_e32 v32, v17
	v_mov_b32_e32 v33, v18
	v_mov_b32_e32 v17, v19
	v_mov_b32_e32 v18, v21
	v_mov_b32_e32 v19, v22
	v_mov_b32_e32 v21, v23
	v_pk_add_f32 v[16:17], v[32:33], v[16:17]
	v_pk_add_f32 v[18:19], v[18:19], v[20:21]
	v_pk_add_f32 v[16:17], v[16:17], v[16:17] op_sel:[0,1] op_sel_hi:[1,0]
	v_pk_add_f32 v[18:19], v[18:19], v[18:19] op_sel:[0,1] op_sel_hi:[1,0]
	v_add_f32_e32 v22, v24, v25
	v_add_f32_e32 v24, v26, v27
	v_mov_b32_e32 v23, v30
	v_mov_b32_e32 v25, v31
	v_mov_b32_e32 v17, v28
	v_mov_b32_e32 v19, v29
	v_pk_add_f32 v[20:21], v[22:23], v[24:25]
	v_pk_add_f32 v[16:17], v[16:17], v[18:19]
	v_lshlrev_b64 v[18:19], 13, v[48:49]
	v_pk_add_f32 v[16:17], v[16:17], v[20:21]
	v_lshl_add_u64 v[18:19], s[52:53], 0, v[18:19]
	v_add_f32_e32 v16, v16, v17
	v_fmamk_f32 v16, v16, 0x3a800000, v150
	v_rsq_f32_e32 v16, v16
	v_lshl_add_u64 v[18:19], v[18:19], 0, v[112:113]
	v_pk_mul_f32 v[0:1], v[0:1], v[16:17] op_sel_hi:[1,0]
	v_pk_mul_f32 v[2:3], v[2:3], v[16:17] op_sel_hi:[1,0]
	v_pk_mul_f32 v[4:5], v[4:5], v[16:17] op_sel_hi:[1,0]
	v_pk_mul_f32 v[6:7], v[6:7], v[16:17] op_sel_hi:[1,0]
	v_pk_mul_f32 v[8:9], v[8:9], v[16:17] op_sel_hi:[1,0]
	v_pk_mul_f32 v[10:11], v[10:11], v[16:17] op_sel_hi:[1,0]
	v_pk_mul_f32 v[12:13], v[12:13], v[16:17] op_sel_hi:[1,0]
	v_pk_mul_f32 v[14:15], v[14:15], v[16:17] op_sel_hi:[1,0]
	v_pk_mul_f32 v[0:1], v[0:1], v[0:1]
	v_pk_mul_f32 v[2:3], v[2:3], v[2:3]
	v_pk_mul_f32 v[4:5], v[4:5], v[4:5]
	v_pk_mul_f32 v[6:7], v[6:7], v[6:7]
	v_pk_mul_f32 v[8:9], v[8:9], v[8:9]
	v_pk_mul_f32 v[10:11], v[10:11], v[10:11]
	v_pk_mul_f32 v[12:13], v[12:13], v[12:13]
	v_pk_mul_f32 v[14:15], v[14:15], v[14:15]
	v_cvt_pk_bf16_f32 v0, v0, v1
	v_cvt_pk_bf16_f32 v1, v4, v5
	v_cvt_pk_bf16_f32 v2, v2, v3
	v_cvt_pk_bf16_f32 v3, v6, v7
	v_cvt_pk_bf16_f32 v4, v8, v9
	v_cvt_pk_bf16_f32 v5, v12, v13
	v_cvt_pk_bf16_f32 v6, v10, v11
	v_cvt_pk_bf16_f32 v7, v14, v15
	global_store_dwordx4 v[18:19], v[0:3], off
	global_store_dwordx4 v[18:19], v[4:7], off offset:256
	s_cbranch_vccnz .LBB0_892
	v_mov_b32_e32 v0, 0
	s_andn2_b64 vcc, exec, s[6:7]
	s_cbranch_vccnz .LBB0_891
	s_barrier
	s_branch .LBB0_891

; DI u32x4 pack_v8(f32x4 v0, f32x4 v1) { u32x4 w; w.x = pk2(v0[0], v0[1]); w.y = pk2(v0[2], v0[3]); w.z = pk2(v1[0], v1[1]); w.w = pk2(v1[2], v1[3]); return w; }
; DI float rstd16(const float* ssq, int row) { const f32x4* p = (const f32x4*)(ssq + (size_t)row * 16); const f32x4 a = p[0], b = p[1], c = p[2], d = p[3];
;   return __builtin_amdgcn_rsqf((((a[0] + a[1]) + (a[2] + a[3])) + ((b[0] + b[1]) + (b[2] + b[3])) + ((c[0] + c[1]) + (c[2] + c[3])) + ((d[0] + d[1]) + (d[2] + d[3]))) * (1.0f / 1024.0f) + EPS); }
;   DI void operator()(AccRef acc, const Unit& u, int wr, int wc, int fr, int fq) const {
;     const int rowb = u.pm * 256 + wr * 64 + fr; const int cb = u.pn * 256 + wc * 32 + 8 * fq;
; #pragma unroll
;     for (int ai = 0; ai < 2; ++ai)
; #pragma unroll
;       for (int m = 0; m < 4; ++m) { const int row = rowb + ai * 128 + m * 16; const float rs = rstd16(SSQH, row);
; #pragma unroll
;         for (int bj = 0; bj < 2; ++bj) { f32x4 v0 = acc[ai][bj][m][0], v1 = acc[ai][bj][m][1];
; #pragma unroll
;           for (int j = 0; j < 4; ++j) { const float a = fmaxf(v0[j], 0.f) * rs, b = fmaxf(v1[j], 0.f) * rs; v0[j] = a * a; v1[j] = b * b; }
;           *(u32x4*)(A2 + (size_t)row * DFF + cb + bj * 128) = pack_v8(v0, v1); } }
;   }
.LBB0_1683:
	s_lshl_b32 s13, s22, 8
	v_mov_b32_e32 v151, v224
	s_add_i32 s13, s13, s36
	v_and_or_b32 v144, v151, 15, s13
	v_ashrrev_i32_e32 v145, 31, v144
	v_lshlrev_b64 v[152:153], 6, v[144:145]
	v_lshl_add_u64 v[164:165], s[58:59], 0, v[152:153]
	v_mov_b32_e32 v208, v164
	v_mov_b32_e32 v209, v165
	s_mov_b64 s[98:99], 0x2000
	v_lshl_add_u64 v[210:211], s[98:99], 0, v[164:165]
	global_load_dwordx4 v[152:155], v[164:165], off
	global_load_dwordx4 v[156:159], v[164:165], off offset:16
	global_load_dwordx4 v[160:163], v[164:165], off offset:32
	s_nop 0
	global_load_dwordx4 v[164:167], v[164:165], off offset:48
	global_load_dwordx4 v[192:195], v[208:209], off offset:1024
	global_load_dwordx4 v[196:199], v[208:209], off offset:1040
	global_load_dwordx4 v[200:203], v[208:209], off offset:1056
	global_load_dwordx4 v[204:207], v[208:209], off offset:1072
	v_max_f32_e32 v169, v117, v117
	v_max_f32_e32 v172, v119, v119
	v_max_f32_e32 v117, 0, v121
	v_max_f32_e32 v119, 0, v127
	v_max_f32_e32 v121, 0, v123
	v_max_f32_e32 v123, 0, v169
	v_max_f32_e32 v127, 0, v172
	v_max_f32_e32 v169, 0, v115
	v_lshlrev_b64 v[172:173], 13, v[144:145]
	s_lshl_b32 s13, s66, 8
	v_max_f32_e32 v171, v114, v114
	v_max_f32_e32 v114, 0, v124
	v_max_f32_e32 v124, 0, v112
	v_lshrrev_b32_e32 v112, 1, v151
	v_and_or_b32 v112, v112, 24, s13
	v_max_f32_e32 v168, v116, v116
	v_max_f32_e32 v170, v118, v118
	v_max_f32_e32 v116, 0, v120
	v_max_f32_e32 v115, 0, v125
	v_max_f32_e32 v118, 0, v126
	v_max_f32_e32 v120, 0, v122
	v_or_b32_e32 v112, s37, v112
	v_max_f32_e32 v122, 0, v168
	v_max_f32_e32 v125, 0, v113
	v_max_f32_e32 v126, 0, v170
	v_max_f32_e32 v168, 0, v171
	v_ashrrev_i32_e32 v113, 31, v112
	v_or_b32_e32 v170, 16, v144
	v_lshlrev_b64 v[112:113], 1, v[112:113]
	v_ashrrev_i32_e32 v171, 31, v170
	v_max_f32_e32 v151, v97, v97
	v_max_f32_e32 v97, 0, v109
	s_waitcnt vmcnt(4) lgkmcnt(0)
	global_load_dwordx4 v[176:179], v[208:209], off offset:2048
	global_load_dwordx4 v[180:183], v[208:209], off offset:2064
	global_load_dwordx4 v[184:187], v[208:209], off offset:2080
	global_load_dwordx4 v[188:191], v[208:209], off offset:2096
	v_mov_b32_e32 v174, v153
	v_mov_b32_e32 v175, v154
	v_mov_b32_e32 v153, v155
	v_mov_b32_e32 v154, v157
	v_mov_b32_e32 v155, v158
	v_mov_b32_e32 v157, v159
	v_pk_add_f32 v[152:153], v[174:175], v[152:153]
	v_pk_add_f32 v[154:155], v[154:155], v[156:157]
	v_pk_add_f32 v[152:153], v[152:153], v[152:153] op_sel:[0,1] op_sel_hi:[1,0]
	v_pk_add_f32 v[154:155], v[154:155], v[154:155] op_sel:[0,1] op_sel_hi:[1,0]
	v_add_f32_e32 v158, v160, v161
	v_add_f32_e32 v160, v162, v163
	v_mov_b32_e32 v159, v166
	v_mov_b32_e32 v161, v167
	v_mov_b32_e32 v153, v164
	v_mov_b32_e32 v155, v165
	v_pk_add_f32 v[156:157], v[158:159], v[160:161]
	v_pk_add_f32 v[152:153], v[152:153], v[154:155]
	v_lshl_add_u64 v[154:155], s[54:55], 0, v[172:173]
	v_pk_add_f32 v[152:153], v[152:153], v[156:157]
	v_lshl_add_u64 v[154:155], v[154:155], 0, v[112:113]
	v_add_f32_e32 v145, v152, v153
	v_fmamk_f32 v145, v145, 0x3a800000, v150
	v_rsq_f32_e32 v152, v145
	v_max_f32_e32 v145, v101, v101
	v_max_f32_e32 v156, v102, v102
	v_max_f32_e32 v157, v98, v98
	v_pk_mul_f32 v[114:115], v[114:115], v[152:153] op_sel_hi:[1,0]
	v_pk_mul_f32 v[116:117], v[116:117], v[152:153] op_sel_hi:[1,0]
	v_pk_mul_f32 v[118:119], v[118:119], v[152:153] op_sel_hi:[1,0]
	v_pk_mul_f32 v[120:121], v[120:121], v[152:153] op_sel_hi:[1,0]
	v_pk_mul_f32 v[122:123], v[122:123], v[152:153] op_sel_hi:[1,0]
	v_pk_mul_f32 v[124:125], v[124:125], v[152:153] op_sel_hi:[1,0]
	v_pk_mul_f32 v[126:127], v[126:127], v[152:153] op_sel_hi:[1,0]
	v_pk_mul_f32 v[152:153], v[168:169], v[152:153] op_sel_hi:[1,0]
	v_pk_mul_f32 v[114:115], v[114:115], v[114:115]
	v_pk_mul_f32 v[116:117], v[116:117], v[116:117]
	v_pk_mul_f32 v[118:119], v[118:119], v[118:119]
	v_pk_mul_f32 v[120:121], v[120:121], v[120:121]
	v_pk_mul_f32 v[122:123], v[122:123], v[122:123]
	v_pk_mul_f32 v[124:125], v[124:125], v[124:125]
	v_pk_mul_f32 v[126:127], v[126:127], v[126:127]
	v_pk_mul_f32 v[152:153], v[152:153], v[152:153]
	v_cvt_pk_bf16_f32 v114, v114, v115
	v_cvt_pk_bf16_f32 v115, v118, v119
	v_cvt_pk_bf16_f32 v116, v116, v117
	v_cvt_pk_bf16_f32 v117, v120, v121
	v_cvt_pk_bf16_f32 v118, v122, v123
	v_cvt_pk_bf16_f32 v119, v126, v127
	v_cvt_pk_bf16_f32 v120, v124, v125
	v_cvt_pk_bf16_f32 v121, v152, v153
	global_store_dwordx4 v[154:155], v[114:117], off
	global_store_dwordx4 v[154:155], v[118:121], off offset:256
	v_max_f32_e32 v158, v103, v103
	v_lshlrev_b64 v[114:115], 6, v[170:171]
	v_lshl_add_u64 v[126:127], s[58:59], 0, v[114:115]
	v_max_f32_e32 v126, v100, v100
	v_max_f32_e32 v127, v96, v96
	v_max_f32_e32 v159, v99, v99
	v_max_f32_e32 v96, 0, v108
	v_max_f32_e32 v98, 0, v104
	v_max_f32_e32 v99, 0, v105
	v_max_f32_e32 v100, 0, v110
	v_max_f32_e32 v102, 0, v106
	v_max_f32_e32 v101, 0, v111
	v_max_f32_e32 v103, 0, v107
	v_max_f32_e32 v104, 0, v126
	v_max_f32_e32 v106, 0, v127
	v_max_f32_e32 v105, 0, v145
	v_max_f32_e32 v107, 0, v151
	v_max_f32_e32 v108, 0, v156
	v_max_f32_e32 v110, 0, v157
	v_max_f32_e32 v109, 0, v158
	v_max_f32_e32 v111, 0, v159
	v_or_b32_e32 v126, 32, v144
	v_lshlrev_b64 v[156:157], 13, v[170:171]
	v_ashrrev_i32_e32 v127, 31, v126
	v_lshlrev_b64 v[158:159], 6, v[126:127]
	s_andn2_b64 vcc, exec, s[4:5]
	s_mov_b64 s[4:5], -1
	s_waitcnt vmcnt(6) lgkmcnt(0)
; DI u32x4 pack_v8(f32x4 v0, f32x4 v1) { u32x4 w; w.x = pk2(v0[0], v0[1]); w.y = pk2(v0[2], v0[3]); w.z = pk2(v1[0], v1[1]); w.w = pk2(v1[2], v1[3]); return w; }
; DI float rstd16(const float* ssq, int row) { const f32x4* p = (const f32x4*)(ssq + (size_t)row * 16); const f32x4 a = p[0], b = p[1], c = p[2], d = p[3];
;   return __builtin_amdgcn_rsqf((((a[0] + a[1]) + (a[2] + a[3])) + ((b[0] + b[1]) + (b[2] + b[3])) + ((c[0] + c[1]) + (c[2] + c[3])) + ((d[0] + d[1]) + (d[2] + d[3]))) * (1.0f / 1024.0f) + EPS); }
;   DI void operator()(AccRef acc, const Unit& u, int wr, int wc, int fr, int fq) const {
;     const int rowb = u.pm * 256 + wr * 64 + fr; const int cb = u.pn * 256 + wc * 32 + 8 * fq;
; #pragma unroll
;     for (int ai = 0; ai < 2; ++ai)
; #pragma unroll
;       for (int m = 0; m < 4; ++m) { const int row = rowb + ai * 128 + m * 16; const float rs = rstd16(SSQH, row);
; #pragma unroll
;         for (int bj = 0; bj < 2; ++bj) { f32x4 v0 = acc[ai][bj][m][0], v1 = acc[ai][bj][m][1];
; #pragma unroll
;           for (int j = 0; j < 4; ++j) { const float a = fmaxf(v0[j], 0.f) * rs, b = fmaxf(v1[j], 0.f) * rs; v0[j] = a * a; v1[j] = b * b; }
;           *(u32x4*)(A2 + (size_t)row * DFF + cb + bj * 128) = pack_v8(v0, v1); } }
;   }
	v_mov_b32_e32 v114, v192
	v_mov_b32_e32 v115, v193
	v_mov_b32_e32 v116, v194
	v_mov_b32_e32 v117, v195
	v_mov_b32_e32 v118, v196
	v_mov_b32_e32 v119, v197
	v_mov_b32_e32 v120, v198
	v_mov_b32_e32 v121, v199
	v_mov_b32_e32 v122, v200
	v_mov_b32_e32 v123, v201
	v_mov_b32_e32 v124, v202
	v_mov_b32_e32 v125, v203
	v_mov_b32_e32 v152, v204
	v_mov_b32_e32 v153, v205
	v_mov_b32_e32 v154, v206
	v_mov_b32_e32 v155, v207
	global_load_dwordx4 v[192:195], v[208:209], off offset:3072
	global_load_dwordx4 v[196:199], v[208:209], off offset:3088
	global_load_dwordx4 v[200:203], v[208:209], off offset:3104
	global_load_dwordx4 v[204:207], v[208:209], off offset:3120
	v_mov_b32_e32 v160, v115
	v_mov_b32_e32 v161, v116
	v_mov_b32_e32 v115, v117
	v_mov_b32_e32 v116, v119
	v_mov_b32_e32 v117, v120
	v_mov_b32_e32 v119, v121
	v_pk_add_f32 v[114:115], v[160:161], v[114:115]
	v_pk_add_f32 v[116:117], v[116:117], v[118:119]
	v_pk_add_f32 v[114:115], v[114:115], v[114:115] op_sel:[0,1] op_sel_hi:[1,0]
	v_pk_add_f32 v[116:117], v[116:117], v[116:117] op_sel:[0,1] op_sel_hi:[1,0]
	v_add_f32_e32 v120, v122, v123
	v_add_f32_e32 v122, v124, v125
	v_mov_b32_e32 v121, v154
	v_mov_b32_e32 v123, v155
	v_mov_b32_e32 v115, v152
	v_mov_b32_e32 v117, v153
	v_pk_add_f32 v[118:119], v[120:121], v[122:123]
	v_pk_add_f32 v[114:115], v[114:115], v[116:117]
	v_lshl_add_u64 v[116:117], s[54:55], 0, v[156:157]
	v_pk_add_f32 v[114:115], v[114:115], v[118:119]
	v_lshl_add_u64 v[116:117], v[116:117], 0, v[112:113]
	v_add_f32_e32 v114, v114, v115
	v_fmamk_f32 v114, v114, 0x3a800000, v150
	v_rsq_f32_e32 v114, v114
	v_lshl_add_u64 v[118:119], s[58:59], 0, v[158:159]
	v_pk_mul_f32 v[96:97], v[96:97], v[114:115] op_sel_hi:[1,0]
	v_pk_mul_f32 v[98:99], v[98:99], v[114:115] op_sel_hi:[1,0]
	v_pk_mul_f32 v[100:101], v[100:101], v[114:115] op_sel_hi:[1,0]
	v_pk_mul_f32 v[102:103], v[102:103], v[114:115] op_sel_hi:[1,0]
	v_pk_mul_f32 v[104:105], v[104:105], v[114:115] op_sel_hi:[1,0]
	v_pk_mul_f32 v[106:107], v[106:107], v[114:115] op_sel_hi:[1,0]
	v_pk_mul_f32 v[108:109], v[108:109], v[114:115] op_sel_hi:[1,0]
	v_pk_mul_f32 v[110:111], v[110:111], v[114:115] op_sel_hi:[1,0]
	v_pk_mul_f32 v[96:97], v[96:97], v[96:97]
	v_pk_mul_f32 v[98:99], v[98:99], v[98:99]
	v_pk_mul_f32 v[100:101], v[100:101], v[100:101]
	v_pk_mul_f32 v[102:103], v[102:103], v[102:103]
	v_pk_mul_f32 v[104:105], v[104:105], v[104:105]
	v_pk_mul_f32 v[106:107], v[106:107], v[106:107]
	v_pk_mul_f32 v[108:109], v[108:109], v[108:109]
	v_pk_mul_f32 v[110:111], v[110:111], v[110:111]
	v_cvt_pk_bf16_f32 v96, v96, v97
	v_cvt_pk_bf16_f32 v97, v100, v101
	v_cvt_pk_bf16_f32 v98, v98, v99
	v_cvt_pk_bf16_f32 v99, v102, v103
	v_cvt_pk_bf16_f32 v100, v104, v105
	v_cvt_pk_bf16_f32 v101, v108, v109
	v_cvt_pk_bf16_f32 v102, v106, v107
	v_cvt_pk_bf16_f32 v103, v110, v111
	global_store_dwordx4 v[116:117], v[96:99], off
	global_store_dwordx4 v[116:117], v[100:103], off offset:256
	s_nop 0
	v_max_f32_e32 v116, v85, v85
	v_max_f32_e32 v117, v81, v81
	v_max_f32_e32 v81, 0, v93
	v_max_f32_e32 v85, 0, v95
	v_max_f32_e32 v93, 0, v87
	v_max_f32_e32 v95, 0, v83
	v_max_f32_e32 v114, v84, v84
	v_max_f32_e32 v115, v80, v80
	v_max_f32_e32 v118, v86, v86
	v_max_f32_e32 v119, v82, v82
	v_max_f32_e32 v80, 0, v92
	v_max_f32_e32 v82, 0, v88
	v_max_f32_e32 v83, 0, v89
	v_max_f32_e32 v84, 0, v94
	v_max_f32_e32 v86, 0, v90
	v_max_f32_e32 v87, 0, v91
	v_max_f32_e32 v88, 0, v114
	v_max_f32_e32 v90, 0, v115
	v_max_f32_e32 v89, 0, v116
	v_max_f32_e32 v91, 0, v117
	v_max_f32_e32 v92, 0, v118
	v_max_f32_e32 v94, 0, v119
	v_or_b32_e32 v114, 48, v144
	v_lshlrev_b64 v[116:117], 13, v[126:127]
	v_ashrrev_i32_e32 v115, 31, v114
	v_lshlrev_b64 v[118:119], 6, v[114:115]
	s_waitcnt vmcnt(8) lgkmcnt(0)
	v_mov_b32_e32 v96, v176
	v_mov_b32_e32 v97, v177
	v_mov_b32_e32 v98, v178
	v_mov_b32_e32 v99, v179
	v_mov_b32_e32 v100, v180
	v_mov_b32_e32 v101, v181
	v_mov_b32_e32 v102, v182
	v_mov_b32_e32 v103, v183
	v_mov_b32_e32 v104, v184
	v_mov_b32_e32 v105, v185
	v_mov_b32_e32 v106, v186
	v_mov_b32_e32 v107, v187
	v_mov_b32_e32 v108, v188
	v_mov_b32_e32 v109, v189
	v_mov_b32_e32 v110, v190
	v_mov_b32_e32 v111, v191
	global_load_dwordx4 v[176:179], v[210:211], off offset:0
	global_load_dwordx4 v[180:183], v[210:211], off offset:16
	global_load_dwordx4 v[184:187], v[210:211], off offset:32
	global_load_dwordx4 v[188:191], v[210:211], off offset:48
	v_mov_b32_e32 v120, v97
	v_mov_b32_e32 v121, v98
	v_mov_b32_e32 v97, v99
	v_mov_b32_e32 v98, v101
	v_mov_b32_e32 v99, v102
	v_mov_b32_e32 v101, v103
	v_pk_add_f32 v[96:97], v[120:121], v[96:97]
	v_pk_add_f32 v[98:99], v[98:99], v[100:101]
	v_pk_add_f32 v[96:97], v[96:97], v[96:97] op_sel:[0,1] op_sel_hi:[1,0]
	v_pk_add_f32 v[98:99], v[98:99], v[98:99] op_sel:[0,1] op_sel_hi:[1,0]
	v_add_f32_e32 v102, v104, v105
	v_add_f32_e32 v104, v106, v107
	v_mov_b32_e32 v103, v110
	v_mov_b32_e32 v105, v111
	v_mov_b32_e32 v97, v108
	v_mov_b32_e32 v99, v109
	v_pk_add_f32 v[100:101], v[102:103], v[104:105]
	v_pk_add_f32 v[96:97], v[96:97], v[98:99]
	v_lshl_add_u64 v[98:99], s[54:55], 0, v[116:117]
	v_pk_add_f32 v[96:97], v[96:97], v[100:101]
	v_lshl_add_u64 v[98:99], v[98:99], 0, v[112:113]
	v_add_f32_e32 v96, v96, v97
	v_fmamk_f32 v96, v96, 0x3a800000, v150
	v_rsq_f32_e32 v96, v96
	v_lshl_add_u64 v[100:101], s[58:59], 0, v[118:119]
	v_pk_mul_f32 v[80:81], v[80:81], v[96:97] op_sel_hi:[1,0]
	v_pk_mul_f32 v[82:83], v[82:83], v[96:97] op_sel_hi:[1,0]
	v_pk_mul_f32 v[84:85], v[84:85], v[96:97] op_sel_hi:[1,0]
	v_pk_mul_f32 v[86:87], v[86:87], v[96:97] op_sel_hi:[1,0]
	v_pk_mul_f32 v[88:89], v[88:89], v[96:97] op_sel_hi:[1,0]
	v_pk_mul_f32 v[90:91], v[90:91], v[96:97] op_sel_hi:[1,0]
; DI u32x4 pack_v8(f32x4 v0, f32x4 v1) { u32x4 w; w.x = pk2(v0[0], v0[1]); w.y = pk2(v0[2], v0[3]); w.z = pk2(v1[0], v1[1]); w.w = pk2(v1[2], v1[3]); return w; }
; DI float rstd16(const float* ssq, int row) { const f32x4* p = (const f32x4*)(ssq + (size_t)row * 16); const f32x4 a = p[0], b = p[1], c = p[2], d = p[3];
;   return __builtin_amdgcn_rsqf((((a[0] + a[1]) + (a[2] + a[3])) + ((b[0] + b[1]) + (b[2] + b[3])) + ((c[0] + c[1]) + (c[2] + c[3])) + ((d[0] + d[1]) + (d[2] + d[3]))) * (1.0f / 1024.0f) + EPS); }
;   DI void operator()(AccRef acc, const Unit& u, int wr, int wc, int fr, int fq) const {
;     const int rowb = u.pm * 256 + wr * 64 + fr; const int cb = u.pn * 256 + wc * 32 + 8 * fq;
; #pragma unroll
;     for (int ai = 0; ai < 2; ++ai)
; #pragma unroll
;       for (int m = 0; m < 4; ++m) { const int row = rowb + ai * 128 + m * 16; const float rs = rstd16(SSQH, row);
; #pragma unroll
;         for (int bj = 0; bj < 2; ++bj) { f32x4 v0 = acc[ai][bj][m][0], v1 = acc[ai][bj][m][1];
; #pragma unroll
;           for (int j = 0; j < 4; ++j) { const float a = fmaxf(v0[j], 0.f) * rs, b = fmaxf(v1[j], 0.f) * rs; v0[j] = a * a; v1[j] = b * b; }
;           *(u32x4*)(A2 + (size_t)row * DFF + cb + bj * 128) = pack_v8(v0, v1); } }
;   }
	v_pk_mul_f32 v[92:93], v[92:93], v[96:97] op_sel_hi:[1,0]
	v_pk_mul_f32 v[94:95], v[94:95], v[96:97] op_sel_hi:[1,0]
	v_pk_mul_f32 v[80:81], v[80:81], v[80:81]
	v_pk_mul_f32 v[82:83], v[82:83], v[82:83]
	v_pk_mul_f32 v[84:85], v[84:85], v[84:85]
	v_pk_mul_f32 v[86:87], v[86:87], v[86:87]
	v_pk_mul_f32 v[88:89], v[88:89], v[88:89]
	v_pk_mul_f32 v[90:91], v[90:91], v[90:91]
	v_pk_mul_f32 v[92:93], v[92:93], v[92:93]
	v_pk_mul_f32 v[94:95], v[94:95], v[94:95]
	v_cvt_pk_bf16_f32 v80, v80, v81
	v_cvt_pk_bf16_f32 v81, v84, v85
	v_cvt_pk_bf16_f32 v82, v82, v83
	v_cvt_pk_bf16_f32 v83, v86, v87
	v_cvt_pk_bf16_f32 v84, v88, v89
	v_cvt_pk_bf16_f32 v85, v92, v93
	v_cvt_pk_bf16_f32 v86, v90, v91
	v_cvt_pk_bf16_f32 v87, v94, v95
	global_store_dwordx4 v[98:99], v[80:83], off
	global_store_dwordx4 v[98:99], v[84:87], off offset:256
	s_nop 0
	v_max_f32_e32 v98, v69, v69
	v_max_f32_e32 v99, v65, v65
	v_max_f32_e32 v65, 0, v77
	v_max_f32_e32 v69, 0, v79
	v_max_f32_e32 v77, 0, v71
	v_max_f32_e32 v79, 0, v67
	v_max_f32_e32 v96, v68, v68
	v_max_f32_e32 v97, v64, v64
	v_max_f32_e32 v100, v70, v70
	v_max_f32_e32 v101, v66, v66
	v_max_f32_e32 v64, 0, v76
	v_max_f32_e32 v66, 0, v72
	v_max_f32_e32 v67, 0, v73
	v_max_f32_e32 v68, 0, v78
	v_max_f32_e32 v70, 0, v74
	v_max_f32_e32 v71, 0, v75
	v_max_f32_e32 v72, 0, v96
	v_max_f32_e32 v74, 0, v97
	v_max_f32_e32 v73, 0, v98
	v_max_f32_e32 v75, 0, v99
	v_max_f32_e32 v76, 0, v100
	v_max_f32_e32 v78, 0, v101
	v_add_u32_e32 v96, 0x80, v144
	v_lshlrev_b64 v[98:99], 13, v[114:115]
	v_ashrrev_i32_e32 v97, 31, v96
	v_lshlrev_b64 v[100:101], 6, v[96:97]
	s_waitcnt vmcnt(8) lgkmcnt(0)
	v_mov_b32_e32 v80, v192
	v_mov_b32_e32 v81, v193
	v_mov_b32_e32 v82, v194
	v_mov_b32_e32 v83, v195
	v_mov_b32_e32 v84, v196
	v_mov_b32_e32 v85, v197
	v_mov_b32_e32 v86, v198
	v_mov_b32_e32 v87, v199
	v_mov_b32_e32 v88, v200
	v_mov_b32_e32 v89, v201
	v_mov_b32_e32 v90, v202
	v_mov_b32_e32 v91, v203
	v_mov_b32_e32 v92, v204
	v_mov_b32_e32 v93, v205
	v_mov_b32_e32 v94, v206
	v_mov_b32_e32 v95, v207
	global_load_dwordx4 v[192:195], v[210:211], off offset:1024
	global_load_dwordx4 v[196:199], v[210:211], off offset:1040
	global_load_dwordx4 v[200:203], v[210:211], off offset:1056
	global_load_dwordx4 v[204:207], v[210:211], off offset:1072
	v_mov_b32_e32 v102, v81
	v_mov_b32_e32 v103, v82
	v_mov_b32_e32 v81, v83
	v_mov_b32_e32 v82, v85
	v_mov_b32_e32 v83, v86
	v_mov_b32_e32 v85, v87
	v_pk_add_f32 v[80:81], v[102:103], v[80:81]
	v_pk_add_f32 v[82:83], v[82:83], v[84:85]
	v_pk_add_f32 v[80:81], v[80:81], v[80:81] op_sel:[0,1] op_sel_hi:[1,0]
	v_pk_add_f32 v[82:83], v[82:83], v[82:83] op_sel:[0,1] op_sel_hi:[1,0]
	v_add_f32_e32 v86, v88, v89
	v_add_f32_e32 v88, v90, v91
	v_mov_b32_e32 v87, v94
	v_mov_b32_e32 v89, v95
	v_mov_b32_e32 v81, v92
	v_mov_b32_e32 v83, v93
	v_pk_add_f32 v[84:85], v[86:87], v[88:89]
	v_pk_add_f32 v[80:81], v[80:81], v[82:83]
	v_lshl_add_u64 v[82:83], s[54:55], 0, v[98:99]
	v_pk_add_f32 v[80:81], v[80:81], v[84:85]
	v_lshl_add_u64 v[82:83], v[82:83], 0, v[112:113]
	v_add_f32_e32 v80, v80, v81
	v_fmamk_f32 v80, v80, 0x3a800000, v150
	v_rsq_f32_e32 v80, v80
	v_lshl_add_u64 v[84:85], s[58:59], 0, v[100:101]
	v_pk_mul_f32 v[64:65], v[64:65], v[80:81] op_sel_hi:[1,0]
	v_pk_mul_f32 v[66:67], v[66:67], v[80:81] op_sel_hi:[1,0]
	v_pk_mul_f32 v[68:69], v[68:69], v[80:81] op_sel_hi:[1,0]
	v_pk_mul_f32 v[70:71], v[70:71], v[80:81] op_sel_hi:[1,0]
	v_pk_mul_f32 v[72:73], v[72:73], v[80:81] op_sel_hi:[1,0]
	v_pk_mul_f32 v[74:75], v[74:75], v[80:81] op_sel_hi:[1,0]
	v_pk_mul_f32 v[76:77], v[76:77], v[80:81] op_sel_hi:[1,0]
	v_pk_mul_f32 v[78:79], v[78:79], v[80:81] op_sel_hi:[1,0]
	v_pk_mul_f32 v[64:65], v[64:65], v[64:65]
	v_pk_mul_f32 v[66:67], v[66:67], v[66:67]
	v_pk_mul_f32 v[68:69], v[68:69], v[68:69]
	v_pk_mul_f32 v[70:71], v[70:71], v[70:71]
	v_pk_mul_f32 v[72:73], v[72:73], v[72:73]
	v_pk_mul_f32 v[74:75], v[74:75], v[74:75]
	v_pk_mul_f32 v[76:77], v[76:77], v[76:77]
	v_pk_mul_f32 v[78:79], v[78:79], v[78:79]
	v_cvt_pk_bf16_f32 v64, v64, v65
	v_cvt_pk_bf16_f32 v65, v68, v69
	v_cvt_pk_bf16_f32 v66, v66, v67
	v_cvt_pk_bf16_f32 v67, v70, v71
	v_cvt_pk_bf16_f32 v68, v72, v73
	v_cvt_pk_bf16_f32 v69, v76, v77
	v_cvt_pk_bf16_f32 v70, v74, v75
	v_cvt_pk_bf16_f32 v71, v78, v79
	global_store_dwordx4 v[82:83], v[64:67], off
	global_store_dwordx4 v[82:83], v[68:71], off offset:256
	s_nop 0
	v_max_f32_e32 v82, v53, v53
	v_max_f32_e32 v83, v49, v49
	v_max_f32_e32 v49, 0, v61
	v_max_f32_e32 v53, 0, v63
	v_max_f32_e32 v61, 0, v55
	v_max_f32_e32 v63, 0, v51
	v_max_f32_e32 v80, v52, v52
	v_max_f32_e32 v81, v48, v48
	v_max_f32_e32 v84, v54, v54
	v_max_f32_e32 v85, v50, v50
	v_max_f32_e32 v48, 0, v60
	v_max_f32_e32 v50, 0, v56
	v_max_f32_e32 v51, 0, v57
	v_max_f32_e32 v52, 0, v62
	v_max_f32_e32 v54, 0, v58
	v_max_f32_e32 v55, 0, v59
	v_max_f32_e32 v56, 0, v80
	v_max_f32_e32 v58, 0, v81
	v_max_f32_e32 v57, 0, v82
	v_max_f32_e32 v59, 0, v83
	v_max_f32_e32 v60, 0, v84
	v_max_f32_e32 v62, 0, v85
	v_add_u32_e32 v80, 0x90, v144
	v_lshlrev_b64 v[82:83], 13, v[96:97]
	v_ashrrev_i32_e32 v81, 31, v80
	v_lshlrev_b64 v[84:85], 6, v[80:81]
	s_waitcnt vmcnt(8) lgkmcnt(0)
; DI u32x4 pack_v8(f32x4 v0, f32x4 v1) { u32x4 w; w.x = pk2(v0[0], v0[1]); w.y = pk2(v0[2], v0[3]); w.z = pk2(v1[0], v1[1]); w.w = pk2(v1[2], v1[3]); return w; }
; DI float rstd16(const float* ssq, int row) { const f32x4* p = (const f32x4*)(ssq + (size_t)row * 16); const f32x4 a = p[0], b = p[1], c = p[2], d = p[3];
;   return __builtin_amdgcn_rsqf((((a[0] + a[1]) + (a[2] + a[3])) + ((b[0] + b[1]) + (b[2] + b[3])) + ((c[0] + c[1]) + (c[2] + c[3])) + ((d[0] + d[1]) + (d[2] + d[3]))) * (1.0f / 1024.0f) + EPS); }
;   DI void operator()(AccRef acc, const Unit& u, int wr, int wc, int fr, int fq) const {
;     const int rowb = u.pm * 256 + wr * 64 + fr; const int cb = u.pn * 256 + wc * 32 + 8 * fq;
; #pragma unroll
;     for (int ai = 0; ai < 2; ++ai)
; #pragma unroll
;       for (int m = 0; m < 4; ++m) { const int row = rowb + ai * 128 + m * 16; const float rs = rstd16(SSQH, row);
; #pragma unroll
;         for (int bj = 0; bj < 2; ++bj) { f32x4 v0 = acc[ai][bj][m][0], v1 = acc[ai][bj][m][1];
; #pragma unroll
;           for (int j = 0; j < 4; ++j) { const float a = fmaxf(v0[j], 0.f) * rs, b = fmaxf(v1[j], 0.f) * rs; v0[j] = a * a; v1[j] = b * b; }
;           *(u32x4*)(A2 + (size_t)row * DFF + cb + bj * 128) = pack_v8(v0, v1); } }
;   }
	v_mov_b32_e32 v64, v176
	v_mov_b32_e32 v65, v177
	v_mov_b32_e32 v66, v178
	v_mov_b32_e32 v67, v179
	v_mov_b32_e32 v68, v180
	v_mov_b32_e32 v69, v181
	v_mov_b32_e32 v70, v182
	v_mov_b32_e32 v71, v183
	v_mov_b32_e32 v72, v184
	v_mov_b32_e32 v73, v185
	v_mov_b32_e32 v74, v186
	v_mov_b32_e32 v75, v187
	v_mov_b32_e32 v76, v188
	v_mov_b32_e32 v77, v189
	v_mov_b32_e32 v78, v190
	v_mov_b32_e32 v79, v191
	global_load_dwordx4 v[176:179], v[210:211], off offset:2048
	global_load_dwordx4 v[180:183], v[210:211], off offset:2064
	global_load_dwordx4 v[184:187], v[210:211], off offset:2080
	global_load_dwordx4 v[188:191], v[210:211], off offset:2096
	v_mov_b32_e32 v86, v65
	v_mov_b32_e32 v87, v66
	v_mov_b32_e32 v65, v67
	v_mov_b32_e32 v66, v69
	v_mov_b32_e32 v67, v70
	v_mov_b32_e32 v69, v71
	v_pk_add_f32 v[64:65], v[86:87], v[64:65]
	v_pk_add_f32 v[66:67], v[66:67], v[68:69]
	v_pk_add_f32 v[64:65], v[64:65], v[64:65] op_sel:[0,1] op_sel_hi:[1,0]
	v_pk_add_f32 v[66:67], v[66:67], v[66:67] op_sel:[0,1] op_sel_hi:[1,0]
	v_add_f32_e32 v70, v72, v73
	v_add_f32_e32 v72, v74, v75
	v_mov_b32_e32 v71, v78
	v_mov_b32_e32 v73, v79
	v_mov_b32_e32 v65, v76
	v_mov_b32_e32 v67, v77
	v_pk_add_f32 v[68:69], v[70:71], v[72:73]
	v_pk_add_f32 v[64:65], v[64:65], v[66:67]
	v_lshl_add_u64 v[66:67], s[54:55], 0, v[82:83]
	v_pk_add_f32 v[64:65], v[64:65], v[68:69]
	v_lshl_add_u64 v[66:67], v[66:67], 0, v[112:113]
	v_add_f32_e32 v64, v64, v65
	v_fmamk_f32 v64, v64, 0x3a800000, v150
	v_rsq_f32_e32 v64, v64
	v_lshl_add_u64 v[68:69], s[58:59], 0, v[84:85]
	v_pk_mul_f32 v[48:49], v[48:49], v[64:65] op_sel_hi:[1,0]
	v_pk_mul_f32 v[50:51], v[50:51], v[64:65] op_sel_hi:[1,0]
	v_pk_mul_f32 v[52:53], v[52:53], v[64:65] op_sel_hi:[1,0]
	v_pk_mul_f32 v[54:55], v[54:55], v[64:65] op_sel_hi:[1,0]
	v_pk_mul_f32 v[56:57], v[56:57], v[64:65] op_sel_hi:[1,0]
	v_pk_mul_f32 v[58:59], v[58:59], v[64:65] op_sel_hi:[1,0]
	v_pk_mul_f32 v[60:61], v[60:61], v[64:65] op_sel_hi:[1,0]
	v_pk_mul_f32 v[62:63], v[62:63], v[64:65] op_sel_hi:[1,0]
	v_pk_mul_f32 v[48:49], v[48:49], v[48:49]
	v_pk_mul_f32 v[50:51], v[50:51], v[50:51]
	v_pk_mul_f32 v[52:53], v[52:53], v[52:53]
	v_pk_mul_f32 v[54:55], v[54:55], v[54:55]
	v_pk_mul_f32 v[56:57], v[56:57], v[56:57]
	v_pk_mul_f32 v[58:59], v[58:59], v[58:59]
	v_pk_mul_f32 v[60:61], v[60:61], v[60:61]
	v_pk_mul_f32 v[62:63], v[62:63], v[62:63]
	v_cvt_pk_bf16_f32 v48, v48, v49
	v_cvt_pk_bf16_f32 v49, v52, v53
	v_cvt_pk_bf16_f32 v50, v50, v51
	v_cvt_pk_bf16_f32 v51, v54, v55
	v_cvt_pk_bf16_f32 v52, v56, v57
	v_cvt_pk_bf16_f32 v53, v60, v61
	v_cvt_pk_bf16_f32 v54, v58, v59
	v_cvt_pk_bf16_f32 v55, v62, v63
	global_store_dwordx4 v[66:67], v[48:51], off
	global_store_dwordx4 v[66:67], v[52:55], off offset:256
	s_nop 0
	v_max_f32_e32 v66, v37, v37
	v_max_f32_e32 v67, v33, v33
	v_max_f32_e32 v33, 0, v45
	v_max_f32_e32 v37, 0, v47
	v_max_f32_e32 v45, 0, v39
	v_max_f32_e32 v47, 0, v35
	v_max_f32_e32 v64, v36, v36
	v_max_f32_e32 v65, v32, v32
	v_max_f32_e32 v68, v38, v38
	v_max_f32_e32 v69, v34, v34
	v_max_f32_e32 v32, 0, v44
	v_max_f32_e32 v34, 0, v40
	v_max_f32_e32 v35, 0, v41
	v_max_f32_e32 v36, 0, v46
	v_max_f32_e32 v38, 0, v42
	v_max_f32_e32 v39, 0, v43
	v_max_f32_e32 v40, 0, v64
	v_max_f32_e32 v42, 0, v65
	v_max_f32_e32 v41, 0, v66
	v_max_f32_e32 v43, 0, v67
	v_max_f32_e32 v44, 0, v68
	v_max_f32_e32 v46, 0, v69
	v_add_u32_e32 v64, 0xa0, v144
	v_lshlrev_b64 v[66:67], 13, v[80:81]
	v_ashrrev_i32_e32 v65, 31, v64
	v_lshlrev_b64 v[68:69], 6, v[64:65]
	s_waitcnt vmcnt(8) lgkmcnt(0)
	v_mov_b32_e32 v48, v192
	v_mov_b32_e32 v49, v193
	v_mov_b32_e32 v50, v194
	v_mov_b32_e32 v51, v195
	v_mov_b32_e32 v52, v196
	v_mov_b32_e32 v53, v197
	v_mov_b32_e32 v54, v198
	v_mov_b32_e32 v55, v199
	v_mov_b32_e32 v56, v200
	v_mov_b32_e32 v57, v201
	v_mov_b32_e32 v58, v202
	v_mov_b32_e32 v59, v203
	v_mov_b32_e32 v60, v204
	v_mov_b32_e32 v61, v205
	v_mov_b32_e32 v62, v206
	v_mov_b32_e32 v63, v207
	global_load_dwordx4 v[192:195], v[210:211], off offset:3072
	global_load_dwordx4 v[196:199], v[210:211], off offset:3088
	global_load_dwordx4 v[200:203], v[210:211], off offset:3104
	global_load_dwordx4 v[204:207], v[210:211], off offset:3120
	v_mov_b32_e32 v70, v49
	v_mov_b32_e32 v71, v50
	v_mov_b32_e32 v49, v51
	v_mov_b32_e32 v50, v53
	v_mov_b32_e32 v51, v54
	v_mov_b32_e32 v53, v55
	v_pk_add_f32 v[48:49], v[70:71], v[48:49]
	v_pk_add_f32 v[50:51], v[50:51], v[52:53]
	v_pk_add_f32 v[48:49], v[48:49], v[48:49] op_sel:[0,1] op_sel_hi:[1,0]
	v_pk_add_f32 v[50:51], v[50:51], v[50:51] op_sel:[0,1] op_sel_hi:[1,0]
	v_add_f32_e32 v54, v56, v57
	v_add_f32_e32 v56, v58, v59
	v_mov_b32_e32 v55, v62
	v_mov_b32_e32 v57, v63
	v_mov_b32_e32 v49, v60
	v_mov_b32_e32 v51, v61
	v_pk_add_f32 v[52:53], v[54:55], v[56:57]
	v_pk_add_f32 v[48:49], v[48:49], v[50:51]
	v_lshl_add_u64 v[50:51], s[54:55], 0, v[66:67]
	v_pk_add_f32 v[48:49], v[48:49], v[52:53]
	v_lshl_add_u64 v[50:51], v[50:51], 0, v[112:113]
	v_add_f32_e32 v48, v48, v49
	v_fmamk_f32 v48, v48, 0x3a800000, v150
	v_rsq_f32_e32 v48, v48
	v_lshl_add_u64 v[52:53], s[58:59], 0, v[68:69]
	v_pk_mul_f32 v[32:33], v[32:33], v[48:49] op_sel_hi:[1,0]
	v_pk_mul_f32 v[34:35], v[34:35], v[48:49] op_sel_hi:[1,0]
	v_pk_mul_f32 v[36:37], v[36:37], v[48:49] op_sel_hi:[1,0]
	v_pk_mul_f32 v[38:39], v[38:39], v[48:49] op_sel_hi:[1,0]
	v_pk_mul_f32 v[40:41], v[40:41], v[48:49] op_sel_hi:[1,0]
	v_pk_mul_f32 v[42:43], v[42:43], v[48:49] op_sel_hi:[1,0]
	v_pk_mul_f32 v[44:45], v[44:45], v[48:49] op_sel_hi:[1,0]
	v_pk_mul_f32 v[46:47], v[46:47], v[48:49] op_sel_hi:[1,0]
	v_pk_mul_f32 v[32:33], v[32:33], v[32:33]
	v_pk_mul_f32 v[34:35], v[34:35], v[34:35]
	v_pk_mul_f32 v[36:37], v[36:37], v[36:37]
	v_pk_mul_f32 v[38:39], v[38:39], v[38:39]
	v_pk_mul_f32 v[40:41], v[40:41], v[40:41]
	v_pk_mul_f32 v[42:43], v[42:43], v[42:43]
	v_pk_mul_f32 v[44:45], v[44:45], v[44:45]
	v_pk_mul_f32 v[46:47], v[46:47], v[46:47]
	v_cvt_pk_bf16_f32 v32, v32, v33
	v_cvt_pk_bf16_f32 v33, v36, v37
	v_cvt_pk_bf16_f32 v34, v34, v35
	v_cvt_pk_bf16_f32 v35, v38, v39
	v_cvt_pk_bf16_f32 v36, v40, v41
	v_cvt_pk_bf16_f32 v37, v44, v45
	v_cvt_pk_bf16_f32 v38, v42, v43
	v_cvt_pk_bf16_f32 v39, v46, v47
	global_store_dwordx4 v[50:51], v[32:35], off
	global_store_dwordx4 v[50:51], v[36:39], off offset:256
	s_nop 0
	v_max_f32_e32 v50, v21, v21
	v_max_f32_e32 v51, v17, v17
	v_max_f32_e32 v17, 0, v29
	v_max_f32_e32 v21, 0, v31
	v_max_f32_e32 v29, 0, v23
	v_max_f32_e32 v31, 0, v19
	v_max_f32_e32 v48, v20, v20
	v_max_f32_e32 v49, v16, v16
	v_max_f32_e32 v52, v22, v22
	v_max_f32_e32 v53, v18, v18
	v_max_f32_e32 v16, 0, v28
	v_max_f32_e32 v18, 0, v24
	v_max_f32_e32 v19, 0, v25
	v_max_f32_e32 v20, 0, v30
	v_max_f32_e32 v22, 0, v26
	v_max_f32_e32 v23, 0, v27
	v_max_f32_e32 v24, 0, v48
	v_max_f32_e32 v26, 0, v49
	v_max_f32_e32 v25, 0, v50
	v_max_f32_e32 v27, 0, v51
	v_max_f32_e32 v28, 0, v52
	v_max_f32_e32 v30, 0, v53
	v_add_u32_e32 v48, 0xb0, v144
	v_lshlrev_b64 v[50:51], 13, v[64:65]
	v_ashrrev_i32_e32 v49, 31, v48
	v_lshlrev_b64 v[52:53], 6, v[48:49]
	s_waitcnt vmcnt(8) lgkmcnt(0)
; DI float ozero() { float z = 0.f; asm volatile("" : "+v"(z)); return z; }
; DI int otid() { int t = threadIdx.x; asm volatile("" : "+v"(t)); return t; }
; #define PG8_BAR __builtin_amdgcn_s_barrier()
; DI u32x4 pack_v8(f32x4 v0, f32x4 v1) { u32x4 w; w.x = pk2(v0[0], v0[1]); w.y = pk2(v0[2], v0[3]); w.z = pk2(v1[0], v1[1]); w.w = pk2(v1[2], v1[3]); return w; }
; template <class Epi, class Sched>
; DI void gemm_phase(LAS unsigned char* lds, const Gemm g, const Sched& S, const Epi& E) {
;     ...
;     if (wr == 0) PG8_BAR;
;     { const int l2 = otid() & 63; E(acc, cur, wr, wc, l2 & 15, l2 >> 4); }
;     if (!has_next) break;
;     { const float z0 = ozero();
; #pragma unroll
;     for (int a = 0; a < 2; ++a)
; #pragma unroll
;       for (int b = 0; b < 2; ++b)
; #pragma unroll
;         for (int m = 0; m < 4; ++m)
; #pragma unroll
;           for (int n = 0; n < 2; ++n) acc[a][b][m][n] = (f32x4){z0, z0, z0, z0}; }
;     cur = nxt; cA = nA; cB = nB; ++ui;
;     if (wr == 1) PG8_BAR;
; DI float rstd16(const float* ssq, int row) { const f32x4* p = (const f32x4*)(ssq + (size_t)row * 16); const f32x4 a = p[0], b = p[1], c = p[2], d = p[3];
;   return __builtin_amdgcn_rsqf((((a[0] + a[1]) + (a[2] + a[3])) + ((b[0] + b[1]) + (b[2] + b[3])) + ((c[0] + c[1]) + (c[2] + c[3])) + ((d[0] + d[1]) + (d[2] + d[3]))) * (1.0f / 1024.0f) + EPS); }
;   DI void operator()(AccRef acc, const Unit& u, int wr, int wc, int fr, int fq) const {
;     const int rowb = u.pm * 256 + wr * 64 + fr; const int cb = u.pn * 256 + wc * 32 + 8 * fq;
; #pragma unroll
;     for (int ai = 0; ai < 2; ++ai)
; #pragma unroll
;       for (int m = 0; m < 4; ++m) { const int row = rowb + ai * 128 + m * 16; const float rs = rstd16(SSQH, row);
; #pragma unroll
;         for (int bj = 0; bj < 2; ++bj) { f32x4 v0 = acc[ai][bj][m][0], v1 = acc[ai][bj][m][1];
; #pragma unroll
;           for (int j = 0; j < 4; ++j) { const float a = fmaxf(v0[j], 0.f) * rs, b = fmaxf(v1[j], 0.f) * rs; v0[j] = a * a; v1[j] = b * b; }
;           *(u32x4*)(A2 + (size_t)row * DFF + cb + bj * 128) = pack_v8(v0, v1); } }
;   }
	v_mov_b32_e32 v32, v176
	v_mov_b32_e32 v33, v177
	v_mov_b32_e32 v34, v178
	v_mov_b32_e32 v35, v179
	v_mov_b32_e32 v36, v180
	v_mov_b32_e32 v37, v181
	v_mov_b32_e32 v38, v182
	v_mov_b32_e32 v39, v183
	v_mov_b32_e32 v40, v184
	v_mov_b32_e32 v41, v185
	v_mov_b32_e32 v42, v186
	v_mov_b32_e32 v43, v187
	v_mov_b32_e32 v44, v188
	v_mov_b32_e32 v45, v189
	v_mov_b32_e32 v46, v190
	v_mov_b32_e32 v47, v191
	v_mov_b32_e32 v54, v33
	v_mov_b32_e32 v55, v34
	v_mov_b32_e32 v33, v35
	v_mov_b32_e32 v34, v37
	v_mov_b32_e32 v35, v38
	v_mov_b32_e32 v37, v39
	v_pk_add_f32 v[32:33], v[54:55], v[32:33]
	v_pk_add_f32 v[34:35], v[34:35], v[36:37]
	v_pk_add_f32 v[32:33], v[32:33], v[32:33] op_sel:[0,1] op_sel_hi:[1,0]
	v_pk_add_f32 v[34:35], v[34:35], v[34:35] op_sel:[0,1] op_sel_hi:[1,0]
	v_add_f32_e32 v38, v40, v41
	v_add_f32_e32 v40, v42, v43
	v_mov_b32_e32 v39, v46
	v_mov_b32_e32 v41, v47
	v_mov_b32_e32 v33, v44
	v_mov_b32_e32 v35, v45
	v_pk_add_f32 v[36:37], v[38:39], v[40:41]
	v_pk_add_f32 v[32:33], v[32:33], v[34:35]
	v_lshl_add_u64 v[34:35], s[54:55], 0, v[50:51]
	v_pk_add_f32 v[32:33], v[32:33], v[36:37]
	v_lshl_add_u64 v[34:35], v[34:35], 0, v[112:113]
	v_add_f32_e32 v32, v32, v33
	v_fmamk_f32 v32, v32, 0x3a800000, v150
	v_rsq_f32_e32 v32, v32
	v_lshl_add_u64 v[36:37], s[58:59], 0, v[52:53]
	v_max_f32_e32 v38, v7, v7
	v_max_f32_e32 v39, v3, v3
	v_pk_mul_f32 v[16:17], v[16:17], v[32:33] op_sel_hi:[1,0]
	v_pk_mul_f32 v[18:19], v[18:19], v[32:33] op_sel_hi:[1,0]
	v_pk_mul_f32 v[20:21], v[20:21], v[32:33] op_sel_hi:[1,0]
	v_pk_mul_f32 v[22:23], v[22:23], v[32:33] op_sel_hi:[1,0]
	v_pk_mul_f32 v[24:25], v[24:25], v[32:33] op_sel_hi:[1,0]
	v_pk_mul_f32 v[26:27], v[26:27], v[32:33] op_sel_hi:[1,0]
	v_pk_mul_f32 v[28:29], v[28:29], v[32:33] op_sel_hi:[1,0]
	v_pk_mul_f32 v[30:31], v[30:31], v[32:33] op_sel_hi:[1,0]
	v_pk_mul_f32 v[16:17], v[16:17], v[16:17]
	v_pk_mul_f32 v[18:19], v[18:19], v[18:19]
	v_pk_mul_f32 v[20:21], v[20:21], v[20:21]
	v_pk_mul_f32 v[22:23], v[22:23], v[22:23]
	v_pk_mul_f32 v[24:25], v[24:25], v[24:25]
	v_pk_mul_f32 v[26:27], v[26:27], v[26:27]
	v_pk_mul_f32 v[28:29], v[28:29], v[28:29]
	v_pk_mul_f32 v[30:31], v[30:31], v[30:31]
	v_cvt_pk_bf16_f32 v16, v16, v17
	v_cvt_pk_bf16_f32 v17, v20, v21
	v_cvt_pk_bf16_f32 v18, v18, v19
	v_cvt_pk_bf16_f32 v19, v22, v23
	v_cvt_pk_bf16_f32 v20, v24, v25
	v_cvt_pk_bf16_f32 v21, v28, v29
	v_cvt_pk_bf16_f32 v22, v26, v27
	v_cvt_pk_bf16_f32 v23, v30, v31
	global_store_dwordx4 v[34:35], v[16:19], off
	global_store_dwordx4 v[34:35], v[20:23], off offset:256
	s_nop 0
	v_max_f32_e32 v36, v6, v6
	v_max_f32_e32 v37, v2, v2
	v_max_f32_e32 v2, 0, v8
	v_max_f32_e32 v6, 0, v10
	v_max_f32_e32 v8, 0, v4
	v_max_f32_e32 v10, 0, v0
	v_max_f32_e32 v34, v5, v5
	v_max_f32_e32 v35, v1, v1
	v_max_f32_e32 v0, 0, v12
	v_max_f32_e32 v1, 0, v13
	v_max_f32_e32 v3, 0, v9
	v_max_f32_e32 v4, 0, v14
	v_max_f32_e32 v5, 0, v15
	v_max_f32_e32 v7, 0, v11
	v_max_f32_e32 v9, 0, v34
	v_max_f32_e32 v11, 0, v35
	v_max_f32_e32 v12, 0, v36
	v_max_f32_e32 v14, 0, v37
	v_max_f32_e32 v13, 0, v38
	v_max_f32_e32 v15, 0, v39
	s_waitcnt vmcnt(4) lgkmcnt(0)
	v_mov_b32_e32 v16, v192
	v_mov_b32_e32 v17, v193
	v_mov_b32_e32 v18, v194
	v_mov_b32_e32 v19, v195
	v_mov_b32_e32 v20, v196
	v_mov_b32_e32 v21, v197
	v_mov_b32_e32 v22, v198
	v_mov_b32_e32 v23, v199
	v_mov_b32_e32 v24, v200
	v_mov_b32_e32 v25, v201
	v_mov_b32_e32 v26, v202
	v_mov_b32_e32 v27, v203
	v_mov_b32_e32 v28, v204
	v_mov_b32_e32 v29, v205
	v_mov_b32_e32 v30, v206
	v_mov_b32_e32 v31, v207
	v_mov_b32_e32 v32, v17
	v_mov_b32_e32 v33, v18
	v_mov_b32_e32 v17, v19
	v_mov_b32_e32 v18, v21
	v_mov_b32_e32 v19, v22
	v_mov_b32_e32 v21, v23
	v_pk_add_f32 v[16:17], v[32:33], v[16:17]
	v_pk_add_f32 v[18:19], v[18:19], v[20:21]
	v_pk_add_f32 v[16:17], v[16:17], v[16:17] op_sel:[0,1] op_sel_hi:[1,0]
	v_pk_add_f32 v[18:19], v[18:19], v[18:19] op_sel:[0,1] op_sel_hi:[1,0]
	v_add_f32_e32 v22, v24, v25
	v_add_f32_e32 v24, v26, v27
	v_mov_b32_e32 v23, v30
	v_mov_b32_e32 v25, v31
	v_mov_b32_e32 v17, v28
	v_mov_b32_e32 v19, v29
	v_pk_add_f32 v[20:21], v[22:23], v[24:25]
	v_pk_add_f32 v[16:17], v[16:17], v[18:19]
	v_lshlrev_b64 v[18:19], 13, v[48:49]
	v_pk_add_f32 v[16:17], v[16:17], v[20:21]
	v_lshl_add_u64 v[18:19], s[54:55], 0, v[18:19]
	v_add_f32_e32 v16, v16, v17
	v_fmamk_f32 v16, v16, 0x3a800000, v150
	v_rsq_f32_e32 v16, v16
	v_lshl_add_u64 v[18:19], v[18:19], 0, v[112:113]
	v_pk_mul_f32 v[0:1], v[0:1], v[16:17] op_sel_hi:[1,0]
	v_pk_mul_f32 v[2:3], v[2:3], v[16:17] op_sel_hi:[1,0]
	v_pk_mul_f32 v[4:5], v[4:5], v[16:17] op_sel_hi:[1,0]
	v_pk_mul_f32 v[6:7], v[6:7], v[16:17] op_sel_hi:[1,0]
	v_pk_mul_f32 v[8:9], v[8:9], v[16:17] op_sel_hi:[1,0]
	v_pk_mul_f32 v[10:11], v[10:11], v[16:17] op_sel_hi:[1,0]
	v_pk_mul_f32 v[12:13], v[12:13], v[16:17] op_sel_hi:[1,0]
	v_pk_mul_f32 v[14:15], v[14:15], v[16:17] op_sel_hi:[1,0]
	v_pk_mul_f32 v[0:1], v[0:1], v[0:1]
	v_pk_mul_f32 v[2:3], v[2:3], v[2:3]
	v_pk_mul_f32 v[4:5], v[4:5], v[4:5]
	v_pk_mul_f32 v[6:7], v[6:7], v[6:7]
	v_pk_mul_f32 v[8:9], v[8:9], v[8:9]
	v_pk_mul_f32 v[10:11], v[10:11], v[10:11]
	v_pk_mul_f32 v[12:13], v[12:13], v[12:13]
	v_pk_mul_f32 v[14:15], v[14:15], v[14:15]
	v_cvt_pk_bf16_f32 v0, v0, v1
	v_cvt_pk_bf16_f32 v1, v4, v5
	v_cvt_pk_bf16_f32 v2, v2, v3
	v_cvt_pk_bf16_f32 v3, v6, v7
	v_cvt_pk_bf16_f32 v4, v8, v9
	v_cvt_pk_bf16_f32 v5, v12, v13
	v_cvt_pk_bf16_f32 v6, v10, v11
	v_cvt_pk_bf16_f32 v7, v14, v15
	global_store_dwordx4 v[18:19], v[0:3], off
	global_store_dwordx4 v[18:19], v[4:7], off offset:256
	s_cbranch_vccnz .LBB0_1676
	v_mov_b32_e32 v0, 0
	s_andn2_b64 vcc, exec, s[6:7]
	s_cbranch_vccnz .LBB0_1675
	s_barrier
	s_branch .LBB0_1675

; DI u32x4 pack_v8(f32x4 v0, f32x4 v1) { u32x4 w; w.x = pk2(v0[0], v0[1]); w.y = pk2(v0[2], v0[3]); w.z = pk2(v1[0], v1[1]); w.w = pk2(v1[2], v1[3]); return w; }
; DI float rstd16(const float* ssq, int row) { const f32x4* p = (const f32x4*)(ssq + (size_t)row * 16); const f32x4 a = p[0], b = p[1], c = p[2], d = p[3];
;   return __builtin_amdgcn_rsqf((((a[0] + a[1]) + (a[2] + a[3])) + ((b[0] + b[1]) + (b[2] + b[3])) + ((c[0] + c[1]) + (c[2] + c[3])) + ((d[0] + d[1]) + (d[2] + d[3]))) * (1.0f / 1024.0f) + EPS); }
;   DI void operator()(AccRef acc, const Unit& u, int wr, int wc, int fr, int fq) const {
;     const int rowb = u.pm * 256 + wr * 64 + fr; const int cb = u.pn * 256 + wc * 32 + 8 * fq;
; #pragma unroll
;     for (int ai = 0; ai < 2; ++ai)
; #pragma unroll
;       for (int m = 0; m < 4; ++m) { const int row = rowb + ai * 128 + m * 16; const float rs = rstd16(SSQH, row);
; #pragma unroll
;         for (int bj = 0; bj < 2; ++bj) { f32x4 v0 = acc[ai][bj][m][0], v1 = acc[ai][bj][m][1];
; #pragma unroll
;           for (int j = 0; j < 4; ++j) { const float a = fmaxf(v0[j], 0.f) * rs, b = fmaxf(v1[j], 0.f) * rs; v0[j] = a * a; v1[j] = b * b; }
;           *(u32x4*)(A2 + (size_t)row * DFF + cb + bj * 128) = pack_v8(v0, v1); } }
;   }
.LBB0_3006:
	s_lshl_b32 s0, s24, 8
	v_mov_b32_e32 v151, v224
	s_add_i32 s0, s0, s42
	v_and_or_b32 v144, v151, 15, s0
	v_ashrrev_i32_e32 v145, 31, v144
	v_lshlrev_b64 v[152:153], 6, v[144:145]
	v_lshl_add_u64 v[164:165], s[56:57], 0, v[152:153]
	v_mov_b32_e32 v208, v164
	v_mov_b32_e32 v209, v165
	s_mov_b64 s[98:99], 0x2000
	v_lshl_add_u64 v[210:211], s[98:99], 0, v[164:165]
	global_load_dwordx4 v[152:155], v[164:165], off
	global_load_dwordx4 v[156:159], v[164:165], off offset:16
	global_load_dwordx4 v[160:163], v[164:165], off offset:32
	s_nop 0
	global_load_dwordx4 v[164:167], v[164:165], off offset:48
	global_load_dwordx4 v[192:195], v[208:209], off offset:1024
	global_load_dwordx4 v[196:199], v[208:209], off offset:1040
	global_load_dwordx4 v[200:203], v[208:209], off offset:1056
	global_load_dwordx4 v[204:207], v[208:209], off offset:1072
	v_max_f32_e32 v169, v117, v117
	v_max_f32_e32 v172, v119, v119
	v_max_f32_e32 v117, 0, v121
	v_max_f32_e32 v119, 0, v127
	v_max_f32_e32 v121, 0, v123
	v_max_f32_e32 v123, 0, v169
	v_max_f32_e32 v127, 0, v172
	v_max_f32_e32 v169, 0, v115
	v_lshlrev_b64 v[172:173], 13, v[144:145]
	s_lshl_b32 s0, s64, 8
	v_max_f32_e32 v171, v114, v114
	v_max_f32_e32 v114, 0, v124
	v_max_f32_e32 v124, 0, v112
	v_lshrrev_b32_e32 v112, 1, v151
	v_and_or_b32 v112, v112, 24, s0
	v_max_f32_e32 v168, v116, v116
	v_max_f32_e32 v170, v118, v118
	v_max_f32_e32 v116, 0, v120
	v_max_f32_e32 v115, 0, v125
	v_max_f32_e32 v118, 0, v126
	v_max_f32_e32 v120, 0, v122
	v_or_b32_e32 v112, s43, v112
	v_max_f32_e32 v122, 0, v168
	v_max_f32_e32 v125, 0, v113
	v_max_f32_e32 v126, 0, v170
	v_max_f32_e32 v168, 0, v171
	v_ashrrev_i32_e32 v113, 31, v112
	v_or_b32_e32 v170, 16, v144
	v_lshlrev_b64 v[112:113], 1, v[112:113]
	v_ashrrev_i32_e32 v171, 31, v170
	v_max_f32_e32 v151, v97, v97
	v_max_f32_e32 v97, 0, v109
	s_waitcnt vmcnt(4) lgkmcnt(0)
	global_load_dwordx4 v[176:179], v[208:209], off offset:2048
	global_load_dwordx4 v[180:183], v[208:209], off offset:2064
	global_load_dwordx4 v[184:187], v[208:209], off offset:2080
	global_load_dwordx4 v[188:191], v[208:209], off offset:2096
	v_mov_b32_e32 v174, v153
	v_mov_b32_e32 v175, v154
	v_mov_b32_e32 v153, v155
	v_mov_b32_e32 v154, v157
	v_mov_b32_e32 v155, v158
	v_mov_b32_e32 v157, v159
	v_pk_add_f32 v[152:153], v[174:175], v[152:153]
	v_pk_add_f32 v[154:155], v[154:155], v[156:157]
	v_pk_add_f32 v[152:153], v[152:153], v[152:153] op_sel:[0,1] op_sel_hi:[1,0]
	v_pk_add_f32 v[154:155], v[154:155], v[154:155] op_sel:[0,1] op_sel_hi:[1,0]
	v_add_f32_e32 v158, v160, v161
	v_add_f32_e32 v160, v162, v163
	v_mov_b32_e32 v159, v166
	v_mov_b32_e32 v161, v167
	v_mov_b32_e32 v153, v164
	v_mov_b32_e32 v155, v165
	v_pk_add_f32 v[156:157], v[158:159], v[160:161]
	v_pk_add_f32 v[152:153], v[152:153], v[154:155]
	v_lshl_add_u64 v[154:155], s[54:55], 0, v[172:173]
	v_pk_add_f32 v[152:153], v[152:153], v[156:157]
	v_lshl_add_u64 v[154:155], v[154:155], 0, v[112:113]
	v_add_f32_e32 v145, v152, v153
	v_fmamk_f32 v145, v145, 0x3a800000, v150
	v_rsq_f32_e32 v152, v145
	v_max_f32_e32 v145, v101, v101
	v_max_f32_e32 v156, v102, v102
	v_max_f32_e32 v157, v98, v98
	v_pk_mul_f32 v[114:115], v[114:115], v[152:153] op_sel_hi:[1,0]
	v_pk_mul_f32 v[116:117], v[116:117], v[152:153] op_sel_hi:[1,0]
	v_pk_mul_f32 v[118:119], v[118:119], v[152:153] op_sel_hi:[1,0]
	v_pk_mul_f32 v[120:121], v[120:121], v[152:153] op_sel_hi:[1,0]
	v_pk_mul_f32 v[122:123], v[122:123], v[152:153] op_sel_hi:[1,0]
	v_pk_mul_f32 v[124:125], v[124:125], v[152:153] op_sel_hi:[1,0]
	v_pk_mul_f32 v[126:127], v[126:127], v[152:153] op_sel_hi:[1,0]
	v_pk_mul_f32 v[152:153], v[168:169], v[152:153] op_sel_hi:[1,0]
	v_pk_mul_f32 v[114:115], v[114:115], v[114:115]
	v_pk_mul_f32 v[116:117], v[116:117], v[116:117]
	v_pk_mul_f32 v[118:119], v[118:119], v[118:119]
	v_pk_mul_f32 v[120:121], v[120:121], v[120:121]
	v_pk_mul_f32 v[122:123], v[122:123], v[122:123]
	v_pk_mul_f32 v[124:125], v[124:125], v[124:125]
	v_pk_mul_f32 v[126:127], v[126:127], v[126:127]
	v_pk_mul_f32 v[152:153], v[152:153], v[152:153]
	v_cvt_pk_bf16_f32 v114, v114, v115
	v_cvt_pk_bf16_f32 v115, v118, v119
	v_cvt_pk_bf16_f32 v116, v116, v117
	v_cvt_pk_bf16_f32 v117, v120, v121
	v_cvt_pk_bf16_f32 v118, v122, v123
	v_cvt_pk_bf16_f32 v119, v126, v127
	v_cvt_pk_bf16_f32 v120, v124, v125
	v_cvt_pk_bf16_f32 v121, v152, v153
	global_store_dwordx4 v[154:155], v[114:117], off
	global_store_dwordx4 v[154:155], v[118:121], off offset:256
	v_max_f32_e32 v158, v103, v103
	v_lshlrev_b64 v[114:115], 6, v[170:171]
	v_lshl_add_u64 v[126:127], s[56:57], 0, v[114:115]
	v_max_f32_e32 v126, v100, v100
	v_max_f32_e32 v127, v96, v96
	v_max_f32_e32 v159, v99, v99
	v_max_f32_e32 v96, 0, v108
	v_max_f32_e32 v98, 0, v104
	v_max_f32_e32 v99, 0, v105
	v_max_f32_e32 v100, 0, v110
	v_max_f32_e32 v102, 0, v106
	v_max_f32_e32 v101, 0, v111
	v_max_f32_e32 v103, 0, v107
	v_max_f32_e32 v104, 0, v126
	v_max_f32_e32 v106, 0, v127
	v_max_f32_e32 v105, 0, v145
	v_max_f32_e32 v107, 0, v151
	v_max_f32_e32 v108, 0, v156
	v_max_f32_e32 v110, 0, v157
	v_max_f32_e32 v109, 0, v158
	v_max_f32_e32 v111, 0, v159
	v_or_b32_e32 v126, 32, v144
	v_lshlrev_b64 v[156:157], 13, v[170:171]
	v_ashrrev_i32_e32 v127, 31, v126
	v_lshlrev_b64 v[158:159], 6, v[126:127]
	s_andn2_b64 vcc, exec, s[4:5]
	s_mov_b64 s[4:5], -1
	s_waitcnt vmcnt(6) lgkmcnt(0)
; DI u32x4 pack_v8(f32x4 v0, f32x4 v1) { u32x4 w; w.x = pk2(v0[0], v0[1]); w.y = pk2(v0[2], v0[3]); w.z = pk2(v1[0], v1[1]); w.w = pk2(v1[2], v1[3]); return w; }
; DI float rstd16(const float* ssq, int row) { const f32x4* p = (const f32x4*)(ssq + (size_t)row * 16); const f32x4 a = p[0], b = p[1], c = p[2], d = p[3];
;   return __builtin_amdgcn_rsqf((((a[0] + a[1]) + (a[2] + a[3])) + ((b[0] + b[1]) + (b[2] + b[3])) + ((c[0] + c[1]) + (c[2] + c[3])) + ((d[0] + d[1]) + (d[2] + d[3]))) * (1.0f / 1024.0f) + EPS); }
;   DI void operator()(AccRef acc, const Unit& u, int wr, int wc, int fr, int fq) const {
;     const int rowb = u.pm * 256 + wr * 64 + fr; const int cb = u.pn * 256 + wc * 32 + 8 * fq;
; #pragma unroll
;     for (int ai = 0; ai < 2; ++ai)
; #pragma unroll
;       for (int m = 0; m < 4; ++m) { const int row = rowb + ai * 128 + m * 16; const float rs = rstd16(SSQH, row);
; #pragma unroll
;         for (int bj = 0; bj < 2; ++bj) { f32x4 v0 = acc[ai][bj][m][0], v1 = acc[ai][bj][m][1];
; #pragma unroll
;           for (int j = 0; j < 4; ++j) { const float a = fmaxf(v0[j], 0.f) * rs, b = fmaxf(v1[j], 0.f) * rs; v0[j] = a * a; v1[j] = b * b; }
;           *(u32x4*)(A2 + (size_t)row * DFF + cb + bj * 128) = pack_v8(v0, v1); } }
;   }
	v_mov_b32_e32 v114, v192
	v_mov_b32_e32 v115, v193
	v_mov_b32_e32 v116, v194
	v_mov_b32_e32 v117, v195
	v_mov_b32_e32 v118, v196
	v_mov_b32_e32 v119, v197
	v_mov_b32_e32 v120, v198
	v_mov_b32_e32 v121, v199
	v_mov_b32_e32 v122, v200
	v_mov_b32_e32 v123, v201
	v_mov_b32_e32 v124, v202
	v_mov_b32_e32 v125, v203
	v_mov_b32_e32 v152, v204
	v_mov_b32_e32 v153, v205
	v_mov_b32_e32 v154, v206
	v_mov_b32_e32 v155, v207
	global_load_dwordx4 v[192:195], v[208:209], off offset:3072
	global_load_dwordx4 v[196:199], v[208:209], off offset:3088
	global_load_dwordx4 v[200:203], v[208:209], off offset:3104
	global_load_dwordx4 v[204:207], v[208:209], off offset:3120
	v_mov_b32_e32 v160, v115
	v_mov_b32_e32 v161, v116
	v_mov_b32_e32 v115, v117
	v_mov_b32_e32 v116, v119
	v_mov_b32_e32 v117, v120
	v_mov_b32_e32 v119, v121
	v_pk_add_f32 v[114:115], v[160:161], v[114:115]
	v_pk_add_f32 v[116:117], v[116:117], v[118:119]
	v_pk_add_f32 v[114:115], v[114:115], v[114:115] op_sel:[0,1] op_sel_hi:[1,0]
	v_pk_add_f32 v[116:117], v[116:117], v[116:117] op_sel:[0,1] op_sel_hi:[1,0]
	v_add_f32_e32 v120, v122, v123
	v_add_f32_e32 v122, v124, v125
	v_mov_b32_e32 v121, v154
	v_mov_b32_e32 v123, v155
	v_mov_b32_e32 v115, v152
	v_mov_b32_e32 v117, v153
	v_pk_add_f32 v[118:119], v[120:121], v[122:123]
	v_pk_add_f32 v[114:115], v[114:115], v[116:117]
	v_lshl_add_u64 v[116:117], s[54:55], 0, v[156:157]
	v_pk_add_f32 v[114:115], v[114:115], v[118:119]
	v_lshl_add_u64 v[116:117], v[116:117], 0, v[112:113]
	v_add_f32_e32 v114, v114, v115
	v_fmamk_f32 v114, v114, 0x3a800000, v150
	v_rsq_f32_e32 v114, v114
	v_lshl_add_u64 v[118:119], s[56:57], 0, v[158:159]
	v_pk_mul_f32 v[96:97], v[96:97], v[114:115] op_sel_hi:[1,0]
	v_pk_mul_f32 v[98:99], v[98:99], v[114:115] op_sel_hi:[1,0]
	v_pk_mul_f32 v[100:101], v[100:101], v[114:115] op_sel_hi:[1,0]
	v_pk_mul_f32 v[102:103], v[102:103], v[114:115] op_sel_hi:[1,0]
	v_pk_mul_f32 v[104:105], v[104:105], v[114:115] op_sel_hi:[1,0]
	v_pk_mul_f32 v[106:107], v[106:107], v[114:115] op_sel_hi:[1,0]
	v_pk_mul_f32 v[108:109], v[108:109], v[114:115] op_sel_hi:[1,0]
	v_pk_mul_f32 v[110:111], v[110:111], v[114:115] op_sel_hi:[1,0]
	v_pk_mul_f32 v[96:97], v[96:97], v[96:97]
	v_pk_mul_f32 v[98:99], v[98:99], v[98:99]
	v_pk_mul_f32 v[100:101], v[100:101], v[100:101]
	v_pk_mul_f32 v[102:103], v[102:103], v[102:103]
	v_pk_mul_f32 v[104:105], v[104:105], v[104:105]
	v_pk_mul_f32 v[106:107], v[106:107], v[106:107]
	v_pk_mul_f32 v[108:109], v[108:109], v[108:109]
	v_pk_mul_f32 v[110:111], v[110:111], v[110:111]
	v_cvt_pk_bf16_f32 v96, v96, v97
	v_cvt_pk_bf16_f32 v97, v100, v101
	v_cvt_pk_bf16_f32 v98, v98, v99
	v_cvt_pk_bf16_f32 v99, v102, v103
	v_cvt_pk_bf16_f32 v100, v104, v105
	v_cvt_pk_bf16_f32 v101, v108, v109
	v_cvt_pk_bf16_f32 v102, v106, v107
	v_cvt_pk_bf16_f32 v103, v110, v111
	global_store_dwordx4 v[116:117], v[96:99], off
	global_store_dwordx4 v[116:117], v[100:103], off offset:256
	s_nop 0
	v_max_f32_e32 v116, v85, v85
	v_max_f32_e32 v117, v81, v81
	v_max_f32_e32 v81, 0, v93
	v_max_f32_e32 v85, 0, v95
	v_max_f32_e32 v93, 0, v87
	v_max_f32_e32 v95, 0, v83
	v_max_f32_e32 v114, v84, v84
	v_max_f32_e32 v115, v80, v80
	v_max_f32_e32 v118, v86, v86
	v_max_f32_e32 v119, v82, v82
	v_max_f32_e32 v80, 0, v92
	v_max_f32_e32 v82, 0, v88
	v_max_f32_e32 v83, 0, v89
	v_max_f32_e32 v84, 0, v94
	v_max_f32_e32 v86, 0, v90
	v_max_f32_e32 v87, 0, v91
	v_max_f32_e32 v88, 0, v114
	v_max_f32_e32 v90, 0, v115
	v_max_f32_e32 v89, 0, v116
	v_max_f32_e32 v91, 0, v117
	v_max_f32_e32 v92, 0, v118
	v_max_f32_e32 v94, 0, v119
	v_or_b32_e32 v114, 48, v144
	v_lshlrev_b64 v[116:117], 13, v[126:127]
	v_ashrrev_i32_e32 v115, 31, v114
	v_lshlrev_b64 v[118:119], 6, v[114:115]
	s_waitcnt vmcnt(8) lgkmcnt(0)
	v_mov_b32_e32 v96, v176
	v_mov_b32_e32 v97, v177
	v_mov_b32_e32 v98, v178
	v_mov_b32_e32 v99, v179
	v_mov_b32_e32 v100, v180
	v_mov_b32_e32 v101, v181
	v_mov_b32_e32 v102, v182
	v_mov_b32_e32 v103, v183
	v_mov_b32_e32 v104, v184
	v_mov_b32_e32 v105, v185
	v_mov_b32_e32 v106, v186
	v_mov_b32_e32 v107, v187
	v_mov_b32_e32 v108, v188
	v_mov_b32_e32 v109, v189
	v_mov_b32_e32 v110, v190
	v_mov_b32_e32 v111, v191
	global_load_dwordx4 v[176:179], v[210:211], off offset:0
	global_load_dwordx4 v[180:183], v[210:211], off offset:16
	global_load_dwordx4 v[184:187], v[210:211], off offset:32
	global_load_dwordx4 v[188:191], v[210:211], off offset:48
	v_mov_b32_e32 v120, v97
	v_mov_b32_e32 v121, v98
	v_mov_b32_e32 v97, v99
	v_mov_b32_e32 v98, v101
	v_mov_b32_e32 v99, v102
	v_mov_b32_e32 v101, v103
	v_pk_add_f32 v[96:97], v[120:121], v[96:97]
	v_pk_add_f32 v[98:99], v[98:99], v[100:101]
	v_pk_add_f32 v[96:97], v[96:97], v[96:97] op_sel:[0,1] op_sel_hi:[1,0]
	v_pk_add_f32 v[98:99], v[98:99], v[98:99] op_sel:[0,1] op_sel_hi:[1,0]
	v_add_f32_e32 v102, v104, v105
	v_add_f32_e32 v104, v106, v107
	v_mov_b32_e32 v103, v110
	v_mov_b32_e32 v105, v111
	v_mov_b32_e32 v97, v108
	v_mov_b32_e32 v99, v109
	v_pk_add_f32 v[100:101], v[102:103], v[104:105]
	v_pk_add_f32 v[96:97], v[96:97], v[98:99]
	v_lshl_add_u64 v[98:99], s[54:55], 0, v[116:117]
	v_pk_add_f32 v[96:97], v[96:97], v[100:101]
	v_lshl_add_u64 v[98:99], v[98:99], 0, v[112:113]
	v_add_f32_e32 v96, v96, v97
	v_fmamk_f32 v96, v96, 0x3a800000, v150
	v_rsq_f32_e32 v96, v96
	v_lshl_add_u64 v[100:101], s[56:57], 0, v[118:119]
	v_pk_mul_f32 v[80:81], v[80:81], v[96:97] op_sel_hi:[1,0]
	v_pk_mul_f32 v[82:83], v[82:83], v[96:97] op_sel_hi:[1,0]
	v_pk_mul_f32 v[84:85], v[84:85], v[96:97] op_sel_hi:[1,0]
	v_pk_mul_f32 v[86:87], v[86:87], v[96:97] op_sel_hi:[1,0]
	v_pk_mul_f32 v[88:89], v[88:89], v[96:97] op_sel_hi:[1,0]
	v_pk_mul_f32 v[90:91], v[90:91], v[96:97] op_sel_hi:[1,0]
; DI u32x4 pack_v8(f32x4 v0, f32x4 v1) { u32x4 w; w.x = pk2(v0[0], v0[1]); w.y = pk2(v0[2], v0[3]); w.z = pk2(v1[0], v1[1]); w.w = pk2(v1[2], v1[3]); return w; }
; DI float rstd16(const float* ssq, int row) { const f32x4* p = (const f32x4*)(ssq + (size_t)row * 16); const f32x4 a = p[0], b = p[1], c = p[2], d = p[3];
;   return __builtin_amdgcn_rsqf((((a[0] + a[1]) + (a[2] + a[3])) + ((b[0] + b[1]) + (b[2] + b[3])) + ((c[0] + c[1]) + (c[2] + c[3])) + ((d[0] + d[1]) + (d[2] + d[3]))) * (1.0f / 1024.0f) + EPS); }
;   DI void operator()(AccRef acc, const Unit& u, int wr, int wc, int fr, int fq) const {
;     const int rowb = u.pm * 256 + wr * 64 + fr; const int cb = u.pn * 256 + wc * 32 + 8 * fq;
; #pragma unroll
;     for (int ai = 0; ai < 2; ++ai)
; #pragma unroll
;       for (int m = 0; m < 4; ++m) { const int row = rowb + ai * 128 + m * 16; const float rs = rstd16(SSQH, row);
; #pragma unroll
;         for (int bj = 0; bj < 2; ++bj) { f32x4 v0 = acc[ai][bj][m][0], v1 = acc[ai][bj][m][1];
; #pragma unroll
;           for (int j = 0; j < 4; ++j) { const float a = fmaxf(v0[j], 0.f) * rs, b = fmaxf(v1[j], 0.f) * rs; v0[j] = a * a; v1[j] = b * b; }
;           *(u32x4*)(A2 + (size_t)row * DFF + cb + bj * 128) = pack_v8(v0, v1); } }
;   }
	v_pk_mul_f32 v[92:93], v[92:93], v[96:97] op_sel_hi:[1,0]
	v_pk_mul_f32 v[94:95], v[94:95], v[96:97] op_sel_hi:[1,0]
	v_pk_mul_f32 v[80:81], v[80:81], v[80:81]
	v_pk_mul_f32 v[82:83], v[82:83], v[82:83]
	v_pk_mul_f32 v[84:85], v[84:85], v[84:85]
	v_pk_mul_f32 v[86:87], v[86:87], v[86:87]
	v_pk_mul_f32 v[88:89], v[88:89], v[88:89]
	v_pk_mul_f32 v[90:91], v[90:91], v[90:91]
	v_pk_mul_f32 v[92:93], v[92:93], v[92:93]
	v_pk_mul_f32 v[94:95], v[94:95], v[94:95]
	v_cvt_pk_bf16_f32 v80, v80, v81
	v_cvt_pk_bf16_f32 v81, v84, v85
	v_cvt_pk_bf16_f32 v82, v82, v83
	v_cvt_pk_bf16_f32 v83, v86, v87
	v_cvt_pk_bf16_f32 v84, v88, v89
	v_cvt_pk_bf16_f32 v85, v92, v93
	v_cvt_pk_bf16_f32 v86, v90, v91
	v_cvt_pk_bf16_f32 v87, v94, v95
	global_store_dwordx4 v[98:99], v[80:83], off
	global_store_dwordx4 v[98:99], v[84:87], off offset:256
	s_nop 0
	v_max_f32_e32 v98, v69, v69
	v_max_f32_e32 v99, v65, v65
	v_max_f32_e32 v65, 0, v77
	v_max_f32_e32 v69, 0, v79
	v_max_f32_e32 v77, 0, v71
	v_max_f32_e32 v79, 0, v67
	v_max_f32_e32 v96, v68, v68
	v_max_f32_e32 v97, v64, v64
	v_max_f32_e32 v100, v70, v70
	v_max_f32_e32 v101, v66, v66
	v_max_f32_e32 v64, 0, v76
	v_max_f32_e32 v66, 0, v72
	v_max_f32_e32 v67, 0, v73
	v_max_f32_e32 v68, 0, v78
	v_max_f32_e32 v70, 0, v74
	v_max_f32_e32 v71, 0, v75
	v_max_f32_e32 v72, 0, v96
	v_max_f32_e32 v74, 0, v97
	v_max_f32_e32 v73, 0, v98
	v_max_f32_e32 v75, 0, v99
	v_max_f32_e32 v76, 0, v100
	v_max_f32_e32 v78, 0, v101
	v_add_u32_e32 v96, 0x80, v144
	v_lshlrev_b64 v[98:99], 13, v[114:115]
	v_ashrrev_i32_e32 v97, 31, v96
	v_lshlrev_b64 v[100:101], 6, v[96:97]
	s_waitcnt vmcnt(8) lgkmcnt(0)
	v_mov_b32_e32 v80, v192
	v_mov_b32_e32 v81, v193
	v_mov_b32_e32 v82, v194
	v_mov_b32_e32 v83, v195
	v_mov_b32_e32 v84, v196
	v_mov_b32_e32 v85, v197
	v_mov_b32_e32 v86, v198
	v_mov_b32_e32 v87, v199
	v_mov_b32_e32 v88, v200
	v_mov_b32_e32 v89, v201
	v_mov_b32_e32 v90, v202
	v_mov_b32_e32 v91, v203
	v_mov_b32_e32 v92, v204
	v_mov_b32_e32 v93, v205
	v_mov_b32_e32 v94, v206
	v_mov_b32_e32 v95, v207
	global_load_dwordx4 v[192:195], v[210:211], off offset:1024
	global_load_dwordx4 v[196:199], v[210:211], off offset:1040
	global_load_dwordx4 v[200:203], v[210:211], off offset:1056
	global_load_dwordx4 v[204:207], v[210:211], off offset:1072
	v_mov_b32_e32 v102, v81
	v_mov_b32_e32 v103, v82
	v_mov_b32_e32 v81, v83
	v_mov_b32_e32 v82, v85
	v_mov_b32_e32 v83, v86
	v_mov_b32_e32 v85, v87
	v_pk_add_f32 v[80:81], v[102:103], v[80:81]
	v_pk_add_f32 v[82:83], v[82:83], v[84:85]
	v_pk_add_f32 v[80:81], v[80:81], v[80:81] op_sel:[0,1] op_sel_hi:[1,0]
	v_pk_add_f32 v[82:83], v[82:83], v[82:83] op_sel:[0,1] op_sel_hi:[1,0]
	v_add_f32_e32 v86, v88, v89
	v_add_f32_e32 v88, v90, v91
	v_mov_b32_e32 v87, v94
	v_mov_b32_e32 v89, v95
	v_mov_b32_e32 v81, v92
	v_mov_b32_e32 v83, v93
	v_pk_add_f32 v[84:85], v[86:87], v[88:89]
	v_pk_add_f32 v[80:81], v[80:81], v[82:83]
	v_lshl_add_u64 v[82:83], s[54:55], 0, v[98:99]
	v_pk_add_f32 v[80:81], v[80:81], v[84:85]
	v_lshl_add_u64 v[82:83], v[82:83], 0, v[112:113]
	v_add_f32_e32 v80, v80, v81
	v_fmamk_f32 v80, v80, 0x3a800000, v150
	v_rsq_f32_e32 v80, v80
	v_lshl_add_u64 v[84:85], s[56:57], 0, v[100:101]
	v_pk_mul_f32 v[64:65], v[64:65], v[80:81] op_sel_hi:[1,0]
	v_pk_mul_f32 v[66:67], v[66:67], v[80:81] op_sel_hi:[1,0]
	v_pk_mul_f32 v[68:69], v[68:69], v[80:81] op_sel_hi:[1,0]
	v_pk_mul_f32 v[70:71], v[70:71], v[80:81] op_sel_hi:[1,0]
	v_pk_mul_f32 v[72:73], v[72:73], v[80:81] op_sel_hi:[1,0]
	v_pk_mul_f32 v[74:75], v[74:75], v[80:81] op_sel_hi:[1,0]
	v_pk_mul_f32 v[76:77], v[76:77], v[80:81] op_sel_hi:[1,0]
	v_pk_mul_f32 v[78:79], v[78:79], v[80:81] op_sel_hi:[1,0]
	v_pk_mul_f32 v[64:65], v[64:65], v[64:65]
	v_pk_mul_f32 v[66:67], v[66:67], v[66:67]
	v_pk_mul_f32 v[68:69], v[68:69], v[68:69]
	v_pk_mul_f32 v[70:71], v[70:71], v[70:71]
	v_pk_mul_f32 v[72:73], v[72:73], v[72:73]
	v_pk_mul_f32 v[74:75], v[74:75], v[74:75]
	v_pk_mul_f32 v[76:77], v[76:77], v[76:77]
	v_pk_mul_f32 v[78:79], v[78:79], v[78:79]
	v_cvt_pk_bf16_f32 v64, v64, v65
	v_cvt_pk_bf16_f32 v65, v68, v69
	v_cvt_pk_bf16_f32 v66, v66, v67
	v_cvt_pk_bf16_f32 v67, v70, v71
	v_cvt_pk_bf16_f32 v68, v72, v73
	v_cvt_pk_bf16_f32 v69, v76, v77
	v_cvt_pk_bf16_f32 v70, v74, v75
	v_cvt_pk_bf16_f32 v71, v78, v79
	global_store_dwordx4 v[82:83], v[64:67], off
	global_store_dwordx4 v[82:83], v[68:71], off offset:256
	s_nop 0
	v_max_f32_e32 v82, v53, v53
	v_max_f32_e32 v83, v49, v49
	v_max_f32_e32 v49, 0, v61
	v_max_f32_e32 v53, 0, v63
	v_max_f32_e32 v61, 0, v55
	v_max_f32_e32 v63, 0, v51
	v_max_f32_e32 v80, v52, v52
	v_max_f32_e32 v81, v48, v48
	v_max_f32_e32 v84, v54, v54
	v_max_f32_e32 v85, v50, v50
	v_max_f32_e32 v48, 0, v60
	v_max_f32_e32 v50, 0, v56
	v_max_f32_e32 v51, 0, v57
	v_max_f32_e32 v52, 0, v62
	v_max_f32_e32 v54, 0, v58
	v_max_f32_e32 v55, 0, v59
	v_max_f32_e32 v56, 0, v80
	v_max_f32_e32 v58, 0, v81
	v_max_f32_e32 v57, 0, v82
	v_max_f32_e32 v59, 0, v83
	v_max_f32_e32 v60, 0, v84
	v_max_f32_e32 v62, 0, v85
	v_add_u32_e32 v80, 0x90, v144
	v_lshlrev_b64 v[82:83], 13, v[96:97]
	v_ashrrev_i32_e32 v81, 31, v80
	v_lshlrev_b64 v[84:85], 6, v[80:81]
	s_waitcnt vmcnt(8) lgkmcnt(0)
; DI u32x4 pack_v8(f32x4 v0, f32x4 v1) { u32x4 w; w.x = pk2(v0[0], v0[1]); w.y = pk2(v0[2], v0[3]); w.z = pk2(v1[0], v1[1]); w.w = pk2(v1[2], v1[3]); return w; }
; DI float rstd16(const float* ssq, int row) { const f32x4* p = (const f32x4*)(ssq + (size_t)row * 16); const f32x4 a = p[0], b = p[1], c = p[2], d = p[3];
;   return __builtin_amdgcn_rsqf((((a[0] + a[1]) + (a[2] + a[3])) + ((b[0] + b[1]) + (b[2] + b[3])) + ((c[0] + c[1]) + (c[2] + c[3])) + ((d[0] + d[1]) + (d[2] + d[3]))) * (1.0f / 1024.0f) + EPS); }
;   DI void operator()(AccRef acc, const Unit& u, int wr, int wc, int fr, int fq) const {
;     const int rowb = u.pm * 256 + wr * 64 + fr; const int cb = u.pn * 256 + wc * 32 + 8 * fq;
; #pragma unroll
;     for (int ai = 0; ai < 2; ++ai)
; #pragma unroll
;       for (int m = 0; m < 4; ++m) { const int row = rowb + ai * 128 + m * 16; const float rs = rstd16(SSQH, row);
; #pragma unroll
;         for (int bj = 0; bj < 2; ++bj) { f32x4 v0 = acc[ai][bj][m][0], v1 = acc[ai][bj][m][1];
; #pragma unroll
;           for (int j = 0; j < 4; ++j) { const float a = fmaxf(v0[j], 0.f) * rs, b = fmaxf(v1[j], 0.f) * rs; v0[j] = a * a; v1[j] = b * b; }
;           *(u32x4*)(A2 + (size_t)row * DFF + cb + bj * 128) = pack_v8(v0, v1); } }
;   }
	v_mov_b32_e32 v64, v176
	v_mov_b32_e32 v65, v177
	v_mov_b32_e32 v66, v178
	v_mov_b32_e32 v67, v179
	v_mov_b32_e32 v68, v180
	v_mov_b32_e32 v69, v181
	v_mov_b32_e32 v70, v182
	v_mov_b32_e32 v71, v183
	v_mov_b32_e32 v72, v184
	v_mov_b32_e32 v73, v185
	v_mov_b32_e32 v74, v186
	v_mov_b32_e32 v75, v187
	v_mov_b32_e32 v76, v188
	v_mov_b32_e32 v77, v189
	v_mov_b32_e32 v78, v190
	v_mov_b32_e32 v79, v191
	global_load_dwordx4 v[176:179], v[210:211], off offset:2048
	global_load_dwordx4 v[180:183], v[210:211], off offset:2064
	global_load_dwordx4 v[184:187], v[210:211], off offset:2080
	global_load_dwordx4 v[188:191], v[210:211], off offset:2096
	v_mov_b32_e32 v86, v65
	v_mov_b32_e32 v87, v66
	v_mov_b32_e32 v65, v67
	v_mov_b32_e32 v66, v69
	v_mov_b32_e32 v67, v70
	v_mov_b32_e32 v69, v71
	v_pk_add_f32 v[64:65], v[86:87], v[64:65]
	v_pk_add_f32 v[66:67], v[66:67], v[68:69]
	v_pk_add_f32 v[64:65], v[64:65], v[64:65] op_sel:[0,1] op_sel_hi:[1,0]
	v_pk_add_f32 v[66:67], v[66:67], v[66:67] op_sel:[0,1] op_sel_hi:[1,0]
	v_add_f32_e32 v70, v72, v73
	v_add_f32_e32 v72, v74, v75
	v_mov_b32_e32 v71, v78
	v_mov_b32_e32 v73, v79
	v_mov_b32_e32 v65, v76
	v_mov_b32_e32 v67, v77
	v_pk_add_f32 v[68:69], v[70:71], v[72:73]
	v_pk_add_f32 v[64:65], v[64:65], v[66:67]
	v_lshl_add_u64 v[66:67], s[54:55], 0, v[82:83]
	v_pk_add_f32 v[64:65], v[64:65], v[68:69]
	v_lshl_add_u64 v[66:67], v[66:67], 0, v[112:113]
	v_add_f32_e32 v64, v64, v65
	v_fmamk_f32 v64, v64, 0x3a800000, v150
	v_rsq_f32_e32 v64, v64
	v_lshl_add_u64 v[68:69], s[56:57], 0, v[84:85]
	v_pk_mul_f32 v[48:49], v[48:49], v[64:65] op_sel_hi:[1,0]
	v_pk_mul_f32 v[50:51], v[50:51], v[64:65] op_sel_hi:[1,0]
	v_pk_mul_f32 v[52:53], v[52:53], v[64:65] op_sel_hi:[1,0]
	v_pk_mul_f32 v[54:55], v[54:55], v[64:65] op_sel_hi:[1,0]
	v_pk_mul_f32 v[56:57], v[56:57], v[64:65] op_sel_hi:[1,0]
	v_pk_mul_f32 v[58:59], v[58:59], v[64:65] op_sel_hi:[1,0]
	v_pk_mul_f32 v[60:61], v[60:61], v[64:65] op_sel_hi:[1,0]
	v_pk_mul_f32 v[62:63], v[62:63], v[64:65] op_sel_hi:[1,0]
	v_pk_mul_f32 v[48:49], v[48:49], v[48:49]
	v_pk_mul_f32 v[50:51], v[50:51], v[50:51]
	v_pk_mul_f32 v[52:53], v[52:53], v[52:53]
	v_pk_mul_f32 v[54:55], v[54:55], v[54:55]
	v_pk_mul_f32 v[56:57], v[56:57], v[56:57]
	v_pk_mul_f32 v[58:59], v[58:59], v[58:59]
	v_pk_mul_f32 v[60:61], v[60:61], v[60:61]
	v_pk_mul_f32 v[62:63], v[62:63], v[62:63]
	v_cvt_pk_bf16_f32 v48, v48, v49
	v_cvt_pk_bf16_f32 v49, v52, v53
	v_cvt_pk_bf16_f32 v50, v50, v51
	v_cvt_pk_bf16_f32 v51, v54, v55
	v_cvt_pk_bf16_f32 v52, v56, v57
	v_cvt_pk_bf16_f32 v53, v60, v61
	v_cvt_pk_bf16_f32 v54, v58, v59
	v_cvt_pk_bf16_f32 v55, v62, v63
	global_store_dwordx4 v[66:67], v[48:51], off
	global_store_dwordx4 v[66:67], v[52:55], off offset:256
	s_nop 0
	v_max_f32_e32 v66, v37, v37
	v_max_f32_e32 v67, v33, v33
	v_max_f32_e32 v33, 0, v45
	v_max_f32_e32 v37, 0, v47
	v_max_f32_e32 v45, 0, v39
	v_max_f32_e32 v47, 0, v35
	v_max_f32_e32 v64, v36, v36
	v_max_f32_e32 v65, v32, v32
	v_max_f32_e32 v68, v38, v38
	v_max_f32_e32 v69, v34, v34
	v_max_f32_e32 v32, 0, v44
	v_max_f32_e32 v34, 0, v40
	v_max_f32_e32 v35, 0, v41
	v_max_f32_e32 v36, 0, v46
	v_max_f32_e32 v38, 0, v42
	v_max_f32_e32 v39, 0, v43
	v_max_f32_e32 v40, 0, v64
	v_max_f32_e32 v42, 0, v65
	v_max_f32_e32 v41, 0, v66
	v_max_f32_e32 v43, 0, v67
	v_max_f32_e32 v44, 0, v68
	v_max_f32_e32 v46, 0, v69
	v_add_u32_e32 v64, 0xa0, v144
	v_lshlrev_b64 v[66:67], 13, v[80:81]
	v_ashrrev_i32_e32 v65, 31, v64
	v_lshlrev_b64 v[68:69], 6, v[64:65]
	s_waitcnt vmcnt(8) lgkmcnt(0)
	v_mov_b32_e32 v48, v192
	v_mov_b32_e32 v49, v193
	v_mov_b32_e32 v50, v194
	v_mov_b32_e32 v51, v195
	v_mov_b32_e32 v52, v196
	v_mov_b32_e32 v53, v197
	v_mov_b32_e32 v54, v198
	v_mov_b32_e32 v55, v199
	v_mov_b32_e32 v56, v200
	v_mov_b32_e32 v57, v201
	v_mov_b32_e32 v58, v202
	v_mov_b32_e32 v59, v203
	v_mov_b32_e32 v60, v204
	v_mov_b32_e32 v61, v205
	v_mov_b32_e32 v62, v206
	v_mov_b32_e32 v63, v207
	global_load_dwordx4 v[192:195], v[210:211], off offset:3072
	global_load_dwordx4 v[196:199], v[210:211], off offset:3088
	global_load_dwordx4 v[200:203], v[210:211], off offset:3104
	global_load_dwordx4 v[204:207], v[210:211], off offset:3120
	v_mov_b32_e32 v70, v49
	v_mov_b32_e32 v71, v50
	v_mov_b32_e32 v49, v51
	v_mov_b32_e32 v50, v53
	v_mov_b32_e32 v51, v54
	v_mov_b32_e32 v53, v55
	v_pk_add_f32 v[48:49], v[70:71], v[48:49]
	v_pk_add_f32 v[50:51], v[50:51], v[52:53]
	v_pk_add_f32 v[48:49], v[48:49], v[48:49] op_sel:[0,1] op_sel_hi:[1,0]
	v_pk_add_f32 v[50:51], v[50:51], v[50:51] op_sel:[0,1] op_sel_hi:[1,0]
	v_add_f32_e32 v54, v56, v57
	v_add_f32_e32 v56, v58, v59
	v_mov_b32_e32 v55, v62
	v_mov_b32_e32 v57, v63
	v_mov_b32_e32 v49, v60
	v_mov_b32_e32 v51, v61
	v_pk_add_f32 v[52:53], v[54:55], v[56:57]
	v_pk_add_f32 v[48:49], v[48:49], v[50:51]
	v_lshl_add_u64 v[50:51], s[54:55], 0, v[66:67]
	v_pk_add_f32 v[48:49], v[48:49], v[52:53]
	v_lshl_add_u64 v[50:51], v[50:51], 0, v[112:113]
	v_add_f32_e32 v48, v48, v49
	v_fmamk_f32 v48, v48, 0x3a800000, v150
	v_rsq_f32_e32 v48, v48
	v_lshl_add_u64 v[52:53], s[56:57], 0, v[68:69]
	v_pk_mul_f32 v[32:33], v[32:33], v[48:49] op_sel_hi:[1,0]
	v_pk_mul_f32 v[34:35], v[34:35], v[48:49] op_sel_hi:[1,0]
	v_pk_mul_f32 v[36:37], v[36:37], v[48:49] op_sel_hi:[1,0]
	v_pk_mul_f32 v[38:39], v[38:39], v[48:49] op_sel_hi:[1,0]
	v_pk_mul_f32 v[40:41], v[40:41], v[48:49] op_sel_hi:[1,0]
	v_pk_mul_f32 v[42:43], v[42:43], v[48:49] op_sel_hi:[1,0]
	v_pk_mul_f32 v[44:45], v[44:45], v[48:49] op_sel_hi:[1,0]
	v_pk_mul_f32 v[46:47], v[46:47], v[48:49] op_sel_hi:[1,0]
	v_pk_mul_f32 v[32:33], v[32:33], v[32:33]
	v_pk_mul_f32 v[34:35], v[34:35], v[34:35]
	v_pk_mul_f32 v[36:37], v[36:37], v[36:37]
	v_pk_mul_f32 v[38:39], v[38:39], v[38:39]
	v_pk_mul_f32 v[40:41], v[40:41], v[40:41]
	v_pk_mul_f32 v[42:43], v[42:43], v[42:43]
	v_pk_mul_f32 v[44:45], v[44:45], v[44:45]
	v_pk_mul_f32 v[46:47], v[46:47], v[46:47]
	v_cvt_pk_bf16_f32 v32, v32, v33
	v_cvt_pk_bf16_f32 v33, v36, v37
	v_cvt_pk_bf16_f32 v34, v34, v35
	v_cvt_pk_bf16_f32 v35, v38, v39
	v_cvt_pk_bf16_f32 v36, v40, v41
	v_cvt_pk_bf16_f32 v37, v44, v45
	v_cvt_pk_bf16_f32 v38, v42, v43
	v_cvt_pk_bf16_f32 v39, v46, v47
	global_store_dwordx4 v[50:51], v[32:35], off
	global_store_dwordx4 v[50:51], v[36:39], off offset:256
	s_nop 0
	v_max_f32_e32 v50, v21, v21
	v_max_f32_e32 v51, v17, v17
	v_max_f32_e32 v17, 0, v29
	v_max_f32_e32 v21, 0, v31
	v_max_f32_e32 v29, 0, v23
	v_max_f32_e32 v31, 0, v19
	v_max_f32_e32 v48, v20, v20
	v_max_f32_e32 v49, v16, v16
	v_max_f32_e32 v52, v22, v22
	v_max_f32_e32 v53, v18, v18
	v_max_f32_e32 v16, 0, v28
	v_max_f32_e32 v18, 0, v24
	v_max_f32_e32 v19, 0, v25
	v_max_f32_e32 v20, 0, v30
	v_max_f32_e32 v22, 0, v26
	v_max_f32_e32 v23, 0, v27
	v_max_f32_e32 v24, 0, v48
	v_max_f32_e32 v26, 0, v49
	v_max_f32_e32 v25, 0, v50
	v_max_f32_e32 v27, 0, v51
	v_max_f32_e32 v28, 0, v52
	v_max_f32_e32 v30, 0, v53
	v_add_u32_e32 v48, 0xb0, v144
	v_lshlrev_b64 v[50:51], 13, v[64:65]
	v_ashrrev_i32_e32 v49, 31, v48
	v_lshlrev_b64 v[52:53], 6, v[48:49]
	s_waitcnt vmcnt(8) lgkmcnt(0)
; DI float ozero() { float z = 0.f; asm volatile("" : "+v"(z)); return z; }
; DI int otid() { int t = threadIdx.x; asm volatile("" : "+v"(t)); return t; }
; #define PG8_BAR __builtin_amdgcn_s_barrier()
; DI u32x4 pack_v8(f32x4 v0, f32x4 v1) { u32x4 w; w.x = pk2(v0[0], v0[1]); w.y = pk2(v0[2], v0[3]); w.z = pk2(v1[0], v1[1]); w.w = pk2(v1[2], v1[3]); return w; }
; template <class Epi, class Sched>
; DI void gemm_phase(LAS unsigned char* lds, const Gemm g, const Sched& S, const Epi& E) {
;     ...
;     if (wr == 0) PG8_BAR;
;     { const int l2 = otid() & 63; E(acc, cur, wr, wc, l2 & 15, l2 >> 4); }
;     if (!has_next) break;
;     { const float z0 = ozero();
; #pragma unroll
;     for (int a = 0; a < 2; ++a)
; #pragma unroll
;       for (int b = 0; b < 2; ++b)
; #pragma unroll
;         for (int m = 0; m < 4; ++m)
; #pragma unroll
;           for (int n = 0; n < 2; ++n) acc[a][b][m][n] = (f32x4){z0, z0, z0, z0}; }
;     cur = nxt; cA = nA; cB = nB; ++ui;
;     if (wr == 1) PG8_BAR;
; DI float rstd16(const float* ssq, int row) { const f32x4* p = (const f32x4*)(ssq + (size_t)row * 16); const f32x4 a = p[0], b = p[1], c = p[2], d = p[3];
;   return __builtin_amdgcn_rsqf((((a[0] + a[1]) + (a[2] + a[3])) + ((b[0] + b[1]) + (b[2] + b[3])) + ((c[0] + c[1]) + (c[2] + c[3])) + ((d[0] + d[1]) + (d[2] + d[3]))) * (1.0f / 1024.0f) + EPS); }
;   DI void operator()(AccRef acc, const Unit& u, int wr, int wc, int fr, int fq) const {
;     const int rowb = u.pm * 256 + wr * 64 + fr; const int cb = u.pn * 256 + wc * 32 + 8 * fq;
; #pragma unroll
;     for (int ai = 0; ai < 2; ++ai)
; #pragma unroll
;       for (int m = 0; m < 4; ++m) { const int row = rowb + ai * 128 + m * 16; const float rs = rstd16(SSQH, row);
; #pragma unroll
;         for (int bj = 0; bj < 2; ++bj) { f32x4 v0 = acc[ai][bj][m][0], v1 = acc[ai][bj][m][1];
; #pragma unroll
;           for (int j = 0; j < 4; ++j) { const float a = fmaxf(v0[j], 0.f) * rs, b = fmaxf(v1[j], 0.f) * rs; v0[j] = a * a; v1[j] = b * b; }
;           *(u32x4*)(A2 + (size_t)row * DFF + cb + bj * 128) = pack_v8(v0, v1); } }
;   }
	v_mov_b32_e32 v32, v176
	v_mov_b32_e32 v33, v177
	v_mov_b32_e32 v34, v178
	v_mov_b32_e32 v35, v179
	v_mov_b32_e32 v36, v180
	v_mov_b32_e32 v37, v181
	v_mov_b32_e32 v38, v182
	v_mov_b32_e32 v39, v183
	v_mov_b32_e32 v40, v184
	v_mov_b32_e32 v41, v185
	v_mov_b32_e32 v42, v186
	v_mov_b32_e32 v43, v187
	v_mov_b32_e32 v44, v188
	v_mov_b32_e32 v45, v189
	v_mov_b32_e32 v46, v190
	v_mov_b32_e32 v47, v191
	v_mov_b32_e32 v54, v33
	v_mov_b32_e32 v55, v34
	v_mov_b32_e32 v33, v35
	v_mov_b32_e32 v34, v37
	v_mov_b32_e32 v35, v38
	v_mov_b32_e32 v37, v39
	v_pk_add_f32 v[32:33], v[54:55], v[32:33]
	v_pk_add_f32 v[34:35], v[34:35], v[36:37]
	v_pk_add_f32 v[32:33], v[32:33], v[32:33] op_sel:[0,1] op_sel_hi:[1,0]
	v_pk_add_f32 v[34:35], v[34:35], v[34:35] op_sel:[0,1] op_sel_hi:[1,0]
	v_add_f32_e32 v38, v40, v41
	v_add_f32_e32 v40, v42, v43
	v_mov_b32_e32 v39, v46
	v_mov_b32_e32 v41, v47
	v_mov_b32_e32 v33, v44
	v_mov_b32_e32 v35, v45
	v_pk_add_f32 v[36:37], v[38:39], v[40:41]
	v_pk_add_f32 v[32:33], v[32:33], v[34:35]
	v_lshl_add_u64 v[34:35], s[54:55], 0, v[50:51]
	v_pk_add_f32 v[32:33], v[32:33], v[36:37]
	v_lshl_add_u64 v[34:35], v[34:35], 0, v[112:113]
	v_add_f32_e32 v32, v32, v33
	v_fmamk_f32 v32, v32, 0x3a800000, v150
	v_rsq_f32_e32 v32, v32
	v_lshl_add_u64 v[36:37], s[56:57], 0, v[52:53]
	v_max_f32_e32 v38, v7, v7
	v_max_f32_e32 v39, v3, v3
	v_pk_mul_f32 v[16:17], v[16:17], v[32:33] op_sel_hi:[1,0]
	v_pk_mul_f32 v[18:19], v[18:19], v[32:33] op_sel_hi:[1,0]
	v_pk_mul_f32 v[20:21], v[20:21], v[32:33] op_sel_hi:[1,0]
	v_pk_mul_f32 v[22:23], v[22:23], v[32:33] op_sel_hi:[1,0]
	v_pk_mul_f32 v[24:25], v[24:25], v[32:33] op_sel_hi:[1,0]
	v_pk_mul_f32 v[26:27], v[26:27], v[32:33] op_sel_hi:[1,0]
	v_pk_mul_f32 v[28:29], v[28:29], v[32:33] op_sel_hi:[1,0]
	v_pk_mul_f32 v[30:31], v[30:31], v[32:33] op_sel_hi:[1,0]
	v_pk_mul_f32 v[16:17], v[16:17], v[16:17]
	v_pk_mul_f32 v[18:19], v[18:19], v[18:19]
	v_pk_mul_f32 v[20:21], v[20:21], v[20:21]
	v_pk_mul_f32 v[22:23], v[22:23], v[22:23]
	v_pk_mul_f32 v[24:25], v[24:25], v[24:25]
	v_pk_mul_f32 v[26:27], v[26:27], v[26:27]
	v_pk_mul_f32 v[28:29], v[28:29], v[28:29]
	v_pk_mul_f32 v[30:31], v[30:31], v[30:31]
	v_cvt_pk_bf16_f32 v16, v16, v17
	v_cvt_pk_bf16_f32 v17, v20, v21
	v_cvt_pk_bf16_f32 v18, v18, v19
	v_cvt_pk_bf16_f32 v19, v22, v23
	v_cvt_pk_bf16_f32 v20, v24, v25
	v_cvt_pk_bf16_f32 v21, v28, v29
	v_cvt_pk_bf16_f32 v22, v26, v27
	v_cvt_pk_bf16_f32 v23, v30, v31
	global_store_dwordx4 v[34:35], v[16:19], off
	global_store_dwordx4 v[34:35], v[20:23], off offset:256
	s_nop 0
	v_max_f32_e32 v36, v6, v6
	v_max_f32_e32 v37, v2, v2
	v_max_f32_e32 v2, 0, v8
	v_max_f32_e32 v6, 0, v10
	v_max_f32_e32 v8, 0, v4
	v_max_f32_e32 v10, 0, v0
	v_max_f32_e32 v34, v5, v5
	v_max_f32_e32 v35, v1, v1
	v_max_f32_e32 v0, 0, v12
	v_max_f32_e32 v1, 0, v13
	v_max_f32_e32 v3, 0, v9
	v_max_f32_e32 v4, 0, v14
	v_max_f32_e32 v5, 0, v15
	v_max_f32_e32 v7, 0, v11
	v_max_f32_e32 v9, 0, v34
	v_max_f32_e32 v11, 0, v35
	v_max_f32_e32 v12, 0, v36
	v_max_f32_e32 v14, 0, v37
	v_max_f32_e32 v13, 0, v38
	v_max_f32_e32 v15, 0, v39
	s_waitcnt vmcnt(4) lgkmcnt(0)
	v_mov_b32_e32 v16, v192
	v_mov_b32_e32 v17, v193
	v_mov_b32_e32 v18, v194
	v_mov_b32_e32 v19, v195
	v_mov_b32_e32 v20, v196
	v_mov_b32_e32 v21, v197
	v_mov_b32_e32 v22, v198
	v_mov_b32_e32 v23, v199
	v_mov_b32_e32 v24, v200
	v_mov_b32_e32 v25, v201
	v_mov_b32_e32 v26, v202
	v_mov_b32_e32 v27, v203
	v_mov_b32_e32 v28, v204
	v_mov_b32_e32 v29, v205
	v_mov_b32_e32 v30, v206
	v_mov_b32_e32 v31, v207
	v_mov_b32_e32 v32, v17
	v_mov_b32_e32 v33, v18
	v_mov_b32_e32 v17, v19
	v_mov_b32_e32 v18, v21
	v_mov_b32_e32 v19, v22
	v_mov_b32_e32 v21, v23
	v_pk_add_f32 v[16:17], v[32:33], v[16:17]
	v_pk_add_f32 v[18:19], v[18:19], v[20:21]
	v_pk_add_f32 v[16:17], v[16:17], v[16:17] op_sel:[0,1] op_sel_hi:[1,0]
	v_pk_add_f32 v[18:19], v[18:19], v[18:19] op_sel:[0,1] op_sel_hi:[1,0]
	v_add_f32_e32 v22, v24, v25
	v_add_f32_e32 v24, v26, v27
	v_mov_b32_e32 v23, v30
	v_mov_b32_e32 v25, v31
	v_mov_b32_e32 v17, v28
	v_mov_b32_e32 v19, v29
	v_pk_add_f32 v[20:21], v[22:23], v[24:25]
	v_pk_add_f32 v[16:17], v[16:17], v[18:19]
	v_lshlrev_b64 v[18:19], 13, v[48:49]
	v_pk_add_f32 v[16:17], v[16:17], v[20:21]
	v_lshl_add_u64 v[18:19], s[54:55], 0, v[18:19]
	v_add_f32_e32 v16, v16, v17
	v_fmamk_f32 v16, v16, 0x3a800000, v150
	v_rsq_f32_e32 v16, v16
	v_lshl_add_u64 v[18:19], v[18:19], 0, v[112:113]
	v_pk_mul_f32 v[0:1], v[0:1], v[16:17] op_sel_hi:[1,0]
	v_pk_mul_f32 v[2:3], v[2:3], v[16:17] op_sel_hi:[1,0]
	v_pk_mul_f32 v[4:5], v[4:5], v[16:17] op_sel_hi:[1,0]
	v_pk_mul_f32 v[6:7], v[6:7], v[16:17] op_sel_hi:[1,0]
	v_pk_mul_f32 v[8:9], v[8:9], v[16:17] op_sel_hi:[1,0]
	v_pk_mul_f32 v[10:11], v[10:11], v[16:17] op_sel_hi:[1,0]
	v_pk_mul_f32 v[12:13], v[12:13], v[16:17] op_sel_hi:[1,0]
	v_pk_mul_f32 v[14:15], v[14:15], v[16:17] op_sel_hi:[1,0]
	v_pk_mul_f32 v[0:1], v[0:1], v[0:1]
	v_pk_mul_f32 v[2:3], v[2:3], v[2:3]
	v_pk_mul_f32 v[4:5], v[4:5], v[4:5]
	v_pk_mul_f32 v[6:7], v[6:7], v[6:7]
	v_pk_mul_f32 v[8:9], v[8:9], v[8:9]
	v_pk_mul_f32 v[10:11], v[10:11], v[10:11]
	v_pk_mul_f32 v[12:13], v[12:13], v[12:13]
	v_pk_mul_f32 v[14:15], v[14:15], v[14:15]
	v_cvt_pk_bf16_f32 v0, v0, v1
	v_cvt_pk_bf16_f32 v1, v4, v5
	v_cvt_pk_bf16_f32 v2, v2, v3
	v_cvt_pk_bf16_f32 v3, v6, v7
	v_cvt_pk_bf16_f32 v4, v8, v9
	v_cvt_pk_bf16_f32 v5, v12, v13
	v_cvt_pk_bf16_f32 v6, v10, v11
	v_cvt_pk_bf16_f32 v7, v14, v15
	global_store_dwordx4 v[18:19], v[0:3], off
	global_store_dwordx4 v[18:19], v[4:7], off offset:256
	s_cbranch_vccnz .LBB0_2999
	v_mov_b32_e32 v0, 0
	s_andn2_b64 vcc, exec, s[6:7]
	s_cbranch_vccnz .LBB0_2998
	s_barrier
	s_branch .LBB0_2998

; DI u32x4 pack_v8(f32x4 v0, f32x4 v1) { u32x4 w; w.x = pk2(v0[0], v0[1]); w.y = pk2(v0[2], v0[3]); w.z = pk2(v1[0], v1[1]); w.w = pk2(v1[2], v1[3]); return w; }
; DI float rstd16(const float* ssq, int row) { const f32x4* p = (const f32x4*)(ssq + (size_t)row * 16); const f32x4 a = p[0], b = p[1], c = p[2], d = p[3];
;   return __builtin_amdgcn_rsqf((((a[0] + a[1]) + (a[2] + a[3])) + ((b[0] + b[1]) + (b[2] + b[3])) + ((c[0] + c[1]) + (c[2] + c[3])) + ((d[0] + d[1]) + (d[2] + d[3]))) * (1.0f / 1024.0f) + EPS); }
;   DI void operator()(AccRef acc, const Unit& u, int wr, int wc, int fr, int fq) const {
;     const int rowb = u.pm * 256 + wr * 64 + fr; const int cb = u.pn * 256 + wc * 32 + 8 * fq;
; #pragma unroll
;     for (int ai = 0; ai < 2; ++ai)
; #pragma unroll
;       for (int m = 0; m < 4; ++m) { const int row = rowb + ai * 128 + m * 16; const float rs = rstd16(SSQH, row);
; #pragma unroll
;         for (int bj = 0; bj < 2; ++bj) { f32x4 v0 = acc[ai][bj][m][0], v1 = acc[ai][bj][m][1];
; #pragma unroll
;           for (int j = 0; j < 4; ++j) { const float a = fmaxf(v0[j], 0.f) * rs, b = fmaxf(v1[j], 0.f) * rs; v0[j] = a * a; v1[j] = b * b; }
;           *(u32x4*)(A2 + (size_t)row * DFF + cb + bj * 128) = pack_v8(v0, v1); } }
;   }
.LBB0_3782:
	s_lshl_b32 s0, s22, 8
	v_mov_b32_e32 v151, v224
	s_add_i32 s0, s0, s36
	v_and_or_b32 v144, v151, 15, s0
	v_ashrrev_i32_e32 v145, 31, v144
	v_lshlrev_b64 v[152:153], 6, v[144:145]
	v_lshl_add_u64 v[164:165], s[58:59], 0, v[152:153]
	v_mov_b32_e32 v208, v164
	v_mov_b32_e32 v209, v165
	s_mov_b64 s[98:99], 0x2000
	v_lshl_add_u64 v[210:211], s[98:99], 0, v[164:165]
	global_load_dwordx4 v[152:155], v[164:165], off
	global_load_dwordx4 v[156:159], v[164:165], off offset:16
	global_load_dwordx4 v[160:163], v[164:165], off offset:32
	s_nop 0
	global_load_dwordx4 v[164:167], v[164:165], off offset:48
	global_load_dwordx4 v[192:195], v[208:209], off offset:1024
	global_load_dwordx4 v[196:199], v[208:209], off offset:1040
	global_load_dwordx4 v[200:203], v[208:209], off offset:1056
	global_load_dwordx4 v[204:207], v[208:209], off offset:1072
	v_max_f32_e32 v169, v117, v117
	v_max_f32_e32 v172, v119, v119
	v_max_f32_e32 v117, 0, v121
	v_max_f32_e32 v119, 0, v127
	v_max_f32_e32 v121, 0, v123
	v_max_f32_e32 v123, 0, v169
	v_max_f32_e32 v127, 0, v172
	v_max_f32_e32 v169, 0, v115
	v_lshlrev_b64 v[172:173], 13, v[144:145]
	s_lshl_b32 s0, s57, 8
	v_max_f32_e32 v171, v114, v114
	v_max_f32_e32 v114, 0, v124
	v_max_f32_e32 v124, 0, v112
	v_lshrrev_b32_e32 v112, 1, v151
	v_and_or_b32 v112, v112, 24, s0
	v_max_f32_e32 v168, v116, v116
	v_max_f32_e32 v170, v118, v118
	v_max_f32_e32 v116, 0, v120
	v_max_f32_e32 v115, 0, v125
	v_max_f32_e32 v118, 0, v126
	v_max_f32_e32 v120, 0, v122
	v_or_b32_e32 v112, s37, v112
	v_max_f32_e32 v122, 0, v168
	v_max_f32_e32 v125, 0, v113
	v_max_f32_e32 v126, 0, v170
	v_max_f32_e32 v168, 0, v171
	v_ashrrev_i32_e32 v113, 31, v112
	v_or_b32_e32 v170, 16, v144
	v_lshlrev_b64 v[112:113], 1, v[112:113]
	v_ashrrev_i32_e32 v171, 31, v170
	v_max_f32_e32 v151, v97, v97
	v_max_f32_e32 v97, 0, v109
	s_waitcnt vmcnt(4) lgkmcnt(0)
	global_load_dwordx4 v[176:179], v[208:209], off offset:2048
	global_load_dwordx4 v[180:183], v[208:209], off offset:2064
	global_load_dwordx4 v[184:187], v[208:209], off offset:2080
	global_load_dwordx4 v[188:191], v[208:209], off offset:2096
	v_mov_b32_e32 v174, v153
	v_mov_b32_e32 v175, v154
	v_mov_b32_e32 v153, v155
	v_mov_b32_e32 v154, v157
	v_mov_b32_e32 v155, v158
	v_mov_b32_e32 v157, v159
	v_pk_add_f32 v[152:153], v[174:175], v[152:153]
	v_pk_add_f32 v[154:155], v[154:155], v[156:157]
	v_pk_add_f32 v[152:153], v[152:153], v[152:153] op_sel:[0,1] op_sel_hi:[1,0]
	v_pk_add_f32 v[154:155], v[154:155], v[154:155] op_sel:[0,1] op_sel_hi:[1,0]
	v_add_f32_e32 v158, v160, v161
	v_add_f32_e32 v160, v162, v163
	v_mov_b32_e32 v159, v166
	v_mov_b32_e32 v161, v167
	v_mov_b32_e32 v153, v164
	v_mov_b32_e32 v155, v165
	v_pk_add_f32 v[156:157], v[158:159], v[160:161]
	v_pk_add_f32 v[152:153], v[152:153], v[154:155]
	v_lshl_add_u64 v[154:155], s[50:51], 0, v[172:173]
	v_pk_add_f32 v[152:153], v[152:153], v[156:157]
	v_lshl_add_u64 v[154:155], v[154:155], 0, v[112:113]
	v_add_f32_e32 v145, v152, v153
	v_fmamk_f32 v145, v145, 0x3a800000, v150
	v_rsq_f32_e32 v152, v145
	v_max_f32_e32 v145, v101, v101
	v_max_f32_e32 v156, v102, v102
	v_max_f32_e32 v157, v98, v98
	v_pk_mul_f32 v[114:115], v[114:115], v[152:153] op_sel_hi:[1,0]
	v_pk_mul_f32 v[116:117], v[116:117], v[152:153] op_sel_hi:[1,0]
	v_pk_mul_f32 v[118:119], v[118:119], v[152:153] op_sel_hi:[1,0]
	v_pk_mul_f32 v[120:121], v[120:121], v[152:153] op_sel_hi:[1,0]
	v_pk_mul_f32 v[122:123], v[122:123], v[152:153] op_sel_hi:[1,0]
	v_pk_mul_f32 v[124:125], v[124:125], v[152:153] op_sel_hi:[1,0]
	v_pk_mul_f32 v[126:127], v[126:127], v[152:153] op_sel_hi:[1,0]
	v_pk_mul_f32 v[152:153], v[168:169], v[152:153] op_sel_hi:[1,0]
	v_pk_mul_f32 v[114:115], v[114:115], v[114:115]
	v_pk_mul_f32 v[116:117], v[116:117], v[116:117]
	v_pk_mul_f32 v[118:119], v[118:119], v[118:119]
	v_pk_mul_f32 v[120:121], v[120:121], v[120:121]
	v_pk_mul_f32 v[122:123], v[122:123], v[122:123]
	v_pk_mul_f32 v[124:125], v[124:125], v[124:125]
	v_pk_mul_f32 v[126:127], v[126:127], v[126:127]
	v_pk_mul_f32 v[152:153], v[152:153], v[152:153]
	v_cvt_pk_bf16_f32 v114, v114, v115
	v_cvt_pk_bf16_f32 v115, v118, v119
	v_cvt_pk_bf16_f32 v116, v116, v117
	v_cvt_pk_bf16_f32 v117, v120, v121
	v_cvt_pk_bf16_f32 v118, v122, v123
	v_cvt_pk_bf16_f32 v119, v126, v127
	v_cvt_pk_bf16_f32 v120, v124, v125
	v_cvt_pk_bf16_f32 v121, v152, v153
	global_store_dwordx4 v[154:155], v[114:117], off
	global_store_dwordx4 v[154:155], v[118:121], off offset:256
	v_max_f32_e32 v158, v103, v103
	v_lshlrev_b64 v[114:115], 6, v[170:171]
	v_lshl_add_u64 v[126:127], s[58:59], 0, v[114:115]
	v_max_f32_e32 v126, v100, v100
	v_max_f32_e32 v127, v96, v96
	v_max_f32_e32 v159, v99, v99
	v_max_f32_e32 v96, 0, v108
	v_max_f32_e32 v98, 0, v104
	v_max_f32_e32 v99, 0, v105
	v_max_f32_e32 v100, 0, v110
	v_max_f32_e32 v102, 0, v106
	v_max_f32_e32 v101, 0, v111
	v_max_f32_e32 v103, 0, v107
	v_max_f32_e32 v104, 0, v126
	v_max_f32_e32 v106, 0, v127
	v_max_f32_e32 v105, 0, v145
	v_max_f32_e32 v107, 0, v151
	v_max_f32_e32 v108, 0, v156
	v_max_f32_e32 v110, 0, v157
	v_max_f32_e32 v109, 0, v158
	v_max_f32_e32 v111, 0, v159
	v_or_b32_e32 v126, 32, v144
	v_lshlrev_b64 v[156:157], 13, v[170:171]
	v_ashrrev_i32_e32 v127, 31, v126
	v_lshlrev_b64 v[158:159], 6, v[126:127]
	s_andn2_b64 vcc, exec, s[4:5]
	s_mov_b64 s[4:5], -1
	s_waitcnt vmcnt(6) lgkmcnt(0)
; DI u32x4 pack_v8(f32x4 v0, f32x4 v1) { u32x4 w; w.x = pk2(v0[0], v0[1]); w.y = pk2(v0[2], v0[3]); w.z = pk2(v1[0], v1[1]); w.w = pk2(v1[2], v1[3]); return w; }
; DI float rstd16(const float* ssq, int row) { const f32x4* p = (const f32x4*)(ssq + (size_t)row * 16); const f32x4 a = p[0], b = p[1], c = p[2], d = p[3];
;   return __builtin_amdgcn_rsqf((((a[0] + a[1]) + (a[2] + a[3])) + ((b[0] + b[1]) + (b[2] + b[3])) + ((c[0] + c[1]) + (c[2] + c[3])) + ((d[0] + d[1]) + (d[2] + d[3]))) * (1.0f / 1024.0f) + EPS); }
;   DI void operator()(AccRef acc, const Unit& u, int wr, int wc, int fr, int fq) const {
;     const int rowb = u.pm * 256 + wr * 64 + fr; const int cb = u.pn * 256 + wc * 32 + 8 * fq;
; #pragma unroll
;     for (int ai = 0; ai < 2; ++ai)
; #pragma unroll
;       for (int m = 0; m < 4; ++m) { const int row = rowb + ai * 128 + m * 16; const float rs = rstd16(SSQH, row);
; #pragma unroll
;         for (int bj = 0; bj < 2; ++bj) { f32x4 v0 = acc[ai][bj][m][0], v1 = acc[ai][bj][m][1];
; #pragma unroll
;           for (int j = 0; j < 4; ++j) { const float a = fmaxf(v0[j], 0.f) * rs, b = fmaxf(v1[j], 0.f) * rs; v0[j] = a * a; v1[j] = b * b; }
;           *(u32x4*)(A2 + (size_t)row * DFF + cb + bj * 128) = pack_v8(v0, v1); } }
;   }
	v_mov_b32_e32 v114, v192
	v_mov_b32_e32 v115, v193
	v_mov_b32_e32 v116, v194
	v_mov_b32_e32 v117, v195
	v_mov_b32_e32 v118, v196
	v_mov_b32_e32 v119, v197
	v_mov_b32_e32 v120, v198
	v_mov_b32_e32 v121, v199
	v_mov_b32_e32 v122, v200
	v_mov_b32_e32 v123, v201
	v_mov_b32_e32 v124, v202
	v_mov_b32_e32 v125, v203
	v_mov_b32_e32 v152, v204
	v_mov_b32_e32 v153, v205
	v_mov_b32_e32 v154, v206
	v_mov_b32_e32 v155, v207
	global_load_dwordx4 v[192:195], v[208:209], off offset:3072
	global_load_dwordx4 v[196:199], v[208:209], off offset:3088
	global_load_dwordx4 v[200:203], v[208:209], off offset:3104
	global_load_dwordx4 v[204:207], v[208:209], off offset:3120
	v_mov_b32_e32 v160, v115
	v_mov_b32_e32 v161, v116
	v_mov_b32_e32 v115, v117
	v_mov_b32_e32 v116, v119
	v_mov_b32_e32 v117, v120
	v_mov_b32_e32 v119, v121
	v_pk_add_f32 v[114:115], v[160:161], v[114:115]
	v_pk_add_f32 v[116:117], v[116:117], v[118:119]
	v_pk_add_f32 v[114:115], v[114:115], v[114:115] op_sel:[0,1] op_sel_hi:[1,0]
	v_pk_add_f32 v[116:117], v[116:117], v[116:117] op_sel:[0,1] op_sel_hi:[1,0]
	v_add_f32_e32 v120, v122, v123
	v_add_f32_e32 v122, v124, v125
	v_mov_b32_e32 v121, v154
	v_mov_b32_e32 v123, v155
	v_mov_b32_e32 v115, v152
	v_mov_b32_e32 v117, v153
	v_pk_add_f32 v[118:119], v[120:121], v[122:123]
	v_pk_add_f32 v[114:115], v[114:115], v[116:117]
	v_lshl_add_u64 v[116:117], s[50:51], 0, v[156:157]
	v_pk_add_f32 v[114:115], v[114:115], v[118:119]
	v_lshl_add_u64 v[116:117], v[116:117], 0, v[112:113]
	v_add_f32_e32 v114, v114, v115
	v_fmamk_f32 v114, v114, 0x3a800000, v150
	v_rsq_f32_e32 v114, v114
	v_lshl_add_u64 v[118:119], s[58:59], 0, v[158:159]
	v_pk_mul_f32 v[96:97], v[96:97], v[114:115] op_sel_hi:[1,0]
	v_pk_mul_f32 v[98:99], v[98:99], v[114:115] op_sel_hi:[1,0]
	v_pk_mul_f32 v[100:101], v[100:101], v[114:115] op_sel_hi:[1,0]
	v_pk_mul_f32 v[102:103], v[102:103], v[114:115] op_sel_hi:[1,0]
	v_pk_mul_f32 v[104:105], v[104:105], v[114:115] op_sel_hi:[1,0]
	v_pk_mul_f32 v[106:107], v[106:107], v[114:115] op_sel_hi:[1,0]
	v_pk_mul_f32 v[108:109], v[108:109], v[114:115] op_sel_hi:[1,0]
	v_pk_mul_f32 v[110:111], v[110:111], v[114:115] op_sel_hi:[1,0]
	v_pk_mul_f32 v[96:97], v[96:97], v[96:97]
	v_pk_mul_f32 v[98:99], v[98:99], v[98:99]
	v_pk_mul_f32 v[100:101], v[100:101], v[100:101]
	v_pk_mul_f32 v[102:103], v[102:103], v[102:103]
	v_pk_mul_f32 v[104:105], v[104:105], v[104:105]
	v_pk_mul_f32 v[106:107], v[106:107], v[106:107]
	v_pk_mul_f32 v[108:109], v[108:109], v[108:109]
	v_pk_mul_f32 v[110:111], v[110:111], v[110:111]
	v_cvt_pk_bf16_f32 v96, v96, v97
	v_cvt_pk_bf16_f32 v97, v100, v101
	v_cvt_pk_bf16_f32 v98, v98, v99
	v_cvt_pk_bf16_f32 v99, v102, v103
	v_cvt_pk_bf16_f32 v100, v104, v105
	v_cvt_pk_bf16_f32 v101, v108, v109
	v_cvt_pk_bf16_f32 v102, v106, v107
	v_cvt_pk_bf16_f32 v103, v110, v111
	global_store_dwordx4 v[116:117], v[96:99], off
	global_store_dwordx4 v[116:117], v[100:103], off offset:256
	s_nop 0
	v_max_f32_e32 v116, v85, v85
	v_max_f32_e32 v117, v81, v81
	v_max_f32_e32 v81, 0, v93
	v_max_f32_e32 v85, 0, v95
	v_max_f32_e32 v93, 0, v87
	v_max_f32_e32 v95, 0, v83
	v_max_f32_e32 v114, v84, v84
	v_max_f32_e32 v115, v80, v80
	v_max_f32_e32 v118, v86, v86
	v_max_f32_e32 v119, v82, v82
	v_max_f32_e32 v80, 0, v92
	v_max_f32_e32 v82, 0, v88
	v_max_f32_e32 v83, 0, v89
	v_max_f32_e32 v84, 0, v94
	v_max_f32_e32 v86, 0, v90
	v_max_f32_e32 v87, 0, v91
	v_max_f32_e32 v88, 0, v114
	v_max_f32_e32 v90, 0, v115
	v_max_f32_e32 v89, 0, v116
	v_max_f32_e32 v91, 0, v117
	v_max_f32_e32 v92, 0, v118
	v_max_f32_e32 v94, 0, v119
	v_or_b32_e32 v114, 48, v144
	v_lshlrev_b64 v[116:117], 13, v[126:127]
	v_ashrrev_i32_e32 v115, 31, v114
	v_lshlrev_b64 v[118:119], 6, v[114:115]
	s_waitcnt vmcnt(8) lgkmcnt(0)
	v_mov_b32_e32 v96, v176
	v_mov_b32_e32 v97, v177
	v_mov_b32_e32 v98, v178
	v_mov_b32_e32 v99, v179
	v_mov_b32_e32 v100, v180
	v_mov_b32_e32 v101, v181
	v_mov_b32_e32 v102, v182
	v_mov_b32_e32 v103, v183
	v_mov_b32_e32 v104, v184
	v_mov_b32_e32 v105, v185
	v_mov_b32_e32 v106, v186
	v_mov_b32_e32 v107, v187
	v_mov_b32_e32 v108, v188
	v_mov_b32_e32 v109, v189
	v_mov_b32_e32 v110, v190
	v_mov_b32_e32 v111, v191
	global_load_dwordx4 v[176:179], v[210:211], off offset:0
	global_load_dwordx4 v[180:183], v[210:211], off offset:16
	global_load_dwordx4 v[184:187], v[210:211], off offset:32
	global_load_dwordx4 v[188:191], v[210:211], off offset:48
	v_mov_b32_e32 v120, v97
	v_mov_b32_e32 v121, v98
	v_mov_b32_e32 v97, v99
	v_mov_b32_e32 v98, v101
	v_mov_b32_e32 v99, v102
	v_mov_b32_e32 v101, v103
	v_pk_add_f32 v[96:97], v[120:121], v[96:97]
	v_pk_add_f32 v[98:99], v[98:99], v[100:101]
	v_pk_add_f32 v[96:97], v[96:97], v[96:97] op_sel:[0,1] op_sel_hi:[1,0]
	v_pk_add_f32 v[98:99], v[98:99], v[98:99] op_sel:[0,1] op_sel_hi:[1,0]
	v_add_f32_e32 v102, v104, v105
	v_add_f32_e32 v104, v106, v107
	v_mov_b32_e32 v103, v110
	v_mov_b32_e32 v105, v111
	v_mov_b32_e32 v97, v108
	v_mov_b32_e32 v99, v109
	v_pk_add_f32 v[100:101], v[102:103], v[104:105]
	v_pk_add_f32 v[96:97], v[96:97], v[98:99]
	v_lshl_add_u64 v[98:99], s[50:51], 0, v[116:117]
	v_pk_add_f32 v[96:97], v[96:97], v[100:101]
	v_lshl_add_u64 v[98:99], v[98:99], 0, v[112:113]
	v_add_f32_e32 v96, v96, v97
	v_fmamk_f32 v96, v96, 0x3a800000, v150
	v_rsq_f32_e32 v96, v96
	v_lshl_add_u64 v[100:101], s[58:59], 0, v[118:119]
	v_pk_mul_f32 v[80:81], v[80:81], v[96:97] op_sel_hi:[1,0]
	v_pk_mul_f32 v[82:83], v[82:83], v[96:97] op_sel_hi:[1,0]
	v_pk_mul_f32 v[84:85], v[84:85], v[96:97] op_sel_hi:[1,0]
	v_pk_mul_f32 v[86:87], v[86:87], v[96:97] op_sel_hi:[1,0]
	v_pk_mul_f32 v[88:89], v[88:89], v[96:97] op_sel_hi:[1,0]
	v_pk_mul_f32 v[90:91], v[90:91], v[96:97] op_sel_hi:[1,0]
; DI u32x4 pack_v8(f32x4 v0, f32x4 v1) { u32x4 w; w.x = pk2(v0[0], v0[1]); w.y = pk2(v0[2], v0[3]); w.z = pk2(v1[0], v1[1]); w.w = pk2(v1[2], v1[3]); return w; }
; DI float rstd16(const float* ssq, int row) { const f32x4* p = (const f32x4*)(ssq + (size_t)row * 16); const f32x4 a = p[0], b = p[1], c = p[2], d = p[3];
;   return __builtin_amdgcn_rsqf((((a[0] + a[1]) + (a[2] + a[3])) + ((b[0] + b[1]) + (b[2] + b[3])) + ((c[0] + c[1]) + (c[2] + c[3])) + ((d[0] + d[1]) + (d[2] + d[3]))) * (1.0f / 1024.0f) + EPS); }
;   DI void operator()(AccRef acc, const Unit& u, int wr, int wc, int fr, int fq) const {
;     ...
;     for (int ai = 0; ai < 2; ++ai)
; #pragma unroll
;       for (int m = 0; m < 4; ++m) { const int row = rowb + ai * 128 + m * 16; const float rs = rstd16(SSQH, row);
; #pragma unroll
;         for (int bj = 0; bj < 2; ++bj) { f32x4 v0 = acc[ai][bj][m][0], v1 = acc[ai][bj][m][1];
; #pragma unroll
;           for (int j = 0; j < 4; ++j) { const float a = fmaxf(v0[j], 0.f) * rs, b = fmaxf(v1[j], 0.f) * rs; v0[j] = a * a; v1[j] = b * b; }
;           *(u32x4*)(A2 + (size_t)row * DFF + cb + bj * 128) = pack_v8(v0, v1); } }
	v_pk_mul_f32 v[92:93], v[92:93], v[96:97] op_sel_hi:[1,0]
	v_pk_mul_f32 v[94:95], v[94:95], v[96:97] op_sel_hi:[1,0]
	v_pk_mul_f32 v[80:81], v[80:81], v[80:81]
	v_pk_mul_f32 v[82:83], v[82:83], v[82:83]
	v_pk_mul_f32 v[84:85], v[84:85], v[84:85]
	v_pk_mul_f32 v[86:87], v[86:87], v[86:87]
	v_pk_mul_f32 v[88:89], v[88:89], v[88:89]
	v_pk_mul_f32 v[90:91], v[90:91], v[90:91]
	v_pk_mul_f32 v[92:93], v[92:93], v[92:93]
	v_pk_mul_f32 v[94:95], v[94:95], v[94:95]
	v_cvt_pk_bf16_f32 v80, v80, v81
	v_cvt_pk_bf16_f32 v81, v84, v85
	v_cvt_pk_bf16_f32 v82, v82, v83
	v_cvt_pk_bf16_f32 v83, v86, v87
	v_cvt_pk_bf16_f32 v84, v88, v89
	v_cvt_pk_bf16_f32 v85, v92, v93
	v_cvt_pk_bf16_f32 v86, v90, v91
	v_cvt_pk_bf16_f32 v87, v94, v95
	global_store_dwordx4 v[98:99], v[80:83], off
	global_store_dwordx4 v[98:99], v[84:87], off offset:256
	s_nop 0
	v_max_f32_e32 v98, v69, v69
	v_max_f32_e32 v99, v65, v65
	v_max_f32_e32 v65, 0, v77
	v_max_f32_e32 v69, 0, v79
	v_max_f32_e32 v77, 0, v71
	v_max_f32_e32 v79, 0, v67
	v_max_f32_e32 v96, v68, v68
	v_max_f32_e32 v97, v64, v64
	v_max_f32_e32 v100, v70, v70
	v_max_f32_e32 v101, v66, v66
	v_max_f32_e32 v64, 0, v76
	v_max_f32_e32 v66, 0, v72
	v_max_f32_e32 v67, 0, v73
	v_max_f32_e32 v68, 0, v78
	v_max_f32_e32 v70, 0, v74
	v_max_f32_e32 v71, 0, v75
	v_max_f32_e32 v72, 0, v96
	v_max_f32_e32 v74, 0, v97
	v_max_f32_e32 v73, 0, v98
	v_max_f32_e32 v75, 0, v99
	v_max_f32_e32 v76, 0, v100
	v_max_f32_e32 v78, 0, v101
	v_add_u32_e32 v96, 0x80, v144
	v_lshlrev_b64 v[98:99], 13, v[114:115]
	v_ashrrev_i32_e32 v97, 31, v96
	v_lshlrev_b64 v[100:101], 6, v[96:97]
	s_waitcnt vmcnt(8) lgkmcnt(0)
	v_mov_b32_e32 v80, v192
	v_mov_b32_e32 v81, v193
	v_mov_b32_e32 v82, v194
	v_mov_b32_e32 v83, v195
	v_mov_b32_e32 v84, v196
	v_mov_b32_e32 v85, v197
	v_mov_b32_e32 v86, v198
	v_mov_b32_e32 v87, v199
	v_mov_b32_e32 v88, v200
	v_mov_b32_e32 v89, v201
	v_mov_b32_e32 v90, v202
	v_mov_b32_e32 v91, v203
	v_mov_b32_e32 v92, v204
	v_mov_b32_e32 v93, v205
	v_mov_b32_e32 v94, v206
	v_mov_b32_e32 v95, v207
	global_load_dwordx4 v[192:195], v[210:211], off offset:1024
	global_load_dwordx4 v[196:199], v[210:211], off offset:1040
	global_load_dwordx4 v[200:203], v[210:211], off offset:1056
	global_load_dwordx4 v[204:207], v[210:211], off offset:1072
	v_mov_b32_e32 v102, v81
	v_mov_b32_e32 v103, v82
	v_mov_b32_e32 v81, v83
	v_mov_b32_e32 v82, v85
	v_mov_b32_e32 v83, v86
	v_mov_b32_e32 v85, v87
	v_pk_add_f32 v[80:81], v[102:103], v[80:81]
	v_pk_add_f32 v[82:83], v[82:83], v[84:85]
	v_pk_add_f32 v[80:81], v[80:81], v[80:81] op_sel:[0,1] op_sel_hi:[1,0]
	v_pk_add_f32 v[82:83], v[82:83], v[82:83] op_sel:[0,1] op_sel_hi:[1,0]
	v_add_f32_e32 v86, v88, v89
	v_add_f32_e32 v88, v90, v91
	v_mov_b32_e32 v87, v94
	v_mov_b32_e32 v89, v95
	v_mov_b32_e32 v81, v92
	v_mov_b32_e32 v83, v93
	v_pk_add_f32 v[84:85], v[86:87], v[88:89]
	v_pk_add_f32 v[80:81], v[80:81], v[82:83]
	v_lshl_add_u64 v[82:83], s[50:51], 0, v[98:99]
	v_pk_add_f32 v[80:81], v[80:81], v[84:85]
	v_lshl_add_u64 v[82:83], v[82:83], 0, v[112:113]
	v_add_f32_e32 v80, v80, v81
	v_fmamk_f32 v80, v80, 0x3a800000, v150
	v_rsq_f32_e32 v80, v80
	v_lshl_add_u64 v[84:85], s[58:59], 0, v[100:101]
	v_pk_mul_f32 v[64:65], v[64:65], v[80:81] op_sel_hi:[1,0]
	v_pk_mul_f32 v[66:67], v[66:67], v[80:81] op_sel_hi:[1,0]
	v_pk_mul_f32 v[68:69], v[68:69], v[80:81] op_sel_hi:[1,0]
	v_pk_mul_f32 v[70:71], v[70:71], v[80:81] op_sel_hi:[1,0]
	v_pk_mul_f32 v[72:73], v[72:73], v[80:81] op_sel_hi:[1,0]
	v_pk_mul_f32 v[74:75], v[74:75], v[80:81] op_sel_hi:[1,0]
	v_pk_mul_f32 v[76:77], v[76:77], v[80:81] op_sel_hi:[1,0]
	v_pk_mul_f32 v[78:79], v[78:79], v[80:81] op_sel_hi:[1,0]
	v_pk_mul_f32 v[64:65], v[64:65], v[64:65]
	v_pk_mul_f32 v[66:67], v[66:67], v[66:67]
	v_pk_mul_f32 v[68:69], v[68:69], v[68:69]
	v_pk_mul_f32 v[70:71], v[70:71], v[70:71]
	v_pk_mul_f32 v[72:73], v[72:73], v[72:73]
	v_pk_mul_f32 v[74:75], v[74:75], v[74:75]
	v_pk_mul_f32 v[76:77], v[76:77], v[76:77]
	v_pk_mul_f32 v[78:79], v[78:79], v[78:79]
	v_cvt_pk_bf16_f32 v64, v64, v65
	v_cvt_pk_bf16_f32 v65, v68, v69
	v_cvt_pk_bf16_f32 v66, v66, v67
	v_cvt_pk_bf16_f32 v67, v70, v71
	v_cvt_pk_bf16_f32 v68, v72, v73
	v_cvt_pk_bf16_f32 v69, v76, v77
	v_cvt_pk_bf16_f32 v70, v74, v75
	v_cvt_pk_bf16_f32 v71, v78, v79
	global_store_dwordx4 v[82:83], v[64:67], off
	global_store_dwordx4 v[82:83], v[68:71], off offset:256
	s_nop 0
	v_max_f32_e32 v82, v53, v53
	v_max_f32_e32 v83, v49, v49
	v_max_f32_e32 v49, 0, v61
	v_max_f32_e32 v53, 0, v63
	v_max_f32_e32 v61, 0, v55
	v_max_f32_e32 v63, 0, v51
	v_max_f32_e32 v80, v52, v52
	v_max_f32_e32 v81, v48, v48
	v_max_f32_e32 v84, v54, v54
	v_max_f32_e32 v85, v50, v50
	v_max_f32_e32 v48, 0, v60
	v_max_f32_e32 v50, 0, v56
	v_max_f32_e32 v51, 0, v57
	v_max_f32_e32 v52, 0, v62
	v_max_f32_e32 v54, 0, v58
	v_max_f32_e32 v55, 0, v59
	v_max_f32_e32 v56, 0, v80
	v_max_f32_e32 v58, 0, v81
	v_max_f32_e32 v57, 0, v82
	v_max_f32_e32 v59, 0, v83
	v_max_f32_e32 v60, 0, v84
	v_max_f32_e32 v62, 0, v85
	v_add_u32_e32 v80, 0x90, v144
	v_lshlrev_b64 v[82:83], 13, v[96:97]
	v_ashrrev_i32_e32 v81, 31, v80
	v_lshlrev_b64 v[84:85], 6, v[80:81]
	s_waitcnt vmcnt(8) lgkmcnt(0)
; DI u32x4 pack_v8(f32x4 v0, f32x4 v1) { u32x4 w; w.x = pk2(v0[0], v0[1]); w.y = pk2(v0[2], v0[3]); w.z = pk2(v1[0], v1[1]); w.w = pk2(v1[2], v1[3]); return w; }
; DI float rstd16(const float* ssq, int row) { const f32x4* p = (const f32x4*)(ssq + (size_t)row * 16); const f32x4 a = p[0], b = p[1], c = p[2], d = p[3];
;   return __builtin_amdgcn_rsqf((((a[0] + a[1]) + (a[2] + a[3])) + ((b[0] + b[1]) + (b[2] + b[3])) + ((c[0] + c[1]) + (c[2] + c[3])) + ((d[0] + d[1]) + (d[2] + d[3]))) * (1.0f / 1024.0f) + EPS); }
;   DI void operator()(AccRef acc, const Unit& u, int wr, int wc, int fr, int fq) const {
;     ...
;     for (int ai = 0; ai < 2; ++ai)
; #pragma unroll
;       for (int m = 0; m < 4; ++m) { const int row = rowb + ai * 128 + m * 16; const float rs = rstd16(SSQH, row);
; #pragma unroll
;         for (int bj = 0; bj < 2; ++bj) { f32x4 v0 = acc[ai][bj][m][0], v1 = acc[ai][bj][m][1];
; #pragma unroll
;           for (int j = 0; j < 4; ++j) { const float a = fmaxf(v0[j], 0.f) * rs, b = fmaxf(v1[j], 0.f) * rs; v0[j] = a * a; v1[j] = b * b; }
;           *(u32x4*)(A2 + (size_t)row * DFF + cb + bj * 128) = pack_v8(v0, v1); } }
	v_mov_b32_e32 v64, v176
	v_mov_b32_e32 v65, v177
	v_mov_b32_e32 v66, v178
	v_mov_b32_e32 v67, v179
	v_mov_b32_e32 v68, v180
	v_mov_b32_e32 v69, v181
	v_mov_b32_e32 v70, v182
	v_mov_b32_e32 v71, v183
	v_mov_b32_e32 v72, v184
	v_mov_b32_e32 v73, v185
	v_mov_b32_e32 v74, v186
	v_mov_b32_e32 v75, v187
	v_mov_b32_e32 v76, v188
	v_mov_b32_e32 v77, v189
	v_mov_b32_e32 v78, v190
	v_mov_b32_e32 v79, v191
	global_load_dwordx4 v[176:179], v[210:211], off offset:2048
	global_load_dwordx4 v[180:183], v[210:211], off offset:2064
	global_load_dwordx4 v[184:187], v[210:211], off offset:2080
	global_load_dwordx4 v[188:191], v[210:211], off offset:2096
	v_mov_b32_e32 v86, v65
	v_mov_b32_e32 v87, v66
	v_mov_b32_e32 v65, v67
	v_mov_b32_e32 v66, v69
	v_mov_b32_e32 v67, v70
	v_mov_b32_e32 v69, v71
	v_pk_add_f32 v[64:65], v[86:87], v[64:65]
	v_pk_add_f32 v[66:67], v[66:67], v[68:69]
	v_pk_add_f32 v[64:65], v[64:65], v[64:65] op_sel:[0,1] op_sel_hi:[1,0]
	v_pk_add_f32 v[66:67], v[66:67], v[66:67] op_sel:[0,1] op_sel_hi:[1,0]
	v_add_f32_e32 v70, v72, v73
	v_add_f32_e32 v72, v74, v75
	v_mov_b32_e32 v71, v78
	v_mov_b32_e32 v73, v79
	v_mov_b32_e32 v65, v76
	v_mov_b32_e32 v67, v77
	v_pk_add_f32 v[68:69], v[70:71], v[72:73]
	v_pk_add_f32 v[64:65], v[64:65], v[66:67]
	v_lshl_add_u64 v[66:67], s[50:51], 0, v[82:83]
	v_pk_add_f32 v[64:65], v[64:65], v[68:69]
	v_lshl_add_u64 v[66:67], v[66:67], 0, v[112:113]
	v_add_f32_e32 v64, v64, v65
	v_fmamk_f32 v64, v64, 0x3a800000, v150
	v_rsq_f32_e32 v64, v64
	v_lshl_add_u64 v[68:69], s[58:59], 0, v[84:85]
	v_pk_mul_f32 v[48:49], v[48:49], v[64:65] op_sel_hi:[1,0]
	v_pk_mul_f32 v[50:51], v[50:51], v[64:65] op_sel_hi:[1,0]
	v_pk_mul_f32 v[52:53], v[52:53], v[64:65] op_sel_hi:[1,0]
	v_pk_mul_f32 v[54:55], v[54:55], v[64:65] op_sel_hi:[1,0]
	v_pk_mul_f32 v[56:57], v[56:57], v[64:65] op_sel_hi:[1,0]
	v_pk_mul_f32 v[58:59], v[58:59], v[64:65] op_sel_hi:[1,0]
	v_pk_mul_f32 v[60:61], v[60:61], v[64:65] op_sel_hi:[1,0]
	v_pk_mul_f32 v[62:63], v[62:63], v[64:65] op_sel_hi:[1,0]
	v_pk_mul_f32 v[48:49], v[48:49], v[48:49]
	v_pk_mul_f32 v[50:51], v[50:51], v[50:51]
	v_pk_mul_f32 v[52:53], v[52:53], v[52:53]
	v_pk_mul_f32 v[54:55], v[54:55], v[54:55]
	v_pk_mul_f32 v[56:57], v[56:57], v[56:57]
	v_pk_mul_f32 v[58:59], v[58:59], v[58:59]
	v_pk_mul_f32 v[60:61], v[60:61], v[60:61]
	v_pk_mul_f32 v[62:63], v[62:63], v[62:63]
	v_cvt_pk_bf16_f32 v48, v48, v49
	v_cvt_pk_bf16_f32 v49, v52, v53
	v_cvt_pk_bf16_f32 v50, v50, v51
	v_cvt_pk_bf16_f32 v51, v54, v55
	v_cvt_pk_bf16_f32 v52, v56, v57
	v_cvt_pk_bf16_f32 v53, v60, v61
	v_cvt_pk_bf16_f32 v54, v58, v59
	v_cvt_pk_bf16_f32 v55, v62, v63
	global_store_dwordx4 v[66:67], v[48:51], off
	global_store_dwordx4 v[66:67], v[52:55], off offset:256
	s_nop 0
	v_max_f32_e32 v66, v37, v37
	v_max_f32_e32 v67, v33, v33
	v_max_f32_e32 v33, 0, v45
	v_max_f32_e32 v37, 0, v47
	v_max_f32_e32 v45, 0, v39
	v_max_f32_e32 v47, 0, v35
	v_max_f32_e32 v64, v36, v36
	v_max_f32_e32 v65, v32, v32
	v_max_f32_e32 v68, v38, v38
	v_max_f32_e32 v69, v34, v34
	v_max_f32_e32 v32, 0, v44
	v_max_f32_e32 v34, 0, v40
	v_max_f32_e32 v35, 0, v41
	v_max_f32_e32 v36, 0, v46
	v_max_f32_e32 v38, 0, v42
	v_max_f32_e32 v39, 0, v43
	v_max_f32_e32 v40, 0, v64
	v_max_f32_e32 v42, 0, v65
	v_max_f32_e32 v41, 0, v66
	v_max_f32_e32 v43, 0, v67
	v_max_f32_e32 v44, 0, v68
	v_max_f32_e32 v46, 0, v69
	v_add_u32_e32 v64, 0xa0, v144
	v_lshlrev_b64 v[66:67], 13, v[80:81]
	v_ashrrev_i32_e32 v65, 31, v64
	v_lshlrev_b64 v[68:69], 6, v[64:65]
	s_waitcnt vmcnt(8) lgkmcnt(0)
	v_mov_b32_e32 v48, v192
	v_mov_b32_e32 v49, v193
	v_mov_b32_e32 v50, v194
	v_mov_b32_e32 v51, v195
	v_mov_b32_e32 v52, v196
	v_mov_b32_e32 v53, v197
	v_mov_b32_e32 v54, v198
	v_mov_b32_e32 v55, v199
	v_mov_b32_e32 v56, v200
	v_mov_b32_e32 v57, v201
	v_mov_b32_e32 v58, v202
	v_mov_b32_e32 v59, v203
	v_mov_b32_e32 v60, v204
	v_mov_b32_e32 v61, v205
	v_mov_b32_e32 v62, v206
	v_mov_b32_e32 v63, v207
	global_load_dwordx4 v[192:195], v[210:211], off offset:3072
	global_load_dwordx4 v[196:199], v[210:211], off offset:3088
	global_load_dwordx4 v[200:203], v[210:211], off offset:3104
	global_load_dwordx4 v[204:207], v[210:211], off offset:3120
	v_mov_b32_e32 v70, v49
	v_mov_b32_e32 v71, v50
	v_mov_b32_e32 v49, v51
	v_mov_b32_e32 v50, v53
	v_mov_b32_e32 v51, v54
	v_mov_b32_e32 v53, v55
	v_pk_add_f32 v[48:49], v[70:71], v[48:49]
	v_pk_add_f32 v[50:51], v[50:51], v[52:53]
	v_pk_add_f32 v[48:49], v[48:49], v[48:49] op_sel:[0,1] op_sel_hi:[1,0]
	v_pk_add_f32 v[50:51], v[50:51], v[50:51] op_sel:[0,1] op_sel_hi:[1,0]
	v_add_f32_e32 v54, v56, v57
	v_add_f32_e32 v56, v58, v59
	v_mov_b32_e32 v55, v62
	v_mov_b32_e32 v57, v63
	v_mov_b32_e32 v49, v60
	v_mov_b32_e32 v51, v61
	v_pk_add_f32 v[52:53], v[54:55], v[56:57]
	v_pk_add_f32 v[48:49], v[48:49], v[50:51]
	v_lshl_add_u64 v[50:51], s[50:51], 0, v[66:67]
	v_pk_add_f32 v[48:49], v[48:49], v[52:53]
	v_lshl_add_u64 v[50:51], v[50:51], 0, v[112:113]
	v_add_f32_e32 v48, v48, v49
	v_fmamk_f32 v48, v48, 0x3a800000, v150
	v_rsq_f32_e32 v48, v48
	v_lshl_add_u64 v[52:53], s[58:59], 0, v[68:69]
	v_pk_mul_f32 v[32:33], v[32:33], v[48:49] op_sel_hi:[1,0]
	v_pk_mul_f32 v[34:35], v[34:35], v[48:49] op_sel_hi:[1,0]
	v_pk_mul_f32 v[36:37], v[36:37], v[48:49] op_sel_hi:[1,0]
	v_pk_mul_f32 v[38:39], v[38:39], v[48:49] op_sel_hi:[1,0]
	v_pk_mul_f32 v[40:41], v[40:41], v[48:49] op_sel_hi:[1,0]
	v_pk_mul_f32 v[42:43], v[42:43], v[48:49] op_sel_hi:[1,0]
	v_pk_mul_f32 v[44:45], v[44:45], v[48:49] op_sel_hi:[1,0]
	v_pk_mul_f32 v[46:47], v[46:47], v[48:49] op_sel_hi:[1,0]
	v_pk_mul_f32 v[32:33], v[32:33], v[32:33]
	v_pk_mul_f32 v[34:35], v[34:35], v[34:35]
	v_pk_mul_f32 v[36:37], v[36:37], v[36:37]
	v_pk_mul_f32 v[38:39], v[38:39], v[38:39]
	v_pk_mul_f32 v[40:41], v[40:41], v[40:41]
	v_pk_mul_f32 v[42:43], v[42:43], v[42:43]
	v_pk_mul_f32 v[44:45], v[44:45], v[44:45]
	v_pk_mul_f32 v[46:47], v[46:47], v[46:47]
	v_cvt_pk_bf16_f32 v32, v32, v33
	v_cvt_pk_bf16_f32 v33, v36, v37
	v_cvt_pk_bf16_f32 v34, v34, v35
	v_cvt_pk_bf16_f32 v35, v38, v39
	v_cvt_pk_bf16_f32 v36, v40, v41
	v_cvt_pk_bf16_f32 v37, v44, v45
	v_cvt_pk_bf16_f32 v38, v42, v43
	v_cvt_pk_bf16_f32 v39, v46, v47
	global_store_dwordx4 v[50:51], v[32:35], off
	global_store_dwordx4 v[50:51], v[36:39], off offset:256
	s_nop 0
	v_max_f32_e32 v50, v21, v21
	v_max_f32_e32 v51, v17, v17
	v_max_f32_e32 v17, 0, v29
	v_max_f32_e32 v21, 0, v31
	v_max_f32_e32 v29, 0, v23
	v_max_f32_e32 v31, 0, v19
	v_max_f32_e32 v48, v20, v20
	v_max_f32_e32 v49, v16, v16
	v_max_f32_e32 v52, v22, v22
	v_max_f32_e32 v53, v18, v18
	v_max_f32_e32 v16, 0, v28
	v_max_f32_e32 v18, 0, v24
	v_max_f32_e32 v19, 0, v25
	v_max_f32_e32 v20, 0, v30
	v_max_f32_e32 v22, 0, v26
	v_max_f32_e32 v23, 0, v27
	v_max_f32_e32 v24, 0, v48
	v_max_f32_e32 v26, 0, v49
	v_max_f32_e32 v25, 0, v50
	v_max_f32_e32 v27, 0, v51
	v_max_f32_e32 v28, 0, v52
	v_max_f32_e32 v30, 0, v53
	v_add_u32_e32 v48, 0xb0, v144
	v_lshlrev_b64 v[50:51], 13, v[64:65]
	v_ashrrev_i32_e32 v49, 31, v48
	v_lshlrev_b64 v[52:53], 6, v[48:49]
	s_waitcnt vmcnt(8) lgkmcnt(0)
; DI u32x4 pack_v8(f32x4 v0, f32x4 v1) { u32x4 w; w.x = pk2(v0[0], v0[1]); w.y = pk2(v0[2], v0[3]); w.z = pk2(v1[0], v1[1]); w.w = pk2(v1[2], v1[3]); return w; }
; DI float rstd16(const float* ssq, int row) { const f32x4* p = (const f32x4*)(ssq + (size_t)row * 16); const f32x4 a = p[0], b = p[1], c = p[2], d = p[3];
;   return __builtin_amdgcn_rsqf((((a[0] + a[1]) + (a[2] + a[3])) + ((b[0] + b[1]) + (b[2] + b[3])) + ((c[0] + c[1]) + (c[2] + c[3])) + ((d[0] + d[1]) + (d[2] + d[3]))) * (1.0f / 1024.0f) + EPS); }
;   DI void operator()(AccRef acc, const Unit& u, int wr, int wc, int fr, int fq) const {
;     ...
;     for (int ai = 0; ai < 2; ++ai)
; #pragma unroll
;       for (int m = 0; m < 4; ++m) { const int row = rowb + ai * 128 + m * 16; const float rs = rstd16(SSQH, row);
; #pragma unroll
;         for (int bj = 0; bj < 2; ++bj) { f32x4 v0 = acc[ai][bj][m][0], v1 = acc[ai][bj][m][1];
; #pragma unroll
;           for (int j = 0; j < 4; ++j) { const float a = fmaxf(v0[j], 0.f) * rs, b = fmaxf(v1[j], 0.f) * rs; v0[j] = a * a; v1[j] = b * b; }
;           *(u32x4*)(A2 + (size_t)row * DFF + cb + bj * 128) = pack_v8(v0, v1); } }
	v_mov_b32_e32 v32, v176
	v_mov_b32_e32 v33, v177
	v_mov_b32_e32 v34, v178
	v_mov_b32_e32 v35, v179
	v_mov_b32_e32 v36, v180
	v_mov_b32_e32 v37, v181
	v_mov_b32_e32 v38, v182
	v_mov_b32_e32 v39, v183
	v_mov_b32_e32 v40, v184
	v_mov_b32_e32 v41, v185
	v_mov_b32_e32 v42, v186
	v_mov_b32_e32 v43, v187
	v_mov_b32_e32 v44, v188
	v_mov_b32_e32 v45, v189
	v_mov_b32_e32 v46, v190
	v_mov_b32_e32 v47, v191
	v_mov_b32_e32 v54, v33
	v_mov_b32_e32 v55, v34
	v_mov_b32_e32 v33, v35
	v_mov_b32_e32 v34, v37
	v_mov_b32_e32 v35, v38
	v_mov_b32_e32 v37, v39
	v_pk_add_f32 v[32:33], v[54:55], v[32:33]
	v_pk_add_f32 v[34:35], v[34:35], v[36:37]
	v_pk_add_f32 v[32:33], v[32:33], v[32:33] op_sel:[0,1] op_sel_hi:[1,0]
	v_pk_add_f32 v[34:35], v[34:35], v[34:35] op_sel:[0,1] op_sel_hi:[1,0]
	v_add_f32_e32 v38, v40, v41
	v_add_f32_e32 v40, v42, v43
	v_mov_b32_e32 v39, v46
	v_mov_b32_e32 v41, v47
	v_mov_b32_e32 v33, v44
	v_mov_b32_e32 v35, v45
	v_pk_add_f32 v[36:37], v[38:39], v[40:41]
	v_pk_add_f32 v[32:33], v[32:33], v[34:35]
	v_lshl_add_u64 v[34:35], s[50:51], 0, v[50:51]
	v_pk_add_f32 v[32:33], v[32:33], v[36:37]
	v_lshl_add_u64 v[34:35], v[34:35], 0, v[112:113]
	v_add_f32_e32 v32, v32, v33
	v_fmamk_f32 v32, v32, 0x3a800000, v150
	v_rsq_f32_e32 v32, v32
	v_lshl_add_u64 v[36:37], s[58:59], 0, v[52:53]
	v_max_f32_e32 v38, v7, v7
	v_max_f32_e32 v39, v3, v3
	v_pk_mul_f32 v[16:17], v[16:17], v[32:33] op_sel_hi:[1,0]
	v_pk_mul_f32 v[18:19], v[18:19], v[32:33] op_sel_hi:[1,0]
	v_pk_mul_f32 v[20:21], v[20:21], v[32:33] op_sel_hi:[1,0]
	v_pk_mul_f32 v[22:23], v[22:23], v[32:33] op_sel_hi:[1,0]
	v_pk_mul_f32 v[24:25], v[24:25], v[32:33] op_sel_hi:[1,0]
	v_pk_mul_f32 v[26:27], v[26:27], v[32:33] op_sel_hi:[1,0]
	v_pk_mul_f32 v[28:29], v[28:29], v[32:33] op_sel_hi:[1,0]
	v_pk_mul_f32 v[30:31], v[30:31], v[32:33] op_sel_hi:[1,0]
	v_pk_mul_f32 v[16:17], v[16:17], v[16:17]
	v_pk_mul_f32 v[18:19], v[18:19], v[18:19]
	v_pk_mul_f32 v[20:21], v[20:21], v[20:21]
	v_pk_mul_f32 v[22:23], v[22:23], v[22:23]
	v_pk_mul_f32 v[24:25], v[24:25], v[24:25]
	v_pk_mul_f32 v[26:27], v[26:27], v[26:27]
	v_pk_mul_f32 v[28:29], v[28:29], v[28:29]
	v_pk_mul_f32 v[30:31], v[30:31], v[30:31]
	v_cvt_pk_bf16_f32 v16, v16, v17
	v_cvt_pk_bf16_f32 v17, v20, v21
	v_cvt_pk_bf16_f32 v18, v18, v19
	v_cvt_pk_bf16_f32 v19, v22, v23
	v_cvt_pk_bf16_f32 v20, v24, v25
	v_cvt_pk_bf16_f32 v21, v28, v29
	v_cvt_pk_bf16_f32 v22, v26, v27
	v_cvt_pk_bf16_f32 v23, v30, v31
	global_store_dwordx4 v[34:35], v[16:19], off
	global_store_dwordx4 v[34:35], v[20:23], off offset:256
	s_nop 0
	v_max_f32_e32 v36, v6, v6
	v_max_f32_e32 v37, v2, v2
	v_max_f32_e32 v2, 0, v8
	v_max_f32_e32 v6, 0, v10
	v_max_f32_e32 v8, 0, v4
	v_max_f32_e32 v10, 0, v0
	v_max_f32_e32 v34, v5, v5
	v_max_f32_e32 v35, v1, v1
	v_max_f32_e32 v0, 0, v12
	v_max_f32_e32 v1, 0, v13
	v_max_f32_e32 v3, 0, v9
	v_max_f32_e32 v4, 0, v14
	v_max_f32_e32 v5, 0, v15
	v_max_f32_e32 v7, 0, v11
	v_max_f32_e32 v9, 0, v34
	v_max_f32_e32 v11, 0, v35
	v_max_f32_e32 v12, 0, v36
	v_max_f32_e32 v14, 0, v37
	v_max_f32_e32 v13, 0, v38
	v_max_f32_e32 v15, 0, v39
	s_waitcnt vmcnt(4) lgkmcnt(0)
	v_mov_b32_e32 v16, v192
	v_mov_b32_e32 v17, v193
	v_mov_b32_e32 v18, v194
	v_mov_b32_e32 v19, v195
	v_mov_b32_e32 v20, v196
	v_mov_b32_e32 v21, v197
	v_mov_b32_e32 v22, v198
	v_mov_b32_e32 v23, v199
	v_mov_b32_e32 v24, v200
	v_mov_b32_e32 v25, v201
	v_mov_b32_e32 v26, v202
	v_mov_b32_e32 v27, v203
	v_mov_b32_e32 v28, v204
	v_mov_b32_e32 v29, v205
	v_mov_b32_e32 v30, v206
	v_mov_b32_e32 v31, v207
	v_mov_b32_e32 v32, v17
	v_mov_b32_e32 v33, v18
	v_mov_b32_e32 v17, v19
	v_mov_b32_e32 v18, v21
	v_mov_b32_e32 v19, v22
	v_mov_b32_e32 v21, v23
	v_pk_add_f32 v[16:17], v[32:33], v[16:17]
	v_pk_add_f32 v[18:19], v[18:19], v[20:21]
	v_pk_add_f32 v[16:17], v[16:17], v[16:17] op_sel:[0,1] op_sel_hi:[1,0]
	v_pk_add_f32 v[18:19], v[18:19], v[18:19] op_sel:[0,1] op_sel_hi:[1,0]
	v_add_f32_e32 v22, v24, v25
	v_add_f32_e32 v24, v26, v27
	v_mov_b32_e32 v23, v30
	v_mov_b32_e32 v25, v31
	v_mov_b32_e32 v17, v28
	v_mov_b32_e32 v19, v29
	v_pk_add_f32 v[20:21], v[22:23], v[24:25]
	v_pk_add_f32 v[16:17], v[16:17], v[18:19]
	v_lshlrev_b64 v[18:19], 13, v[48:49]
	v_pk_add_f32 v[16:17], v[16:17], v[20:21]
	v_lshl_add_u64 v[18:19], s[50:51], 0, v[18:19]
	v_add_f32_e32 v16, v16, v17
	v_fmamk_f32 v16, v16, 0x3a800000, v150
	v_rsq_f32_e32 v16, v16
	v_lshl_add_u64 v[18:19], v[18:19], 0, v[112:113]
	v_pk_mul_f32 v[0:1], v[0:1], v[16:17] op_sel_hi:[1,0]
	v_pk_mul_f32 v[2:3], v[2:3], v[16:17] op_sel_hi:[1,0]
	v_pk_mul_f32 v[4:5], v[4:5], v[16:17] op_sel_hi:[1,0]
	v_pk_mul_f32 v[6:7], v[6:7], v[16:17] op_sel_hi:[1,0]
	v_pk_mul_f32 v[8:9], v[8:9], v[16:17] op_sel_hi:[1,0]
	v_pk_mul_f32 v[10:11], v[10:11], v[16:17] op_sel_hi:[1,0]
	v_pk_mul_f32 v[12:13], v[12:13], v[16:17] op_sel_hi:[1,0]
	v_pk_mul_f32 v[14:15], v[14:15], v[16:17] op_sel_hi:[1,0]
	v_pk_mul_f32 v[0:1], v[0:1], v[0:1]
	v_pk_mul_f32 v[2:3], v[2:3], v[2:3]
	v_pk_mul_f32 v[4:5], v[4:5], v[4:5]
	v_pk_mul_f32 v[6:7], v[6:7], v[6:7]
	v_pk_mul_f32 v[8:9], v[8:9], v[8:9]
	v_pk_mul_f32 v[10:11], v[10:11], v[10:11]
	v_pk_mul_f32 v[12:13], v[12:13], v[12:13]
	v_pk_mul_f32 v[14:15], v[14:15], v[14:15]
	v_cvt_pk_bf16_f32 v0, v0, v1
	v_cvt_pk_bf16_f32 v1, v4, v5
	v_cvt_pk_bf16_f32 v2, v2, v3
	v_cvt_pk_bf16_f32 v3, v6, v7
	v_cvt_pk_bf16_f32 v4, v8, v9
	v_cvt_pk_bf16_f32 v5, v12, v13
	v_cvt_pk_bf16_f32 v6, v10, v11
	v_cvt_pk_bf16_f32 v7, v14, v15
	global_store_dwordx4 v[18:19], v[0:3], off
	global_store_dwordx4 v[18:19], v[4:7], off offset:256
	s_cbranch_vccnz .LBB0_3775
	v_mov_b32_e32 v0, 0
	s_andn2_b64 vcc, exec, s[6:7]
	s_cbranch_vccnz .LBB0_3774
	s_barrier
	s_branch .LBB0_3774
